# in-proj epilogue fast path for tiles without norm statistics (straight-line, packed sigmoid, hoisted addressing); gated-merge epilogue pipelined; first grid seam uses the XCD barrier
# speedup vs baseline: 1.0331x; 1.0260x over previous
; __device__ __forceinline__ int mk_tid(int wv) { return (wv << 6) | lane_now(); }
; __device__ __forceinline__ unsigned xb_ld(unsigned* p)              { return __hip_atomic_load(p, __ATOMIC_RELAXED, __HIP_MEMORY_SCOPE_AGENT); }
; __device__ __forceinline__ unsigned xb_add(unsigned* p, unsigned v) { return __hip_atomic_fetch_add(p, v, __ATOMIC_RELAXED, __HIP_MEMORY_SCOPE_AGENT); }
; __device__ __forceinline__ void xcd_barrier_complete(unsigned* bar, unsigned x, unsigned& nloc, unsigned& nx) {
;     const unsigned G = gridDim.x * gridDim.y * gridDim.z;
;     unsigned sum, cnt, mine, sp = 0u;
;     for (;;) {
;         sum = 0u; cnt = 0u; mine = 0u;
; #pragma unroll
;         for (unsigned j = 0; j < 16; ++j) { const unsigned c = xb_ld(&bar[XB_XCNT(j)]); sum += c; cnt += (c > 0u) ? 1u : 0u; mine = (j == x) ? c : mine; }
;         if (sum == G) break;
;         __builtin_amdgcn_s_sleep(1);
;         if ((++sp & 255u) == 0u) { if (xb_ld(&bar[XB_TMO])) break; if (sp > XB_SPIN_CAP) { atomicAdd(&bar[XB_TMO], 1u); break; } }
; __device__ __forceinline__ void xcd_barrier(const XcdBarrier& b, const int wv) {
;     asm volatile("s_waitcnt vmcnt(0)" ::: "memory");
;     __syncthreads();
;     if (mk_tid(wv) == 0) {
;         unsigned* bar = b.bar;
;         __builtin_amdgcn_s_waitcnt(0);
;         unsigned nloc = b.st[0], nx = b.st[1];
;         if (nloc == 0u) { xcd_barrier_complete(bar, b.x, nloc, nx); b.st[0] = nloc; b.st[1] = nx; }
;         const unsigned old = xb_add(&bar[XB_XSUB(b.x)], 1u);
;         const unsigned gen = old / nloc;
;         if (old + 1u == (gen + 1u) * nloc) {
;             __builtin_amdgcn_fence(__ATOMIC_RELEASE, "agent");
;             asm volatile("s_waitcnt vmcnt(0)" ::: "memory");
;             const unsigned og = xb_add(&bar[XB_TOP], 1u);
.LBB0_66:
	s_load_dwordx2 s[36:37], s[24:25], 0x4
	s_waitcnt lgkmcnt(0)
	s_mov_b64 s[6:7], s[0:1]
	s_getreg_b32 s3, hwreg(HW_REG_XCC_ID, 0, 4)
	s_waitcnt vmcnt(0)
	s_waitcnt vmcnt(16) lgkmcnt(0)
	s_barrier
	v_mbcnt_lo_u32_b32 v0, -1, 0
	v_mbcnt_hi_u32_b32 v0, -1, v0
	s_nop 0
	v_or_b32_e32 v0, s69, v0
	v_cmp_eq_u32_e32 vcc, 0, v0
	s_and_saveexec_b64 s[4:5], vcc
	s_cbranch_execz .Lseam1_362
	s_add_i32 s10, 0, 0x24840
	v_mov_b32_e32 v0, s10
	s_load_dwordx2 s[6:7], s[6:7], 0xc0
	s_waitcnt vmcnt(0) expcnt(0) lgkmcnt(0)
	ds_read_b32 v2, v0
	s_add_i32 s10, 0, 0x24844
	v_mov_b32_e32 v0, s10
	ds_read_b32 v0, v0
	s_and_b32 s3, s3, 15
	s_waitcnt lgkmcnt(1)
	v_cmp_ne_u32_e32 vcc, 0, v2
	s_cbranch_vccnz .Lseam1_326
	s_add_u32 s10, s6, 0x4200
	s_addc_u32 s11, s7, 0
	s_add_u32 s12, s6, 0x4400
	s_addc_u32 s13, s7, 0
	s_add_u32 s14, s6, 0x4500
	s_addc_u32 s15, s7, 0
	s_add_u32 s16, s6, 0x4600
	s_addc_u32 s17, s7, 0
	s_add_u32 s18, s6, 0x4700
	s_addc_u32 s19, s7, 0
	s_add_u32 s20, s6, 0x4800
	s_addc_u32 s21, s7, 0
	s_add_u32 s22, s6, 0x4900
	s_addc_u32 s23, s7, 0
	s_add_u32 s24, s6, 0x4a00
	s_addc_u32 s25, s7, 0
	s_add_u32 s26, s6, 0x4b00
	s_addc_u32 s27, s7, 0
	s_add_u32 s28, s6, 0x4c00
	s_addc_u32 s29, s7, 0
	s_add_u32 s42, s6, 0x4d00
	s_addc_u32 s43, s7, 0
	s_add_u32 s44, s6, 0x4e00
	s_addc_u32 s45, s7, 0
	s_add_u32 s46, s6, 0x4f00
	s_addc_u32 s47, s7, 0
	s_add_u32 s48, s6, 0x5000
	s_addc_u32 s49, s7, 0
	s_add_u32 s50, s6, 0x5100
	s_addc_u32 s51, s7, 0
	s_add_u32 s52, s6, 0x5200
	s_addc_u32 s53, s7, 0
	s_mul_i32 s31, s37, s33
	s_add_u32 s54, s6, 0x5300
	s_mul_i32 s31, s31, s36
	s_addc_u32 s55, s7, 0
	s_mov_b32 s35, 1
	v_mov_b32_e32 v16, 0
	s_branch .Lseam1_314

; #define LAS __attribute__((address_space(3)))
; #define q_logf ((float*)(karg_ws() + WS_LOGF))
; #define q_cum ((float*)(karg_ws() + WS_CUM))
; #define FRESH_IDS() const int tid = tid_fresh(wv), lane = tid & 63, wave = wv
; template <int l, int SEL> __device__ __forceinline__ void layer_body(const Args& args, LAS unsigned char* ldsp, unsigned char* lds, const int G, const int bx, const int vcu, const int wv) {
;     ...
;         if (bx < 8) {
;             FRESH_IDS();
;             const float* lf = q_logf + (size_t)bx * M + 32 * tid; float* co = q_cum + (size_t)bx * M + 32 * tid;
;             f32x4 v[8]; float run = 0.f;
; #pragma unroll
;             for (int j = 0; j < 8; ++j) { v[j] = *(const f32x4*)(lf + 4 * j); v[j].x += run; v[j].y += v[j].x; v[j].z += v[j].y; v[j].w += v[j].z; run = v[j].w; }
;             float inc = run;
; #pragma unroll
;             for (int o = 1; o < 64; o <<= 1) { const float t = __shfl_up(inc, o); if (lane >= o) inc += t; }
;             LAS float* wt = (LAS float*)ldsp;
;             if (lane == 63) wt[wave] = inc;
;             __syncthreads();
;             float base = inc - run;
;             for (int w = 0; w < wave; ++w) base += wt[w];
; #pragma unroll
;             for (int j = 0; j < 8; ++j) *(f32x4*)(co + 4 * j) = v[j] + base;
;             __syncthreads();
;         }
.Lseam1_362:
	s_or_b64 exec, exec, s[4:5]
	s_cmp_lt_i32 s2, 8
	s_cselect_b64 s[96:97], -1, 0
	s_cmp_gt_i32 s2, 7
	s_waitcnt lgkmcnt(0)
	s_barrier
	s_cbranch_scc1 .LBB0_88
	s_mov_b64 s[4:5], s[0:1]
	v_mbcnt_lo_u32_b32 v20, -1, 0
	v_mbcnt_hi_u32_b32 v20, -1, v20
	s_load_dwordx2 s[4:5], s[4:5], 0xc0
	s_ashr_i32 s3, s2, 31
	s_lshl_b64 s[6:7], s[2:3], 16
	v_and_b32_e32 v34, 63, v20
	s_waitcnt lgkmcnt(0)
	s_add_u32 s4, s4, s6
	s_addc_u32 s5, s5, s7
	s_lshl_b32 s6, s68, 11
	v_lshl_or_b32 v0, v20, 5, s6
	v_ashrrev_i32_e32 v1, 31, v0
	v_lshl_add_u64 v[6:7], v[0:1], 2, s[4:5]
	s_mov_b32 s6, 0x100000
	v_add_co_u32_e32 v2, vcc, s6, v6
	s_mov_b64 s[4:5], s[0:1]
	s_nop 0
	v_addc_co_u32_e32 v3, vcc, 0, v7, vcc
	global_load_dwordx4 v[2:5], v[2:3], off
	s_mov_b64 s[6:7], 0x100000
	v_lshl_add_u64 v[18:19], v[6:7], 0, s[6:7]
	global_load_dwordx4 v[6:9], v[18:19], off offset:16
	global_load_dwordx4 v[10:13], v[18:19], off offset:32
	global_load_dwordx4 v[14:17], v[18:19], off offset:48
	global_load_dwordx4 v[36:39], v[18:19], off offset:64
	global_load_dwordx4 v[40:43], v[18:19], off offset:80
	global_load_dwordx4 v[44:47], v[18:19], off offset:96
	global_load_dwordx4 v[48:51], v[18:19], off offset:112
	v_mbcnt_lo_u32_b32 v18, -1, 0
	v_mbcnt_hi_u32_b32 v35, -1, v18
	v_and_b32_e32 v52, 64, v35
	v_add_u32_e32 v18, -1, v35
	v_cmp_lt_i32_e32 vcc, v18, v52
	s_waitcnt vmcnt(7)
	v_add_f32_e32 v30, 0, v2
	v_add_f32_e32 v31, v3, v30
	v_add_f32_e32 v32, v4, v31
	v_add_f32_e32 v33, v5, v32
	s_waitcnt vmcnt(6)
	v_add_f32_e32 v26, v6, v33
	v_add_f32_e32 v27, v7, v26
	v_add_f32_e32 v28, v8, v27
	v_add_f32_e32 v29, v9, v28
	s_waitcnt vmcnt(5)
	v_add_f32_e32 v22, v10, v29
	v_add_f32_e32 v23, v11, v22
	v_add_f32_e32 v24, v12, v23
	v_cndmask_b32_e32 v18, v18, v35, vcc
	v_add_f32_e32 v25, v13, v24
	v_lshlrev_b32_e32 v53, 2, v18
	s_waitcnt vmcnt(4)
	v_add_f32_e32 v18, v14, v25
	v_add_f32_e32 v19, v15, v18
	v_add_f32_e32 v20, v16, v19
	v_add_f32_e32 v21, v17, v20
	s_waitcnt vmcnt(3)
	v_add_f32_e32 v14, v36, v21
	v_add_f32_e32 v15, v37, v14
	v_add_f32_e32 v16, v38, v15
	v_add_f32_e32 v17, v39, v16
	s_waitcnt vmcnt(2)
	v_add_f32_e32 v10, v40, v17
	v_add_f32_e32 v11, v41, v10
	v_add_f32_e32 v12, v42, v11
	v_add_f32_e32 v13, v43, v12
	s_waitcnt vmcnt(1)
	v_add_f32_e32 v6, v44, v13
	v_add_f32_e32 v7, v45, v6
	v_add_f32_e32 v8, v46, v7
	v_add_f32_e32 v9, v47, v8
	s_waitcnt vmcnt(0)
	v_add_f32_e32 v2, v48, v9
	v_add_f32_e32 v3, v49, v2
	v_add_f32_e32 v4, v50, v3
	v_add_f32_e32 v5, v51, v4
	ds_bpermute_b32 v36, v53, v5
	v_add_u32_e32 v37, -2, v35
	v_cmp_lt_i32_e32 vcc, v37, v52
	v_add_u32_e32 v38, -4, v35
	s_waitcnt lgkmcnt(0)
	v_add_f32_e32 v36, v5, v36
	v_cndmask_b32_e32 v37, v37, v35, vcc
	v_cmp_eq_u32_e32 vcc, 0, v34
	v_lshlrev_b32_e32 v37, 2, v37
	s_nop 0
	v_cndmask_b32_e32 v36, v36, v5, vcc
	ds_bpermute_b32 v37, v37, v36
	v_cmp_lt_i32_e32 vcc, v38, v52
	s_waitcnt lgkmcnt(0)
	v_add_f32_e32 v37, v36, v37
	v_cndmask_b32_e32 v38, v38, v35, vcc
	v_cmp_gt_u32_e32 vcc, 2, v34
	v_lshlrev_b32_e32 v38, 2, v38
	s_nop 0
	v_cndmask_b32_e32 v36, v37, v36, vcc
	ds_bpermute_b32 v37, v38, v36
	v_add_u32_e32 v38, -8, v35
	v_cmp_lt_i32_e32 vcc, v38, v52
	s_waitcnt lgkmcnt(0)
	v_add_f32_e32 v37, v36, v37
	v_cndmask_b32_e32 v38, v38, v35, vcc
	v_cmp_gt_u32_e32 vcc, 4, v34
	v_lshlrev_b32_e32 v38, 2, v38
	s_nop 0
	v_cndmask_b32_e32 v36, v37, v36, vcc
	ds_bpermute_b32 v37, v38, v36
	v_add_u32_e32 v38, -16, v35
	v_cmp_lt_i32_e32 vcc, v38, v52
	s_waitcnt lgkmcnt(0)
	v_add_f32_e32 v37, v36, v37
	v_cndmask_b32_e32 v38, v38, v35, vcc
	v_cmp_gt_u32_e32 vcc, 8, v34
	v_lshlrev_b32_e32 v38, 2, v38
	s_nop 0
	v_cndmask_b32_e32 v36, v37, v36, vcc
	ds_bpermute_b32 v37, v38, v36
	v_subrev_u32_e32 v38, 32, v35
	v_cmp_lt_i32_e32 vcc, v38, v52
	s_nop 1
	v_cndmask_b32_e32 v35, v38, v35, vcc
	v_lshlrev_b32_e32 v38, 2, v35
	s_waitcnt lgkmcnt(0)
	v_add_f32_e32 v35, v36, v37
	v_cmp_gt_u32_e32 vcc, 16, v34
	s_nop 1
	v_cndmask_b32_e32 v35, v35, v36, vcc
	ds_bpermute_b32 v36, v38, v35
	v_cmp_eq_u32_e32 vcc, 63, v34
	s_waitcnt lgkmcnt(0)
	v_add_f32_e32 v36, v35, v36
	s_and_saveexec_b64 s[6:7], vcc
	s_lshl_b32 s8, s68, 2
	s_add_i32 s8, s8, 0
	v_mov_b32_e32 v37, s8
	ds_write_b32 v37, v36
	s_or_b64 exec, exec, s[6:7]
	s_load_dwordx2 s[4:5], s[4:5], 0xc0
	v_cmp_gt_u32_e32 vcc, 32, v34
	s_cmp_lt_u32 s70, 64
	s_waitcnt lgkmcnt(0)
	v_cndmask_b32_e32 v34, v36, v35, vcc
	v_sub_f32_e32 v34, v34, v5
	s_barrier
	s_cbranch_scc1 .LBB0_87
	s_add_i32 s6, s68, -1
	s_cmp_lt_u32 s6, 7
	s_cbranch_scc1 .LBB0_84
	s_and_b32 s6, s68, 0x3fffff8
	s_mov_b32 s7, 0
	s_mov_b32 s8, 0

; __device__ __forceinline__ unsigned cvt_pk_bf16(float lo, float hi) { unsigned r; asm volatile("v_cvt_pk_bf16_f32 %0, %1, %2" : "=v"(r) : "v"(lo), "v"(hi)); return r; }
; __device__ __forceinline__ float sigm(float x) { return __builtin_amdgcn_rcpf(1.f + __builtin_amdgcn_exp2f(-1.4426950408889634f * x)); }
;     __device__ __forceinline__ void operator()(const f32x4 (&acc)[2][2][4][2], const Unit& u, int wr, int wc, int fr, int fq) const {
;         const int pn = u.pn; const float sc = (pn < 2 || (pn >= 6 && pn < 8)) ? qscale : 1.f; const bool gate = pn >= 12;
;         const int row0 = u.pm * BM + wr * 64 + fr;
;         const int seg = pn >> 1;
; #pragma unroll
;         for (int ai = 0; ai < 2; ++ai)
; #pragma unroll
;             for (int m = 0; m < 4; ++m) { const size_t row = (size_t)(row0 + ai * HALF + m * 16);
; #pragma unroll
;                 for (int bj = 0; bj < 2; ++bj) { f32x4 v0 = acc[ai][bj][m][0], v1 = acc[ai][bj][m][1];
;                     if (gate) { v0 = (f32x4){sigm(v0[0]), sigm(v0[1]), sigm(v0[2]), sigm(v0[3])}; v1 = (f32x4){sigm(v1[0]), sigm(v1[1]), sigm(v1[2]), sigm(v1[3])}; }
;                     else { v0 = v0 * sc; v1 = v1 * sc; }
;                     u32x4 w; w.x = cvt_pk_bf16(v0[0], v0[1]); w.y = cvt_pk_bf16(v0[2], v0[3]); w.z = cvt_pk_bf16(v1[0], v1[1]); w.w = cvt_pk_bf16(v1[2], v1[3]);
;                     const int g64 = 4 * (pn & 1) + 2 * bj + (wc >> 1), cin = 32 * (wc & 1) + 8 * fq;
;                     bf16_t* dst;
;                     if (gate) dst = O + (size_t)6 * 512 * M_ROWS + row * 2048 + (pn - 12) * BM + bj * HALF + wc * 32 + 8 * fq;
;                     else if (seg == 5) dst = O + (size_t)5 * 512 * M_ROWS + ((size_t)(g64 >> 1) * M_ROWS + row) * 128 + 64 * (g64 & 1) + cin;
;                     else dst = O + (size_t)seg * 512 * M_ROWS + ((size_t)g64 * M_ROWS + row) * 64 + cin;
;                     *(u32x4*)dst = w; } }
.LBB0_102:
	s_cmp_lt_i32 s59, 4
	s_cbranch_scc1 .Lproj_l0_old
	s_lshl_b32 s6, s24, 8
	v_mbcnt_lo_u32_b32 v128, -1, 0
	v_mbcnt_hi_u32_b32 v128, -1, v128
	s_add_i32 s6, s6, s71
	v_and_b32_e32 v129, 15, v128
	v_bfe_u32 v130, v128, 4, 2
	v_or_b32_e32 v129, s6, v129
	v_lshlrev_b32_e32 v130, 4, v130
	s_cmp_gt_i32 s59, 11
	s_cbranch_scc1 .Lproj_l0_G
	s_lshr_b32 s7, s59, 1
	s_lshl_b32 s10, s75, 1
	v_or_b32_e32 v130, s10, v130
	s_cmp_eq_u32 s7, 5
	s_cbranch_scc1 .Lproj_l0_V
	s_lshl_b32 s10, s7, 24
	s_and_b32 s11, s59, 1
	s_lshl_b32 s11, s11, 2
	s_or_b32 s11, s11, s67
	s_lshl_b32 s11, s11, 21
	s_add_i32 s10, s10, s11
	v_lshl_add_u32 v138, v129, 7, v130
	s_cmp_eq_u32 s7, 3
	s_cselect_b32 s11, 0x3e38aa3b, 1.0
	v_add_u32_e32 v138, s10, v138
	v_mov_b32_e32 v140, s11
	v_mov_b32_e32 v141, s11
	v_add_u32_e32 v139, 0x400000, v138
	v_pk_mul_f32 v[124:125], v[140:141], v[124:125]
	v_pk_mul_f32 v[126:127], v[140:141], v[126:127]
	v_pk_mul_f32 v[120:121], v[140:141], v[120:121]
	v_pk_mul_f32 v[122:123], v[140:141], v[122:123]
	v_cvt_pk_bf16_f32 v178, v124, v125
	v_cvt_pk_bf16_f32 v179, v126, v127
	v_cvt_pk_bf16_f32 v180, v120, v121
	v_cvt_pk_bf16_f32 v181, v122, v123
	global_store_dwordx4 v138, v[178:181], s[26:27]
	v_pk_mul_f32 v[116:117], v[140:141], v[116:117]
	v_pk_mul_f32 v[118:119], v[140:141], v[118:119]
	v_pk_mul_f32 v[108:109], v[140:141], v[108:109]
	v_pk_mul_f32 v[110:111], v[140:141], v[110:111]
	v_cvt_pk_bf16_f32 v182, v116, v117
	v_cvt_pk_bf16_f32 v183, v118, v119
	v_cvt_pk_bf16_f32 v184, v108, v109
	v_cvt_pk_bf16_f32 v185, v110, v111
	global_store_dwordx4 v139, v[182:185], s[26:27]
	v_add_u32_e32 v138, 0x800, v138
	v_add_u32_e32 v139, 0x800, v139
	v_pk_mul_f32 v[112:113], v[140:141], v[112:113]
	v_pk_mul_f32 v[114:115], v[140:141], v[114:115]
	v_pk_mul_f32 v[104:105], v[140:141], v[104:105]
	v_pk_mul_f32 v[106:107], v[140:141], v[106:107]
	v_cvt_pk_bf16_f32 v178, v112, v113
	v_cvt_pk_bf16_f32 v179, v114, v115
	v_cvt_pk_bf16_f32 v180, v104, v105
	v_cvt_pk_bf16_f32 v181, v106, v107
	global_store_dwordx4 v138, v[178:181], s[26:27]
	v_pk_mul_f32 v[100:101], v[140:141], v[100:101]
	v_pk_mul_f32 v[102:103], v[140:141], v[102:103]
	v_pk_mul_f32 v[92:93], v[140:141], v[92:93]
	v_pk_mul_f32 v[94:95], v[140:141], v[94:95]
	v_cvt_pk_bf16_f32 v182, v100, v101
	v_cvt_pk_bf16_f32 v183, v102, v103
	v_cvt_pk_bf16_f32 v184, v92, v93
	v_cvt_pk_bf16_f32 v185, v94, v95
	global_store_dwordx4 v139, v[182:185], s[26:27]
	v_add_u32_e32 v138, 0x800, v138
	v_add_u32_e32 v139, 0x800, v139
	v_pk_mul_f32 v[96:97], v[140:141], v[96:97]
	v_pk_mul_f32 v[98:99], v[140:141], v[98:99]
	v_pk_mul_f32 v[88:89], v[140:141], v[88:89]
	v_pk_mul_f32 v[90:91], v[140:141], v[90:91]
	v_cvt_pk_bf16_f32 v178, v96, v97
	v_cvt_pk_bf16_f32 v179, v98, v99
	v_cvt_pk_bf16_f32 v180, v88, v89
	v_cvt_pk_bf16_f32 v181, v90, v91
	global_store_dwordx4 v138, v[178:181], s[26:27]
	v_pk_mul_f32 v[84:85], v[140:141], v[84:85]
	v_pk_mul_f32 v[86:87], v[140:141], v[86:87]
	v_pk_mul_f32 v[76:77], v[140:141], v[76:77]
	v_pk_mul_f32 v[78:79], v[140:141], v[78:79]
	v_cvt_pk_bf16_f32 v182, v84, v85
	v_cvt_pk_bf16_f32 v183, v86, v87
	v_cvt_pk_bf16_f32 v184, v76, v77
	v_cvt_pk_bf16_f32 v185, v78, v79
	global_store_dwordx4 v139, v[182:185], s[26:27]
	v_add_u32_e32 v138, 0x800, v138
	v_add_u32_e32 v139, 0x800, v139
	v_pk_mul_f32 v[80:81], v[140:141], v[80:81]
	v_pk_mul_f32 v[82:83], v[140:141], v[82:83]
	v_pk_mul_f32 v[72:73], v[140:141], v[72:73]
	v_pk_mul_f32 v[74:75], v[140:141], v[74:75]
	v_cvt_pk_bf16_f32 v178, v80, v81
	v_cvt_pk_bf16_f32 v179, v82, v83
	v_cvt_pk_bf16_f32 v180, v72, v73
	v_cvt_pk_bf16_f32 v181, v74, v75
	global_store_dwordx4 v138, v[178:181], s[26:27]
	v_pk_mul_f32 v[68:69], v[140:141], v[68:69]
	v_pk_mul_f32 v[70:71], v[140:141], v[70:71]
	v_pk_mul_f32 v[64:65], v[140:141], v[64:65]
	v_pk_mul_f32 v[66:67], v[140:141], v[66:67]
	v_cvt_pk_bf16_f32 v182, v68, v69
	v_cvt_pk_bf16_f32 v183, v70, v71
	v_cvt_pk_bf16_f32 v184, v64, v65
	v_cvt_pk_bf16_f32 v185, v66, v67
	global_store_dwordx4 v139, v[182:185], s[26:27]
	v_add_u32_e32 v138, 0x2800, v138
	v_add_u32_e32 v139, 0x2800, v139
	v_pk_mul_f32 v[60:61], v[140:141], v[60:61]
	v_pk_mul_f32 v[62:63], v[140:141], v[62:63]
	v_pk_mul_f32 v[56:57], v[140:141], v[56:57]
	v_pk_mul_f32 v[58:59], v[140:141], v[58:59]
	v_cvt_pk_bf16_f32 v178, v60, v61
	v_cvt_pk_bf16_f32 v179, v62, v63
	v_cvt_pk_bf16_f32 v180, v56, v57
	v_cvt_pk_bf16_f32 v181, v58, v59
	global_store_dwordx4 v138, v[178:181], s[26:27]
	v_pk_mul_f32 v[52:53], v[140:141], v[52:53]
	v_pk_mul_f32 v[54:55], v[140:141], v[54:55]
	v_pk_mul_f32 v[44:45], v[140:141], v[44:45]
	v_pk_mul_f32 v[46:47], v[140:141], v[46:47]
	v_cvt_pk_bf16_f32 v182, v52, v53
	v_cvt_pk_bf16_f32 v183, v54, v55
	v_cvt_pk_bf16_f32 v184, v44, v45
	v_cvt_pk_bf16_f32 v185, v46, v47
	global_store_dwordx4 v139, v[182:185], s[26:27]
	v_add_u32_e32 v138, 0x800, v138
	v_add_u32_e32 v139, 0x800, v139
	v_pk_mul_f32 v[48:49], v[140:141], v[48:49]
	v_pk_mul_f32 v[50:51], v[140:141], v[50:51]
	v_pk_mul_f32 v[40:41], v[140:141], v[40:41]
	v_pk_mul_f32 v[42:43], v[140:141], v[42:43]
	v_cvt_pk_bf16_f32 v178, v48, v49
	v_cvt_pk_bf16_f32 v179, v50, v51
	v_cvt_pk_bf16_f32 v180, v40, v41
	v_cvt_pk_bf16_f32 v181, v42, v43
	global_store_dwordx4 v138, v[178:181], s[26:27]
	v_pk_mul_f32 v[36:37], v[140:141], v[36:37]
	v_pk_mul_f32 v[38:39], v[140:141], v[38:39]
	v_pk_mul_f32 v[28:29], v[140:141], v[28:29]
	v_pk_mul_f32 v[30:31], v[140:141], v[30:31]
	v_cvt_pk_bf16_f32 v182, v36, v37
	v_cvt_pk_bf16_f32 v183, v38, v39
	v_cvt_pk_bf16_f32 v184, v28, v29
	v_cvt_pk_bf16_f32 v185, v30, v31
	global_store_dwordx4 v139, v[182:185], s[26:27]
	v_add_u32_e32 v138, 0x800, v138
; __device__ __forceinline__ unsigned cvt_pk_bf16(float lo, float hi) { unsigned r; asm volatile("v_cvt_pk_bf16_f32 %0, %1, %2" : "=v"(r) : "v"(lo), "v"(hi)); return r; }
; __device__ __forceinline__ float sigm(float x) { return __builtin_amdgcn_rcpf(1.f + __builtin_amdgcn_exp2f(-1.4426950408889634f * x)); }
;     __device__ __forceinline__ void operator()(const f32x4 (&acc)[2][2][4][2], const Unit& u, int wr, int wc, int fr, int fq) const {
;     ...
;                 for (int bj = 0; bj < 2; ++bj) { f32x4 v0 = acc[ai][bj][m][0], v1 = acc[ai][bj][m][1];
;                     if (gate) { v0 = (f32x4){sigm(v0[0]), sigm(v0[1]), sigm(v0[2]), sigm(v0[3])}; v1 = (f32x4){sigm(v1[0]), sigm(v1[1]), sigm(v1[2]), sigm(v1[3])}; }
;                     else { v0 = v0 * sc; v1 = v1 * sc; }
;                     u32x4 w; w.x = cvt_pk_bf16(v0[0], v0[1]); w.y = cvt_pk_bf16(v0[2], v0[3]); w.z = cvt_pk_bf16(v1[0], v1[1]); w.w = cvt_pk_bf16(v1[2], v1[3]);
;                     const int g64 = 4 * (pn & 1) + 2 * bj + (wc >> 1), cin = 32 * (wc & 1) + 8 * fq;
;                     bf16_t* dst;
;                     if (gate) dst = O + (size_t)6 * 512 * M_ROWS + row * 2048 + (pn - 12) * BM + bj * HALF + wc * 32 + 8 * fq;
;                     else if (seg == 5) dst = O + (size_t)5 * 512 * M_ROWS + ((size_t)(g64 >> 1) * M_ROWS + row) * 128 + 64 * (g64 & 1) + cin;
;                     else dst = O + (size_t)seg * 512 * M_ROWS + ((size_t)g64 * M_ROWS + row) * 64 + cin;
;                     *(u32x4*)dst = w; } }
	v_add_u32_e32 v139, 0x800, v139
	v_pk_mul_f32 v[32:33], v[140:141], v[32:33]
	v_pk_mul_f32 v[34:35], v[140:141], v[34:35]
	v_pk_mul_f32 v[24:25], v[140:141], v[24:25]
	v_pk_mul_f32 v[26:27], v[140:141], v[26:27]
	v_cvt_pk_bf16_f32 v178, v32, v33
	v_cvt_pk_bf16_f32 v179, v34, v35
	v_cvt_pk_bf16_f32 v180, v24, v25
	v_cvt_pk_bf16_f32 v181, v26, v27
	global_store_dwordx4 v138, v[178:181], s[26:27]
	v_pk_mul_f32 v[20:21], v[140:141], v[20:21]
	v_pk_mul_f32 v[22:23], v[140:141], v[22:23]
	v_pk_mul_f32 v[12:13], v[140:141], v[12:13]
	v_pk_mul_f32 v[14:15], v[140:141], v[14:15]
	v_cvt_pk_bf16_f32 v182, v20, v21
	v_cvt_pk_bf16_f32 v183, v22, v23
	v_cvt_pk_bf16_f32 v184, v12, v13
	v_cvt_pk_bf16_f32 v185, v14, v15
	global_store_dwordx4 v139, v[182:185], s[26:27]
	v_add_u32_e32 v138, 0x800, v138
	v_add_u32_e32 v139, 0x800, v139
	v_pk_mul_f32 v[16:17], v[140:141], v[16:17]
	v_pk_mul_f32 v[18:19], v[140:141], v[18:19]
	v_pk_mul_f32 v[8:9], v[140:141], v[8:9]
	v_pk_mul_f32 v[10:11], v[140:141], v[10:11]
	v_cvt_pk_bf16_f32 v178, v16, v17
	v_cvt_pk_bf16_f32 v179, v18, v19
	v_cvt_pk_bf16_f32 v180, v8, v9
	v_cvt_pk_bf16_f32 v181, v10, v11
	global_store_dwordx4 v138, v[178:181], s[26:27]
	v_pk_mul_f32 v[4:5], v[140:141], v[4:5]
	v_pk_mul_f32 v[6:7], v[140:141], v[6:7]
	v_pk_mul_f32 v[0:1], v[140:141], v[0:1]
	v_pk_mul_f32 v[2:3], v[140:141], v[2:3]
	v_cvt_pk_bf16_f32 v182, v4, v5
	v_cvt_pk_bf16_f32 v183, v6, v7
	v_cvt_pk_bf16_f32 v184, v0, v1
	v_cvt_pk_bf16_f32 v185, v2, v3
	global_store_dwordx4 v139, v[182:185], s[26:27]
	s_branch .LBB0_306
.Lproj_l0_V:
	s_and_b32 s11, s59, 1
	s_lshl_b32 s11, s11, 23
	v_lshl_add_u32 v138, v129, 8, v130
	v_mov_b32_e32 v140, 1.0
	v_mov_b32_e32 v141, 1.0
	v_add_u32_e32 v138, s11, v138
	v_add_u32_e32 v139, 0x400000, v138
	v_pk_mul_f32 v[124:125], v[140:141], v[124:125]
	v_pk_mul_f32 v[126:127], v[140:141], v[126:127]
	v_pk_mul_f32 v[120:121], v[140:141], v[120:121]
	v_pk_mul_f32 v[122:123], v[140:141], v[122:123]
	v_cvt_pk_bf16_f32 v178, v124, v125
	v_cvt_pk_bf16_f32 v179, v126, v127
	v_cvt_pk_bf16_f32 v180, v120, v121
	v_cvt_pk_bf16_f32 v181, v122, v123
	global_store_dwordx4 v138, v[178:181], s[42:43]
	v_pk_mul_f32 v[116:117], v[140:141], v[116:117]
	v_pk_mul_f32 v[118:119], v[140:141], v[118:119]
	v_pk_mul_f32 v[108:109], v[140:141], v[108:109]
	v_pk_mul_f32 v[110:111], v[140:141], v[110:111]
	v_cvt_pk_bf16_f32 v182, v116, v117
	v_cvt_pk_bf16_f32 v183, v118, v119
	v_cvt_pk_bf16_f32 v184, v108, v109
	v_cvt_pk_bf16_f32 v185, v110, v111
	global_store_dwordx4 v139, v[182:185], s[42:43]
	v_add_u32_e32 v138, 0x1000, v138
	v_add_u32_e32 v139, 0x1000, v139
	v_pk_mul_f32 v[112:113], v[140:141], v[112:113]
	v_pk_mul_f32 v[114:115], v[140:141], v[114:115]
	v_pk_mul_f32 v[104:105], v[140:141], v[104:105]
	v_pk_mul_f32 v[106:107], v[140:141], v[106:107]
	v_cvt_pk_bf16_f32 v178, v112, v113
	v_cvt_pk_bf16_f32 v179, v114, v115
	v_cvt_pk_bf16_f32 v180, v104, v105
	v_cvt_pk_bf16_f32 v181, v106, v107
	global_store_dwordx4 v138, v[178:181], s[42:43]
	v_pk_mul_f32 v[100:101], v[140:141], v[100:101]
	v_pk_mul_f32 v[102:103], v[140:141], v[102:103]
	v_pk_mul_f32 v[92:93], v[140:141], v[92:93]
	v_pk_mul_f32 v[94:95], v[140:141], v[94:95]
	v_cvt_pk_bf16_f32 v182, v100, v101
	v_cvt_pk_bf16_f32 v183, v102, v103
	v_cvt_pk_bf16_f32 v184, v92, v93
	v_cvt_pk_bf16_f32 v185, v94, v95
	global_store_dwordx4 v139, v[182:185], s[42:43]
	v_add_u32_e32 v138, 0x1000, v138
	v_add_u32_e32 v139, 0x1000, v139
	v_pk_mul_f32 v[96:97], v[140:141], v[96:97]
	v_pk_mul_f32 v[98:99], v[140:141], v[98:99]
	v_pk_mul_f32 v[88:89], v[140:141], v[88:89]
	v_pk_mul_f32 v[90:91], v[140:141], v[90:91]
	v_cvt_pk_bf16_f32 v178, v96, v97
	v_cvt_pk_bf16_f32 v179, v98, v99
	v_cvt_pk_bf16_f32 v180, v88, v89
	v_cvt_pk_bf16_f32 v181, v90, v91
	global_store_dwordx4 v138, v[178:181], s[42:43]
	v_pk_mul_f32 v[84:85], v[140:141], v[84:85]
	v_pk_mul_f32 v[86:87], v[140:141], v[86:87]
	v_pk_mul_f32 v[76:77], v[140:141], v[76:77]
	v_pk_mul_f32 v[78:79], v[140:141], v[78:79]
	v_cvt_pk_bf16_f32 v182, v84, v85
	v_cvt_pk_bf16_f32 v183, v86, v87
	v_cvt_pk_bf16_f32 v184, v76, v77
	v_cvt_pk_bf16_f32 v185, v78, v79
	global_store_dwordx4 v139, v[182:185], s[42:43]
	v_add_u32_e32 v138, 0x1000, v138
	v_add_u32_e32 v139, 0x1000, v139
	v_pk_mul_f32 v[80:81], v[140:141], v[80:81]
	v_pk_mul_f32 v[82:83], v[140:141], v[82:83]
	v_pk_mul_f32 v[72:73], v[140:141], v[72:73]
	v_pk_mul_f32 v[74:75], v[140:141], v[74:75]
	v_cvt_pk_bf16_f32 v178, v80, v81
	v_cvt_pk_bf16_f32 v179, v82, v83
	v_cvt_pk_bf16_f32 v180, v72, v73
	v_cvt_pk_bf16_f32 v181, v74, v75
	global_store_dwordx4 v138, v[178:181], s[42:43]
	v_pk_mul_f32 v[68:69], v[140:141], v[68:69]
	v_pk_mul_f32 v[70:71], v[140:141], v[70:71]
	v_pk_mul_f32 v[64:65], v[140:141], v[64:65]
	v_pk_mul_f32 v[66:67], v[140:141], v[66:67]
	v_cvt_pk_bf16_f32 v182, v68, v69
	v_cvt_pk_bf16_f32 v183, v70, v71
	v_cvt_pk_bf16_f32 v184, v64, v65
	v_cvt_pk_bf16_f32 v185, v66, v67
	global_store_dwordx4 v139, v[182:185], s[42:43]
	v_add_u32_e32 v138, 0x5000, v138
	v_add_u32_e32 v139, 0x5000, v139
	v_pk_mul_f32 v[60:61], v[140:141], v[60:61]
	v_pk_mul_f32 v[62:63], v[140:141], v[62:63]
	v_pk_mul_f32 v[56:57], v[140:141], v[56:57]
	v_pk_mul_f32 v[58:59], v[140:141], v[58:59]
	v_cvt_pk_bf16_f32 v178, v60, v61
	v_cvt_pk_bf16_f32 v179, v62, v63
	v_cvt_pk_bf16_f32 v180, v56, v57
	v_cvt_pk_bf16_f32 v181, v58, v59
	global_store_dwordx4 v138, v[178:181], s[42:43]
	v_pk_mul_f32 v[52:53], v[140:141], v[52:53]
	v_pk_mul_f32 v[54:55], v[140:141], v[54:55]
	v_pk_mul_f32 v[44:45], v[140:141], v[44:45]
	v_pk_mul_f32 v[46:47], v[140:141], v[46:47]
	v_cvt_pk_bf16_f32 v182, v52, v53
	v_cvt_pk_bf16_f32 v183, v54, v55
; __device__ __forceinline__ unsigned cvt_pk_bf16(float lo, float hi) { unsigned r; asm volatile("v_cvt_pk_bf16_f32 %0, %1, %2" : "=v"(r) : "v"(lo), "v"(hi)); return r; }
; __device__ __forceinline__ float sigm(float x) { return __builtin_amdgcn_rcpf(1.f + __builtin_amdgcn_exp2f(-1.4426950408889634f * x)); }
;     __device__ __forceinline__ void operator()(const f32x4 (&acc)[2][2][4][2], const Unit& u, int wr, int wc, int fr, int fq) const {
;     ...
;                     if (gate) { v0 = (f32x4){sigm(v0[0]), sigm(v0[1]), sigm(v0[2]), sigm(v0[3])}; v1 = (f32x4){sigm(v1[0]), sigm(v1[1]), sigm(v1[2]), sigm(v1[3])}; }
;                     else { v0 = v0 * sc; v1 = v1 * sc; }
;                     u32x4 w; w.x = cvt_pk_bf16(v0[0], v0[1]); w.y = cvt_pk_bf16(v0[2], v0[3]); w.z = cvt_pk_bf16(v1[0], v1[1]); w.w = cvt_pk_bf16(v1[2], v1[3]);
;                     const int g64 = 4 * (pn & 1) + 2 * bj + (wc >> 1), cin = 32 * (wc & 1) + 8 * fq;
;                     bf16_t* dst;
;                     if (gate) dst = O + (size_t)6 * 512 * M_ROWS + row * 2048 + (pn - 12) * BM + bj * HALF + wc * 32 + 8 * fq;
;                     else if (seg == 5) dst = O + (size_t)5 * 512 * M_ROWS + ((size_t)(g64 >> 1) * M_ROWS + row) * 128 + 64 * (g64 & 1) + cin;
;                     else dst = O + (size_t)seg * 512 * M_ROWS + ((size_t)g64 * M_ROWS + row) * 64 + cin;
;                     *(u32x4*)dst = w; } }
	v_cvt_pk_bf16_f32 v184, v44, v45
	v_cvt_pk_bf16_f32 v185, v46, v47
	global_store_dwordx4 v139, v[182:185], s[42:43]
	v_add_u32_e32 v138, 0x1000, v138
	v_add_u32_e32 v139, 0x1000, v139
	v_pk_mul_f32 v[48:49], v[140:141], v[48:49]
	v_pk_mul_f32 v[50:51], v[140:141], v[50:51]
	v_pk_mul_f32 v[40:41], v[140:141], v[40:41]
	v_pk_mul_f32 v[42:43], v[140:141], v[42:43]
	v_cvt_pk_bf16_f32 v178, v48, v49
	v_cvt_pk_bf16_f32 v179, v50, v51
	v_cvt_pk_bf16_f32 v180, v40, v41
	v_cvt_pk_bf16_f32 v181, v42, v43
	global_store_dwordx4 v138, v[178:181], s[42:43]
	v_pk_mul_f32 v[36:37], v[140:141], v[36:37]
	v_pk_mul_f32 v[38:39], v[140:141], v[38:39]
	v_pk_mul_f32 v[28:29], v[140:141], v[28:29]
	v_pk_mul_f32 v[30:31], v[140:141], v[30:31]
	v_cvt_pk_bf16_f32 v182, v36, v37
	v_cvt_pk_bf16_f32 v183, v38, v39
	v_cvt_pk_bf16_f32 v184, v28, v29
	v_cvt_pk_bf16_f32 v185, v30, v31
	global_store_dwordx4 v139, v[182:185], s[42:43]
	v_add_u32_e32 v138, 0x1000, v138
	v_add_u32_e32 v139, 0x1000, v139
	v_pk_mul_f32 v[32:33], v[140:141], v[32:33]
	v_pk_mul_f32 v[34:35], v[140:141], v[34:35]
	v_pk_mul_f32 v[24:25], v[140:141], v[24:25]
	v_pk_mul_f32 v[26:27], v[140:141], v[26:27]
	v_cvt_pk_bf16_f32 v178, v32, v33
	v_cvt_pk_bf16_f32 v179, v34, v35
	v_cvt_pk_bf16_f32 v180, v24, v25
	v_cvt_pk_bf16_f32 v181, v26, v27
	global_store_dwordx4 v138, v[178:181], s[42:43]
	v_pk_mul_f32 v[20:21], v[140:141], v[20:21]
	v_pk_mul_f32 v[22:23], v[140:141], v[22:23]
	v_pk_mul_f32 v[12:13], v[140:141], v[12:13]
	v_pk_mul_f32 v[14:15], v[140:141], v[14:15]
	v_cvt_pk_bf16_f32 v182, v20, v21
	v_cvt_pk_bf16_f32 v183, v22, v23
	v_cvt_pk_bf16_f32 v184, v12, v13
	v_cvt_pk_bf16_f32 v185, v14, v15
	global_store_dwordx4 v139, v[182:185], s[42:43]
	v_add_u32_e32 v138, 0x1000, v138
	v_add_u32_e32 v139, 0x1000, v139
	v_pk_mul_f32 v[16:17], v[140:141], v[16:17]
	v_pk_mul_f32 v[18:19], v[140:141], v[18:19]
	v_pk_mul_f32 v[8:9], v[140:141], v[8:9]
	v_pk_mul_f32 v[10:11], v[140:141], v[10:11]
	v_cvt_pk_bf16_f32 v178, v16, v17
	v_cvt_pk_bf16_f32 v179, v18, v19
	v_cvt_pk_bf16_f32 v180, v8, v9
	v_cvt_pk_bf16_f32 v181, v10, v11
	global_store_dwordx4 v138, v[178:181], s[42:43]
	v_pk_mul_f32 v[4:5], v[140:141], v[4:5]
	v_pk_mul_f32 v[6:7], v[140:141], v[6:7]
	v_pk_mul_f32 v[0:1], v[140:141], v[0:1]
	v_pk_mul_f32 v[2:3], v[140:141], v[2:3]
	v_cvt_pk_bf16_f32 v182, v4, v5
	v_cvt_pk_bf16_f32 v183, v6, v7
	v_cvt_pk_bf16_f32 v184, v0, v1
	v_cvt_pk_bf16_f32 v185, v2, v3
	global_store_dwordx4 v139, v[182:185], s[42:43]
	s_branch .LBB0_306
.Lproj_l0_G:
	s_add_i32 s7, s59, -12
	s_lshl_b32 s7, s7, 9
	s_lshl_b32 s10, s78, 1
	s_add_i32 s7, s7, s10
	v_lshl_add_u32 v138, v129, 12, v130
	v_mov_b32_e32 v142, 0xbfb8aa3b
	v_mov_b32_e32 v143, 0xbfb8aa3b
	v_add_u32_e32 v138, s7, v138
	v_mov_b32_e32 v144, 1.0
	v_mov_b32_e32 v145, 1.0
	v_pk_mul_f32 v[162:163], v[142:143], v[124:125]
	v_pk_mul_f32 v[164:165], v[142:143], v[126:127]
	v_pk_mul_f32 v[166:167], v[142:143], v[120:121]
	v_pk_mul_f32 v[168:169], v[142:143], v[122:123]
	v_exp_f32_e32 v162, v162
	v_exp_f32_e32 v163, v163
	v_exp_f32_e32 v164, v164
	v_exp_f32_e32 v165, v165
	v_exp_f32_e32 v166, v166
	v_exp_f32_e32 v167, v167
	v_exp_f32_e32 v168, v168
	v_exp_f32_e32 v169, v169
	v_pk_add_f32 v[162:163], v[144:145], v[162:163]
	v_pk_add_f32 v[164:165], v[144:145], v[164:165]
	v_pk_add_f32 v[166:167], v[144:145], v[166:167]
	v_pk_add_f32 v[168:169], v[144:145], v[168:169]
	v_rcp_f32_e32 v162, v162
	v_rcp_f32_e32 v163, v163
	v_rcp_f32_e32 v164, v164
	v_rcp_f32_e32 v165, v165
	v_rcp_f32_e32 v166, v166
	v_rcp_f32_e32 v167, v167
	v_rcp_f32_e32 v168, v168
	v_rcp_f32_e32 v169, v169
	v_cvt_pk_bf16_f32 v178, v162, v163
	v_cvt_pk_bf16_f32 v179, v164, v165
	v_cvt_pk_bf16_f32 v180, v166, v167
	v_cvt_pk_bf16_f32 v181, v168, v169
	global_store_dwordx4 v138, v[178:181], s[44:45]
	v_pk_mul_f32 v[170:171], v[142:143], v[116:117]
	v_pk_mul_f32 v[172:173], v[142:143], v[118:119]
	v_pk_mul_f32 v[174:175], v[142:143], v[108:109]
	v_pk_mul_f32 v[176:177], v[142:143], v[110:111]
	v_exp_f32_e32 v170, v170
	v_exp_f32_e32 v171, v171
	v_exp_f32_e32 v172, v172
	v_exp_f32_e32 v173, v173
	v_exp_f32_e32 v174, v174
	v_exp_f32_e32 v175, v175
	v_exp_f32_e32 v176, v176
	v_exp_f32_e32 v177, v177
	v_pk_add_f32 v[170:171], v[144:145], v[170:171]
	v_pk_add_f32 v[172:173], v[144:145], v[172:173]
	v_pk_add_f32 v[174:175], v[144:145], v[174:175]
	v_pk_add_f32 v[176:177], v[144:145], v[176:177]
	v_rcp_f32_e32 v170, v170
	v_rcp_f32_e32 v171, v171
	v_rcp_f32_e32 v172, v172
	v_rcp_f32_e32 v173, v173
	v_rcp_f32_e32 v174, v174
	v_rcp_f32_e32 v175, v175
	v_rcp_f32_e32 v176, v176
	v_rcp_f32_e32 v177, v177
	v_cvt_pk_bf16_f32 v182, v170, v171
	v_cvt_pk_bf16_f32 v183, v172, v173
	v_cvt_pk_bf16_f32 v184, v174, v175
	v_cvt_pk_bf16_f32 v185, v176, v177
	global_store_dwordx4 v138, v[182:185], s[44:45] offset:256
	v_add_u32_e32 v138, 0x10000, v138
	v_pk_mul_f32 v[162:163], v[142:143], v[112:113]
	v_pk_mul_f32 v[164:165], v[142:143], v[114:115]
	v_pk_mul_f32 v[166:167], v[142:143], v[104:105]
	v_pk_mul_f32 v[168:169], v[142:143], v[106:107]
	v_exp_f32_e32 v162, v162
	v_exp_f32_e32 v163, v163
	v_exp_f32_e32 v164, v164
	v_exp_f32_e32 v165, v165
	v_exp_f32_e32 v166, v166
	v_exp_f32_e32 v167, v167
	v_exp_f32_e32 v168, v168
	v_exp_f32_e32 v169, v169
	v_pk_add_f32 v[162:163], v[144:145], v[162:163]
	v_pk_add_f32 v[164:165], v[144:145], v[164:165]
	v_pk_add_f32 v[166:167], v[144:145], v[166:167]
	v_pk_add_f32 v[168:169], v[144:145], v[168:169]
	v_rcp_f32_e32 v162, v162
	v_rcp_f32_e32 v163, v163
	v_rcp_f32_e32 v164, v164
	v_rcp_f32_e32 v165, v165
	v_rcp_f32_e32 v166, v166
	v_rcp_f32_e32 v167, v167
	v_rcp_f32_e32 v168, v168
	v_rcp_f32_e32 v169, v169
; __device__ __forceinline__ unsigned cvt_pk_bf16(float lo, float hi) { unsigned r; asm volatile("v_cvt_pk_bf16_f32 %0, %1, %2" : "=v"(r) : "v"(lo), "v"(hi)); return r; }
; __device__ __forceinline__ float sigm(float x) { return __builtin_amdgcn_rcpf(1.f + __builtin_amdgcn_exp2f(-1.4426950408889634f * x)); }
;     __device__ __forceinline__ void operator()(const f32x4 (&acc)[2][2][4][2], const Unit& u, int wr, int wc, int fr, int fq) const {
;     ...
;                     if (gate) { v0 = (f32x4){sigm(v0[0]), sigm(v0[1]), sigm(v0[2]), sigm(v0[3])}; v1 = (f32x4){sigm(v1[0]), sigm(v1[1]), sigm(v1[2]), sigm(v1[3])}; }
;                     else { v0 = v0 * sc; v1 = v1 * sc; }
;                     u32x4 w; w.x = cvt_pk_bf16(v0[0], v0[1]); w.y = cvt_pk_bf16(v0[2], v0[3]); w.z = cvt_pk_bf16(v1[0], v1[1]); w.w = cvt_pk_bf16(v1[2], v1[3]);
;                     const int g64 = 4 * (pn & 1) + 2 * bj + (wc >> 1), cin = 32 * (wc & 1) + 8 * fq;
;                     bf16_t* dst;
;                     if (gate) dst = O + (size_t)6 * 512 * M_ROWS + row * 2048 + (pn - 12) * BM + bj * HALF + wc * 32 + 8 * fq;
	v_cvt_pk_bf16_f32 v178, v162, v163
	v_cvt_pk_bf16_f32 v179, v164, v165
	v_cvt_pk_bf16_f32 v180, v166, v167
	v_cvt_pk_bf16_f32 v181, v168, v169
	global_store_dwordx4 v138, v[178:181], s[44:45]
	v_pk_mul_f32 v[170:171], v[142:143], v[100:101]
	v_pk_mul_f32 v[172:173], v[142:143], v[102:103]
	v_pk_mul_f32 v[174:175], v[142:143], v[92:93]
	v_pk_mul_f32 v[176:177], v[142:143], v[94:95]
	v_exp_f32_e32 v170, v170
	v_exp_f32_e32 v171, v171
	v_exp_f32_e32 v172, v172
	v_exp_f32_e32 v173, v173
	v_exp_f32_e32 v174, v174
	v_exp_f32_e32 v175, v175
	v_exp_f32_e32 v176, v176
	v_exp_f32_e32 v177, v177
	v_pk_add_f32 v[170:171], v[144:145], v[170:171]
	v_pk_add_f32 v[172:173], v[144:145], v[172:173]
	v_pk_add_f32 v[174:175], v[144:145], v[174:175]
	v_pk_add_f32 v[176:177], v[144:145], v[176:177]
	v_rcp_f32_e32 v170, v170
	v_rcp_f32_e32 v171, v171
	v_rcp_f32_e32 v172, v172
	v_rcp_f32_e32 v173, v173
	v_rcp_f32_e32 v174, v174
	v_rcp_f32_e32 v175, v175
	v_rcp_f32_e32 v176, v176
	v_rcp_f32_e32 v177, v177
	v_cvt_pk_bf16_f32 v182, v170, v171
	v_cvt_pk_bf16_f32 v183, v172, v173
	v_cvt_pk_bf16_f32 v184, v174, v175
	v_cvt_pk_bf16_f32 v185, v176, v177
	global_store_dwordx4 v138, v[182:185], s[44:45] offset:256
	v_add_u32_e32 v138, 0x10000, v138
	v_pk_mul_f32 v[162:163], v[142:143], v[96:97]
	v_pk_mul_f32 v[164:165], v[142:143], v[98:99]
	v_pk_mul_f32 v[166:167], v[142:143], v[88:89]
	v_pk_mul_f32 v[168:169], v[142:143], v[90:91]
	v_exp_f32_e32 v162, v162
	v_exp_f32_e32 v163, v163
	v_exp_f32_e32 v164, v164
	v_exp_f32_e32 v165, v165
	v_exp_f32_e32 v166, v166
	v_exp_f32_e32 v167, v167
	v_exp_f32_e32 v168, v168
	v_exp_f32_e32 v169, v169
	v_pk_add_f32 v[162:163], v[144:145], v[162:163]
	v_pk_add_f32 v[164:165], v[144:145], v[164:165]
	v_pk_add_f32 v[166:167], v[144:145], v[166:167]
	v_pk_add_f32 v[168:169], v[144:145], v[168:169]
	v_rcp_f32_e32 v162, v162
	v_rcp_f32_e32 v163, v163
	v_rcp_f32_e32 v164, v164
	v_rcp_f32_e32 v165, v165
	v_rcp_f32_e32 v166, v166
	v_rcp_f32_e32 v167, v167
	v_rcp_f32_e32 v168, v168
	v_rcp_f32_e32 v169, v169
	v_cvt_pk_bf16_f32 v178, v162, v163
	v_cvt_pk_bf16_f32 v179, v164, v165
	v_cvt_pk_bf16_f32 v180, v166, v167
	v_cvt_pk_bf16_f32 v181, v168, v169
	global_store_dwordx4 v138, v[178:181], s[44:45]
	v_pk_mul_f32 v[170:171], v[142:143], v[84:85]
	v_pk_mul_f32 v[172:173], v[142:143], v[86:87]
	v_pk_mul_f32 v[174:175], v[142:143], v[76:77]
	v_pk_mul_f32 v[176:177], v[142:143], v[78:79]
	v_exp_f32_e32 v170, v170
	v_exp_f32_e32 v171, v171
	v_exp_f32_e32 v172, v172
	v_exp_f32_e32 v173, v173
	v_exp_f32_e32 v174, v174
	v_exp_f32_e32 v175, v175
	v_exp_f32_e32 v176, v176
	v_exp_f32_e32 v177, v177
	v_pk_add_f32 v[170:171], v[144:145], v[170:171]
	v_pk_add_f32 v[172:173], v[144:145], v[172:173]
	v_pk_add_f32 v[174:175], v[144:145], v[174:175]
	v_pk_add_f32 v[176:177], v[144:145], v[176:177]
	v_rcp_f32_e32 v170, v170
	v_rcp_f32_e32 v171, v171
	v_rcp_f32_e32 v172, v172
	v_rcp_f32_e32 v173, v173
	v_rcp_f32_e32 v174, v174
	v_rcp_f32_e32 v175, v175
	v_rcp_f32_e32 v176, v176
	v_rcp_f32_e32 v177, v177
	v_cvt_pk_bf16_f32 v182, v170, v171
	v_cvt_pk_bf16_f32 v183, v172, v173
	v_cvt_pk_bf16_f32 v184, v174, v175
	v_cvt_pk_bf16_f32 v185, v176, v177
	global_store_dwordx4 v138, v[182:185], s[44:45] offset:256
	v_add_u32_e32 v138, 0x10000, v138
	v_pk_mul_f32 v[162:163], v[142:143], v[80:81]
	v_pk_mul_f32 v[164:165], v[142:143], v[82:83]
	v_pk_mul_f32 v[166:167], v[142:143], v[72:73]
	v_pk_mul_f32 v[168:169], v[142:143], v[74:75]
	v_exp_f32_e32 v162, v162
	v_exp_f32_e32 v163, v163
	v_exp_f32_e32 v164, v164
	v_exp_f32_e32 v165, v165
	v_exp_f32_e32 v166, v166
	v_exp_f32_e32 v167, v167
	v_exp_f32_e32 v168, v168
	v_exp_f32_e32 v169, v169
	v_pk_add_f32 v[162:163], v[144:145], v[162:163]
	v_pk_add_f32 v[164:165], v[144:145], v[164:165]
	v_pk_add_f32 v[166:167], v[144:145], v[166:167]
	v_pk_add_f32 v[168:169], v[144:145], v[168:169]
	v_rcp_f32_e32 v162, v162
	v_rcp_f32_e32 v163, v163
	v_rcp_f32_e32 v164, v164
	v_rcp_f32_e32 v165, v165
	v_rcp_f32_e32 v166, v166
	v_rcp_f32_e32 v167, v167
	v_rcp_f32_e32 v168, v168
	v_rcp_f32_e32 v169, v169
	v_cvt_pk_bf16_f32 v178, v162, v163
	v_cvt_pk_bf16_f32 v179, v164, v165
	v_cvt_pk_bf16_f32 v180, v166, v167
	v_cvt_pk_bf16_f32 v181, v168, v169
	global_store_dwordx4 v138, v[178:181], s[44:45]
	v_pk_mul_f32 v[170:171], v[142:143], v[68:69]
	v_pk_mul_f32 v[172:173], v[142:143], v[70:71]
	v_pk_mul_f32 v[174:175], v[142:143], v[64:65]
	v_pk_mul_f32 v[176:177], v[142:143], v[66:67]
	v_exp_f32_e32 v170, v170
	v_exp_f32_e32 v171, v171
	v_exp_f32_e32 v172, v172
	v_exp_f32_e32 v173, v173
	v_exp_f32_e32 v174, v174
	v_exp_f32_e32 v175, v175
	v_exp_f32_e32 v176, v176
	v_exp_f32_e32 v177, v177
	v_pk_add_f32 v[170:171], v[144:145], v[170:171]
	v_pk_add_f32 v[172:173], v[144:145], v[172:173]
	v_pk_add_f32 v[174:175], v[144:145], v[174:175]
	v_pk_add_f32 v[176:177], v[144:145], v[176:177]
	v_rcp_f32_e32 v170, v170
	v_rcp_f32_e32 v171, v171
	v_rcp_f32_e32 v172, v172
	v_rcp_f32_e32 v173, v173
	v_rcp_f32_e32 v174, v174
	v_rcp_f32_e32 v175, v175
	v_rcp_f32_e32 v176, v176
	v_rcp_f32_e32 v177, v177
	v_cvt_pk_bf16_f32 v182, v170, v171
	v_cvt_pk_bf16_f32 v183, v172, v173
	v_cvt_pk_bf16_f32 v184, v174, v175
	v_cvt_pk_bf16_f32 v185, v176, v177
	global_store_dwordx4 v138, v[182:185], s[44:45] offset:256
	v_add_u32_e32 v138, 0x50000, v138
	v_pk_mul_f32 v[162:163], v[142:143], v[60:61]
	v_pk_mul_f32 v[164:165], v[142:143], v[62:63]
	v_pk_mul_f32 v[166:167], v[142:143], v[56:57]
	v_pk_mul_f32 v[168:169], v[142:143], v[58:59]
	v_exp_f32_e32 v162, v162
	v_exp_f32_e32 v163, v163
	v_exp_f32_e32 v164, v164
	v_exp_f32_e32 v165, v165
	v_exp_f32_e32 v166, v166
	v_exp_f32_e32 v167, v167
; __device__ __forceinline__ unsigned cvt_pk_bf16(float lo, float hi) { unsigned r; asm volatile("v_cvt_pk_bf16_f32 %0, %1, %2" : "=v"(r) : "v"(lo), "v"(hi)); return r; }
; __device__ __forceinline__ float sigm(float x) { return __builtin_amdgcn_rcpf(1.f + __builtin_amdgcn_exp2f(-1.4426950408889634f * x)); }
;     __device__ __forceinline__ void operator()(const f32x4 (&acc)[2][2][4][2], const Unit& u, int wr, int wc, int fr, int fq) const {
;     ...
;                     if (gate) { v0 = (f32x4){sigm(v0[0]), sigm(v0[1]), sigm(v0[2]), sigm(v0[3])}; v1 = (f32x4){sigm(v1[0]), sigm(v1[1]), sigm(v1[2]), sigm(v1[3])}; }
;                     else { v0 = v0 * sc; v1 = v1 * sc; }
;                     u32x4 w; w.x = cvt_pk_bf16(v0[0], v0[1]); w.y = cvt_pk_bf16(v0[2], v0[3]); w.z = cvt_pk_bf16(v1[0], v1[1]); w.w = cvt_pk_bf16(v1[2], v1[3]);
;                     const int g64 = 4 * (pn & 1) + 2 * bj + (wc >> 1), cin = 32 * (wc & 1) + 8 * fq;
;                     bf16_t* dst;
;                     if (gate) dst = O + (size_t)6 * 512 * M_ROWS + row * 2048 + (pn - 12) * BM + bj * HALF + wc * 32 + 8 * fq;
	v_exp_f32_e32 v168, v168
	v_exp_f32_e32 v169, v169
	v_pk_add_f32 v[162:163], v[144:145], v[162:163]
	v_pk_add_f32 v[164:165], v[144:145], v[164:165]
	v_pk_add_f32 v[166:167], v[144:145], v[166:167]
	v_pk_add_f32 v[168:169], v[144:145], v[168:169]
	v_rcp_f32_e32 v162, v162
	v_rcp_f32_e32 v163, v163
	v_rcp_f32_e32 v164, v164
	v_rcp_f32_e32 v165, v165
	v_rcp_f32_e32 v166, v166
	v_rcp_f32_e32 v167, v167
	v_rcp_f32_e32 v168, v168
	v_rcp_f32_e32 v169, v169
	v_cvt_pk_bf16_f32 v178, v162, v163
	v_cvt_pk_bf16_f32 v179, v164, v165
	v_cvt_pk_bf16_f32 v180, v166, v167
	v_cvt_pk_bf16_f32 v181, v168, v169
	global_store_dwordx4 v138, v[178:181], s[44:45]
	v_pk_mul_f32 v[170:171], v[142:143], v[52:53]
	v_pk_mul_f32 v[172:173], v[142:143], v[54:55]
	v_pk_mul_f32 v[174:175], v[142:143], v[44:45]
	v_pk_mul_f32 v[176:177], v[142:143], v[46:47]
	v_exp_f32_e32 v170, v170
	v_exp_f32_e32 v171, v171
	v_exp_f32_e32 v172, v172
	v_exp_f32_e32 v173, v173
	v_exp_f32_e32 v174, v174
	v_exp_f32_e32 v175, v175
	v_exp_f32_e32 v176, v176
	v_exp_f32_e32 v177, v177
	v_pk_add_f32 v[170:171], v[144:145], v[170:171]
	v_pk_add_f32 v[172:173], v[144:145], v[172:173]
	v_pk_add_f32 v[174:175], v[144:145], v[174:175]
	v_pk_add_f32 v[176:177], v[144:145], v[176:177]
	v_rcp_f32_e32 v170, v170
	v_rcp_f32_e32 v171, v171
	v_rcp_f32_e32 v172, v172
	v_rcp_f32_e32 v173, v173
	v_rcp_f32_e32 v174, v174
	v_rcp_f32_e32 v175, v175
	v_rcp_f32_e32 v176, v176
	v_rcp_f32_e32 v177, v177
	v_cvt_pk_bf16_f32 v182, v170, v171
	v_cvt_pk_bf16_f32 v183, v172, v173
	v_cvt_pk_bf16_f32 v184, v174, v175
	v_cvt_pk_bf16_f32 v185, v176, v177
	global_store_dwordx4 v138, v[182:185], s[44:45] offset:256
	v_add_u32_e32 v138, 0x10000, v138
	v_pk_mul_f32 v[162:163], v[142:143], v[48:49]
	v_pk_mul_f32 v[164:165], v[142:143], v[50:51]
	v_pk_mul_f32 v[166:167], v[142:143], v[40:41]
	v_pk_mul_f32 v[168:169], v[142:143], v[42:43]
	v_exp_f32_e32 v162, v162
	v_exp_f32_e32 v163, v163
	v_exp_f32_e32 v164, v164
	v_exp_f32_e32 v165, v165
	v_exp_f32_e32 v166, v166
	v_exp_f32_e32 v167, v167
	v_exp_f32_e32 v168, v168
	v_exp_f32_e32 v169, v169
	v_pk_add_f32 v[162:163], v[144:145], v[162:163]
	v_pk_add_f32 v[164:165], v[144:145], v[164:165]
	v_pk_add_f32 v[166:167], v[144:145], v[166:167]
	v_pk_add_f32 v[168:169], v[144:145], v[168:169]
	v_rcp_f32_e32 v162, v162
	v_rcp_f32_e32 v163, v163
	v_rcp_f32_e32 v164, v164
	v_rcp_f32_e32 v165, v165
	v_rcp_f32_e32 v166, v166
	v_rcp_f32_e32 v167, v167
	v_rcp_f32_e32 v168, v168
	v_rcp_f32_e32 v169, v169
	v_cvt_pk_bf16_f32 v178, v162, v163
	v_cvt_pk_bf16_f32 v179, v164, v165
	v_cvt_pk_bf16_f32 v180, v166, v167
	v_cvt_pk_bf16_f32 v181, v168, v169
	global_store_dwordx4 v138, v[178:181], s[44:45]
	v_pk_mul_f32 v[170:171], v[142:143], v[36:37]
	v_pk_mul_f32 v[172:173], v[142:143], v[38:39]
	v_pk_mul_f32 v[174:175], v[142:143], v[28:29]
	v_pk_mul_f32 v[176:177], v[142:143], v[30:31]
	v_exp_f32_e32 v170, v170
	v_exp_f32_e32 v171, v171
	v_exp_f32_e32 v172, v172
	v_exp_f32_e32 v173, v173
	v_exp_f32_e32 v174, v174
	v_exp_f32_e32 v175, v175
	v_exp_f32_e32 v176, v176
	v_exp_f32_e32 v177, v177
	v_pk_add_f32 v[170:171], v[144:145], v[170:171]
	v_pk_add_f32 v[172:173], v[144:145], v[172:173]
	v_pk_add_f32 v[174:175], v[144:145], v[174:175]
	v_pk_add_f32 v[176:177], v[144:145], v[176:177]
	v_rcp_f32_e32 v170, v170
	v_rcp_f32_e32 v171, v171
	v_rcp_f32_e32 v172, v172
	v_rcp_f32_e32 v173, v173
	v_rcp_f32_e32 v174, v174
	v_rcp_f32_e32 v175, v175
	v_rcp_f32_e32 v176, v176
	v_rcp_f32_e32 v177, v177
	v_cvt_pk_bf16_f32 v182, v170, v171
	v_cvt_pk_bf16_f32 v183, v172, v173
	v_cvt_pk_bf16_f32 v184, v174, v175
	v_cvt_pk_bf16_f32 v185, v176, v177
	global_store_dwordx4 v138, v[182:185], s[44:45] offset:256
	v_add_u32_e32 v138, 0x10000, v138
	v_pk_mul_f32 v[162:163], v[142:143], v[32:33]
	v_pk_mul_f32 v[164:165], v[142:143], v[34:35]
	v_pk_mul_f32 v[166:167], v[142:143], v[24:25]
; __device__ __forceinline__ unsigned cvt_pk_bf16(float lo, float hi) { unsigned r; asm volatile("v_cvt_pk_bf16_f32 %0, %1, %2" : "=v"(r) : "v"(lo), "v"(hi)); return r; }
; __device__ __forceinline__ float sigm(float x) { return __builtin_amdgcn_rcpf(1.f + __builtin_amdgcn_exp2f(-1.4426950408889634f * x)); }
;     __device__ __forceinline__ void operator()(const f32x4 (&acc)[2][2][4][2], const Unit& u, int wr, int wc, int fr, int fq) const {
;     ...
;                     if (gate) { v0 = (f32x4){sigm(v0[0]), sigm(v0[1]), sigm(v0[2]), sigm(v0[3])}; v1 = (f32x4){sigm(v1[0]), sigm(v1[1]), sigm(v1[2]), sigm(v1[3])}; }
;                     else { v0 = v0 * sc; v1 = v1 * sc; }
;                     u32x4 w; w.x = cvt_pk_bf16(v0[0], v0[1]); w.y = cvt_pk_bf16(v0[2], v0[3]); w.z = cvt_pk_bf16(v1[0], v1[1]); w.w = cvt_pk_bf16(v1[2], v1[3]);
;                     const int g64 = 4 * (pn & 1) + 2 * bj + (wc >> 1), cin = 32 * (wc & 1) + 8 * fq;
;                     bf16_t* dst;
;                     if (gate) dst = O + (size_t)6 * 512 * M_ROWS + row * 2048 + (pn - 12) * BM + bj * HALF + wc * 32 + 8 * fq;
	v_pk_mul_f32 v[168:169], v[142:143], v[26:27]
	v_exp_f32_e32 v162, v162
	v_exp_f32_e32 v163, v163
	v_exp_f32_e32 v164, v164
	v_exp_f32_e32 v165, v165
	v_exp_f32_e32 v166, v166
	v_exp_f32_e32 v167, v167
	v_exp_f32_e32 v168, v168
	v_exp_f32_e32 v169, v169
	v_pk_add_f32 v[162:163], v[144:145], v[162:163]
	v_pk_add_f32 v[164:165], v[144:145], v[164:165]
	v_pk_add_f32 v[166:167], v[144:145], v[166:167]
	v_pk_add_f32 v[168:169], v[144:145], v[168:169]
	v_rcp_f32_e32 v162, v162
	v_rcp_f32_e32 v163, v163
	v_rcp_f32_e32 v164, v164
	v_rcp_f32_e32 v165, v165
	v_rcp_f32_e32 v166, v166
	v_rcp_f32_e32 v167, v167
	v_rcp_f32_e32 v168, v168
	v_rcp_f32_e32 v169, v169
	v_cvt_pk_bf16_f32 v178, v162, v163
	v_cvt_pk_bf16_f32 v179, v164, v165
	v_cvt_pk_bf16_f32 v180, v166, v167
	v_cvt_pk_bf16_f32 v181, v168, v169
	global_store_dwordx4 v138, v[178:181], s[44:45]
	v_pk_mul_f32 v[170:171], v[142:143], v[20:21]
	v_pk_mul_f32 v[172:173], v[142:143], v[22:23]
	v_pk_mul_f32 v[174:175], v[142:143], v[12:13]
	v_pk_mul_f32 v[176:177], v[142:143], v[14:15]
	v_exp_f32_e32 v170, v170
	v_exp_f32_e32 v171, v171
	v_exp_f32_e32 v172, v172
	v_exp_f32_e32 v173, v173
	v_exp_f32_e32 v174, v174
	v_exp_f32_e32 v175, v175
	v_exp_f32_e32 v176, v176
	v_exp_f32_e32 v177, v177
	v_pk_add_f32 v[170:171], v[144:145], v[170:171]
	v_pk_add_f32 v[172:173], v[144:145], v[172:173]
	v_pk_add_f32 v[174:175], v[144:145], v[174:175]
	v_pk_add_f32 v[176:177], v[144:145], v[176:177]
	v_rcp_f32_e32 v170, v170
	v_rcp_f32_e32 v171, v171
	v_rcp_f32_e32 v172, v172
	v_rcp_f32_e32 v173, v173
	v_rcp_f32_e32 v174, v174
	v_rcp_f32_e32 v175, v175
	v_rcp_f32_e32 v176, v176
	v_rcp_f32_e32 v177, v177
	v_cvt_pk_bf16_f32 v182, v170, v171
	v_cvt_pk_bf16_f32 v183, v172, v173
	v_cvt_pk_bf16_f32 v184, v174, v175
	v_cvt_pk_bf16_f32 v185, v176, v177
	global_store_dwordx4 v138, v[182:185], s[44:45] offset:256
	v_add_u32_e32 v138, 0x10000, v138
	v_pk_mul_f32 v[162:163], v[142:143], v[16:17]
	v_pk_mul_f32 v[164:165], v[142:143], v[18:19]
	v_pk_mul_f32 v[166:167], v[142:143], v[8:9]
	v_pk_mul_f32 v[168:169], v[142:143], v[10:11]
	v_exp_f32_e32 v162, v162
	v_exp_f32_e32 v163, v163
	v_exp_f32_e32 v164, v164
	v_exp_f32_e32 v165, v165
	v_exp_f32_e32 v166, v166
	v_exp_f32_e32 v167, v167
	v_exp_f32_e32 v168, v168
	v_exp_f32_e32 v169, v169
	v_pk_add_f32 v[162:163], v[144:145], v[162:163]
	v_pk_add_f32 v[164:165], v[144:145], v[164:165]
	v_pk_add_f32 v[166:167], v[144:145], v[166:167]
	v_pk_add_f32 v[168:169], v[144:145], v[168:169]
	v_rcp_f32_e32 v162, v162
	v_rcp_f32_e32 v163, v163
	v_rcp_f32_e32 v164, v164
	v_rcp_f32_e32 v165, v165
	v_rcp_f32_e32 v166, v166
	v_rcp_f32_e32 v167, v167
	v_rcp_f32_e32 v168, v168
	v_rcp_f32_e32 v169, v169
	v_cvt_pk_bf16_f32 v178, v162, v163
	v_cvt_pk_bf16_f32 v179, v164, v165
	v_cvt_pk_bf16_f32 v180, v166, v167
	v_cvt_pk_bf16_f32 v181, v168, v169
	global_store_dwordx4 v138, v[178:181], s[44:45]
	v_pk_mul_f32 v[170:171], v[142:143], v[4:5]
	v_pk_mul_f32 v[172:173], v[142:143], v[6:7]
	v_pk_mul_f32 v[174:175], v[142:143], v[0:1]
	v_pk_mul_f32 v[176:177], v[142:143], v[2:3]
	v_exp_f32_e32 v170, v170
	v_exp_f32_e32 v171, v171
	v_exp_f32_e32 v172, v172
	v_exp_f32_e32 v173, v173
	v_exp_f32_e32 v174, v174
	v_exp_f32_e32 v175, v175
	v_exp_f32_e32 v176, v176
	v_exp_f32_e32 v177, v177
	v_pk_add_f32 v[170:171], v[144:145], v[170:171]
	v_pk_add_f32 v[172:173], v[144:145], v[172:173]
	v_pk_add_f32 v[174:175], v[144:145], v[174:175]
	v_pk_add_f32 v[176:177], v[144:145], v[176:177]
	v_rcp_f32_e32 v170, v170
	v_rcp_f32_e32 v171, v171
	v_rcp_f32_e32 v172, v172
	v_rcp_f32_e32 v173, v173
	v_rcp_f32_e32 v174, v174
	v_rcp_f32_e32 v175, v175
	v_rcp_f32_e32 v176, v176
	v_rcp_f32_e32 v177, v177
	v_cvt_pk_bf16_f32 v182, v170, v171
	v_cvt_pk_bf16_f32 v183, v172, v173
	v_cvt_pk_bf16_f32 v184, v174, v175
	v_cvt_pk_bf16_f32 v185, v176, v177
	global_store_dwordx4 v138, v[182:185], s[44:45] offset:256
	s_branch .LBB0_306

; __device__ __forceinline__ unsigned cvt_pk_bf16(float lo, float hi) { unsigned r; asm volatile("v_cvt_pk_bf16_f32 %0, %1, %2" : "=v"(r) : "v"(lo), "v"(hi)); return r; }
; __device__ __forceinline__ float bf_lo(unsigned w) { return __uint_as_float(w << 16); }
; __device__ __forceinline__ float bf_hi(unsigned w) { return __uint_as_float(w & 0xffff0000u); }
;     __device__ __forceinline__ void operator()(const f32x4 (&acc)[2][2][4][2], const Unit& u, int wr, int wc, int fr, int fq) const {
;         const bool second = u.pn >= 4; const int pn = second ? u.pn - 4 : u.pn, pm = second ? u.pm - 64 : u.pm;
;         const int row0 = pm * BM + wr * 64 + fr, col0 = pn * BM + wc * 32 + 8 * fq; const int goff = second ? 1024 : 0;
; #pragma unroll
;         for (int ai = 0; ai < 2; ++ai)
; #pragma unroll
;             for (int m = 0; m < 4; ++m) { const size_t row = (size_t)(row0 + ai * HALF + m * 16);
; #pragma unroll
;                 for (int bj = 0; bj < 2; ++bj) { const int col = col0 + bj * HALF;
;                     const u32x4 gw = *(const u32x4*)(proj + (size_t)6 * 512 * M_ROWS + row * 2048 + goff + col);
;                     const f32x4 g0 = (f32x4){bf_lo(gw.x), bf_hi(gw.x), bf_lo(gw.y), bf_hi(gw.y)}, g1 = (f32x4){bf_lo(gw.z), bf_hi(gw.z), bf_lo(gw.w), bf_hi(gw.w)};
;                     f32x4 v0 = acc[ai][bj][m][0] * g0, v1 = acc[ai][bj][m][1] * g1; bf16_t* mp = merged + row * 1024 + col;
;                     if (second) { const u32x4 tw = *(const u32x4*)mp;
;                         v0 = v0 + (f32x4){bf_lo(tw.x), bf_hi(tw.x), bf_lo(tw.y), bf_hi(tw.y)}; v1 = v1 + (f32x4){bf_lo(tw.z), bf_hi(tw.z), bf_lo(tw.w), bf_hi(tw.w)}; }
;                     u32x4 w; w.x = cvt_pk_bf16(v0[0], v0[1]); w.y = cvt_pk_bf16(v0[2], v0[3]); w.z = cvt_pk_bf16(v1[0], v1[1]); w.w = cvt_pk_bf16(v1[2], v1[3]);
;                     *(u32x4*)mp = w; }
;                 asm volatile("" ::: "memory"); }
.LBB0_673:
	s_lshl_b32 s22, s22, 8
	s_lshl_b32 s42, s40, 8
	s_add_i32 s41, s22, 0xffffc000
	s_add_i32 s43, s42, 0xfffffc00
	s_cmp_gt_i32 s40, 3
	s_cselect_b64 s[18:19], -1, 0
	s_and_b64 s[10:11], s[18:19], exec
	s_cselect_b32 s11, s41, s22
	v_mbcnt_lo_u32_b32 v132, -1, 0
	v_mbcnt_hi_u32_b32 v132, -1, v132
	s_cselect_b32 s10, 0x400, 0
	s_cselect_b32 s41, s43, s42
	s_add_i32 s11, s11, s71
	v_and_or_b32 v134, v132, 15, s11
	v_lshrrev_b32_e32 v132, 1, v132
	v_and_or_b32 v132, v132, 24, s41
	v_ashrrev_i32_e32 v135, 31, v134
	v_or_b32_e32 v132, s75, v132
	s_lshl_b32 s22, s10, 1
	v_lshlrev_b32_e32 v248, 12, v134
	v_lshlrev_b32_e32 v249, 11, v134
	v_lshl_add_u32 v248, v132, 1, v248
	v_lshl_add_u32 v249, v132, 1, v249
	v_add_u32_e32 v248, s22, v248
	v_mov_b32_e32 v250, v249
	s_and_b64 vcc, exec, s[18:19]
	s_cbranch_vccnz .Lmrg_l0_second
	global_load_dwordx4 v[152:155], v248, s[28:29]
	global_load_dwordx4 v[156:159], v248, s[28:29] offset:256
	v_add_u32_e32 v248, 0x10000, v248
	global_load_dwordx4 v[160:163], v248, s[28:29]
	global_load_dwordx4 v[164:167], v248, s[28:29] offset:256
	v_add_u32_e32 v248, 0x10000, v248
	global_load_dwordx4 v[184:187], v248, s[28:29]
	global_load_dwordx4 v[188:191], v248, s[28:29] offset:256
	v_add_u32_e32 v248, 0x10000, v248
	global_load_dwordx4 v[192:195], v248, s[28:29]
	global_load_dwordx4 v[196:199], v248, s[28:29] offset:256
	v_add_u32_e32 v248, 0x50000, v248
	global_load_dwordx4 v[216:219], v248, s[28:29]
	global_load_dwordx4 v[220:223], v248, s[28:29] offset:256
	v_add_u32_e32 v248, 0x10000, v248
	global_load_dwordx4 v[224:227], v248, s[28:29]
	global_load_dwordx4 v[228:231], v248, s[28:29] offset:256
	s_waitcnt vmcnt(8)
	v_lshlrev_b32_e32 v132, 16, v152
	v_and_b32_e32 v133, 0xffff0000, v152
	v_lshlrev_b32_e32 v134, 16, v153
	v_and_b32_e32 v135, 0xffff0000, v153
	v_lshlrev_b32_e32 v136, 16, v154
	v_and_b32_e32 v137, 0xffff0000, v154
	v_lshlrev_b32_e32 v138, 16, v155
	v_and_b32_e32 v139, 0xffff0000, v155
	v_pk_mul_f32 v[124:125], v[124:125], v[132:133]
	v_pk_mul_f32 v[126:127], v[126:127], v[134:135]
	v_pk_mul_f32 v[120:121], v[120:121], v[136:137]
	v_pk_mul_f32 v[122:123], v[122:123], v[138:139]
	v_cvt_pk_bf16_f32 v152, v124, v125
	v_cvt_pk_bf16_f32 v153, v126, v127
	v_cvt_pk_bf16_f32 v154, v120, v121
	v_cvt_pk_bf16_f32 v155, v122, v123
	global_store_dwordx4 v250, v[152:155], s[24:25]
	v_lshlrev_b32_e32 v132, 16, v156
	v_and_b32_e32 v133, 0xffff0000, v156
	v_lshlrev_b32_e32 v134, 16, v157
	v_and_b32_e32 v135, 0xffff0000, v157
	v_lshlrev_b32_e32 v136, 16, v158
	v_and_b32_e32 v137, 0xffff0000, v158
	v_lshlrev_b32_e32 v138, 16, v159
	v_and_b32_e32 v139, 0xffff0000, v159
	v_pk_mul_f32 v[116:117], v[116:117], v[132:133]
	v_pk_mul_f32 v[118:119], v[118:119], v[134:135]
	v_pk_mul_f32 v[112:113], v[112:113], v[136:137]
	v_pk_mul_f32 v[114:115], v[114:115], v[138:139]
	v_cvt_pk_bf16_f32 v156, v116, v117
	v_cvt_pk_bf16_f32 v157, v118, v119
	v_cvt_pk_bf16_f32 v158, v112, v113
	v_cvt_pk_bf16_f32 v159, v114, v115
	global_store_dwordx4 v250, v[156:159], s[24:25] offset:256
	v_lshlrev_b32_e32 v132, 16, v160
	v_and_b32_e32 v133, 0xffff0000, v160
	v_lshlrev_b32_e32 v134, 16, v161
	v_and_b32_e32 v135, 0xffff0000, v161
	v_lshlrev_b32_e32 v136, 16, v162
	v_and_b32_e32 v137, 0xffff0000, v162
	v_lshlrev_b32_e32 v138, 16, v163
	v_and_b32_e32 v139, 0xffff0000, v163
	v_pk_mul_f32 v[108:109], v[108:109], v[132:133]
	v_pk_mul_f32 v[110:111], v[110:111], v[134:135]
	v_pk_mul_f32 v[104:105], v[104:105], v[136:137]
	v_pk_mul_f32 v[106:107], v[106:107], v[138:139]
	v_cvt_pk_bf16_f32 v160, v108, v109
	v_cvt_pk_bf16_f32 v161, v110, v111
	v_cvt_pk_bf16_f32 v162, v104, v105
	v_cvt_pk_bf16_f32 v163, v106, v107
	v_add_u32_e32 v250, 0x8000, v250
	global_store_dwordx4 v250, v[160:163], s[24:25]
	v_lshlrev_b32_e32 v132, 16, v164
	v_and_b32_e32 v133, 0xffff0000, v164
	v_lshlrev_b32_e32 v134, 16, v165
	v_and_b32_e32 v135, 0xffff0000, v165
	v_lshlrev_b32_e32 v136, 16, v166
	v_and_b32_e32 v137, 0xffff0000, v166
	v_lshlrev_b32_e32 v138, 16, v167
	v_and_b32_e32 v139, 0xffff0000, v167
	v_pk_mul_f32 v[100:101], v[100:101], v[132:133]
	v_pk_mul_f32 v[102:103], v[102:103], v[134:135]
	v_pk_mul_f32 v[96:97], v[96:97], v[136:137]
	v_pk_mul_f32 v[98:99], v[98:99], v[138:139]
	v_cvt_pk_bf16_f32 v164, v100, v101
	v_cvt_pk_bf16_f32 v165, v102, v103
	v_cvt_pk_bf16_f32 v166, v96, v97
	v_cvt_pk_bf16_f32 v167, v98, v99
	global_store_dwordx4 v250, v[164:167], s[24:25] offset:256
	v_add_u32_e32 v248, 0x10000, v248
	global_load_dwordx4 v[152:155], v248, s[28:29]
	global_load_dwordx4 v[156:159], v248, s[28:29] offset:256
	v_add_u32_e32 v248, 0x10000, v248
	global_load_dwordx4 v[160:163], v248, s[28:29]
	global_load_dwordx4 v[164:167], v248, s[28:29] offset:256
	s_waitcnt vmcnt(12)
; __device__ __forceinline__ unsigned cvt_pk_bf16(float lo, float hi) { unsigned r; asm volatile("v_cvt_pk_bf16_f32 %0, %1, %2" : "=v"(r) : "v"(lo), "v"(hi)); return r; }
; __device__ __forceinline__ float bf_lo(unsigned w) { return __uint_as_float(w << 16); }
; __device__ __forceinline__ float bf_hi(unsigned w) { return __uint_as_float(w & 0xffff0000u); }
;     __device__ __forceinline__ void operator()(const f32x4 (&acc)[2][2][4][2], const Unit& u, int wr, int wc, int fr, int fq) const {
;     ...
;                 for (int bj = 0; bj < 2; ++bj) { const int col = col0 + bj * HALF;
;                     const u32x4 gw = *(const u32x4*)(proj + (size_t)6 * 512 * M_ROWS + row * 2048 + goff + col);
;                     const f32x4 g0 = (f32x4){bf_lo(gw.x), bf_hi(gw.x), bf_lo(gw.y), bf_hi(gw.y)}, g1 = (f32x4){bf_lo(gw.z), bf_hi(gw.z), bf_lo(gw.w), bf_hi(gw.w)};
;                     f32x4 v0 = acc[ai][bj][m][0] * g0, v1 = acc[ai][bj][m][1] * g1; bf16_t* mp = merged + row * 1024 + col;
;                     if (second) { const u32x4 tw = *(const u32x4*)mp;
;                         v0 = v0 + (f32x4){bf_lo(tw.x), bf_hi(tw.x), bf_lo(tw.y), bf_hi(tw.y)}; v1 = v1 + (f32x4){bf_lo(tw.z), bf_hi(tw.z), bf_lo(tw.w), bf_hi(tw.w)}; }
;                     u32x4 w; w.x = cvt_pk_bf16(v0[0], v0[1]); w.y = cvt_pk_bf16(v0[2], v0[3]); w.z = cvt_pk_bf16(v1[0], v1[1]); w.w = cvt_pk_bf16(v1[2], v1[3]);
;                     *(u32x4*)mp = w; }
	v_lshlrev_b32_e32 v132, 16, v184
	v_and_b32_e32 v133, 0xffff0000, v184
	v_lshlrev_b32_e32 v134, 16, v185
	v_and_b32_e32 v135, 0xffff0000, v185
	v_lshlrev_b32_e32 v136, 16, v186
	v_and_b32_e32 v137, 0xffff0000, v186
	v_lshlrev_b32_e32 v138, 16, v187
	v_and_b32_e32 v139, 0xffff0000, v187
	v_pk_mul_f32 v[92:93], v[92:93], v[132:133]
	v_pk_mul_f32 v[94:95], v[94:95], v[134:135]
	v_pk_mul_f32 v[88:89], v[88:89], v[136:137]
	v_pk_mul_f32 v[90:91], v[90:91], v[138:139]
	v_cvt_pk_bf16_f32 v184, v92, v93
	v_cvt_pk_bf16_f32 v185, v94, v95
	v_cvt_pk_bf16_f32 v186, v88, v89
	v_cvt_pk_bf16_f32 v187, v90, v91
	v_add_u32_e32 v250, 0x8000, v250
	global_store_dwordx4 v250, v[184:187], s[24:25]
	v_lshlrev_b32_e32 v132, 16, v188
	v_and_b32_e32 v133, 0xffff0000, v188
	v_lshlrev_b32_e32 v134, 16, v189
	v_and_b32_e32 v135, 0xffff0000, v189
	v_lshlrev_b32_e32 v136, 16, v190
	v_and_b32_e32 v137, 0xffff0000, v190
	v_lshlrev_b32_e32 v138, 16, v191
	v_and_b32_e32 v139, 0xffff0000, v191
	v_pk_mul_f32 v[84:85], v[84:85], v[132:133]
	v_pk_mul_f32 v[86:87], v[86:87], v[134:135]
	v_pk_mul_f32 v[80:81], v[80:81], v[136:137]
	v_pk_mul_f32 v[82:83], v[82:83], v[138:139]
	v_cvt_pk_bf16_f32 v188, v84, v85
	v_cvt_pk_bf16_f32 v189, v86, v87
	v_cvt_pk_bf16_f32 v190, v80, v81
	v_cvt_pk_bf16_f32 v191, v82, v83
	global_store_dwordx4 v250, v[188:191], s[24:25] offset:256
	v_lshlrev_b32_e32 v132, 16, v192
	v_and_b32_e32 v133, 0xffff0000, v192
	v_lshlrev_b32_e32 v134, 16, v193
	v_and_b32_e32 v135, 0xffff0000, v193
	v_lshlrev_b32_e32 v136, 16, v194
	v_and_b32_e32 v137, 0xffff0000, v194
	v_lshlrev_b32_e32 v138, 16, v195
	v_and_b32_e32 v139, 0xffff0000, v195
	v_pk_mul_f32 v[76:77], v[76:77], v[132:133]
	v_pk_mul_f32 v[78:79], v[78:79], v[134:135]
	v_pk_mul_f32 v[72:73], v[72:73], v[136:137]
	v_pk_mul_f32 v[74:75], v[74:75], v[138:139]
	v_cvt_pk_bf16_f32 v192, v76, v77
	v_cvt_pk_bf16_f32 v193, v78, v79
	v_cvt_pk_bf16_f32 v194, v72, v73
	v_cvt_pk_bf16_f32 v195, v74, v75
	v_add_u32_e32 v250, 0x8000, v250
	global_store_dwordx4 v250, v[192:195], s[24:25]
	v_lshlrev_b32_e32 v132, 16, v196
	v_and_b32_e32 v133, 0xffff0000, v196
	v_lshlrev_b32_e32 v134, 16, v197
	v_and_b32_e32 v135, 0xffff0000, v197
	v_lshlrev_b32_e32 v136, 16, v198
	v_and_b32_e32 v137, 0xffff0000, v198
	v_lshlrev_b32_e32 v138, 16, v199
	v_and_b32_e32 v139, 0xffff0000, v199
	v_pk_mul_f32 v[68:69], v[68:69], v[132:133]
	v_pk_mul_f32 v[70:71], v[70:71], v[134:135]
	v_pk_mul_f32 v[64:65], v[64:65], v[136:137]
	v_pk_mul_f32 v[66:67], v[66:67], v[138:139]
	v_cvt_pk_bf16_f32 v196, v68, v69
	v_cvt_pk_bf16_f32 v197, v70, v71
	v_cvt_pk_bf16_f32 v198, v64, v65
	v_cvt_pk_bf16_f32 v199, v66, v67
	global_store_dwordx4 v250, v[196:199], s[24:25] offset:256
	s_waitcnt vmcnt(12)
	v_lshlrev_b32_e32 v132, 16, v216
	v_and_b32_e32 v133, 0xffff0000, v216
	v_lshlrev_b32_e32 v134, 16, v217
	v_and_b32_e32 v135, 0xffff0000, v217
	v_lshlrev_b32_e32 v136, 16, v218
	v_and_b32_e32 v137, 0xffff0000, v218
	v_lshlrev_b32_e32 v138, 16, v219
	v_and_b32_e32 v139, 0xffff0000, v219
	v_pk_mul_f32 v[60:61], v[60:61], v[132:133]
	v_pk_mul_f32 v[62:63], v[62:63], v[134:135]
	v_pk_mul_f32 v[56:57], v[56:57], v[136:137]
	v_pk_mul_f32 v[58:59], v[58:59], v[138:139]
	v_cvt_pk_bf16_f32 v216, v60, v61
	v_cvt_pk_bf16_f32 v217, v62, v63
	v_cvt_pk_bf16_f32 v218, v56, v57
	v_cvt_pk_bf16_f32 v219, v58, v59
	v_add_u32_e32 v250, 0x28000, v250
	global_store_dwordx4 v250, v[216:219], s[24:25]
	v_lshlrev_b32_e32 v132, 16, v220
	v_and_b32_e32 v133, 0xffff0000, v220
	v_lshlrev_b32_e32 v134, 16, v221
	v_and_b32_e32 v135, 0xffff0000, v221
	v_lshlrev_b32_e32 v136, 16, v222
	v_and_b32_e32 v137, 0xffff0000, v222
	v_lshlrev_b32_e32 v138, 16, v223
	v_and_b32_e32 v139, 0xffff0000, v223
	v_pk_mul_f32 v[52:53], v[52:53], v[132:133]
	v_pk_mul_f32 v[54:55], v[54:55], v[134:135]
	v_pk_mul_f32 v[48:49], v[48:49], v[136:137]
	v_pk_mul_f32 v[50:51], v[50:51], v[138:139]
	v_cvt_pk_bf16_f32 v220, v52, v53
	v_cvt_pk_bf16_f32 v221, v54, v55
	v_cvt_pk_bf16_f32 v222, v48, v49
	v_cvt_pk_bf16_f32 v223, v50, v51
	global_store_dwordx4 v250, v[220:223], s[24:25] offset:256
	v_lshlrev_b32_e32 v132, 16, v224
	v_and_b32_e32 v133, 0xffff0000, v224
	v_lshlrev_b32_e32 v134, 16, v225
	v_and_b32_e32 v135, 0xffff0000, v225
	v_lshlrev_b32_e32 v136, 16, v226
	v_and_b32_e32 v137, 0xffff0000, v226
	v_lshlrev_b32_e32 v138, 16, v227
	v_and_b32_e32 v139, 0xffff0000, v227
	v_pk_mul_f32 v[44:45], v[44:45], v[132:133]
	v_pk_mul_f32 v[46:47], v[46:47], v[134:135]
	v_pk_mul_f32 v[40:41], v[40:41], v[136:137]
	v_pk_mul_f32 v[42:43], v[42:43], v[138:139]
	v_cvt_pk_bf16_f32 v224, v44, v45
	v_cvt_pk_bf16_f32 v225, v46, v47
	v_cvt_pk_bf16_f32 v226, v40, v41
	v_cvt_pk_bf16_f32 v227, v42, v43
	v_add_u32_e32 v250, 0x8000, v250
	global_store_dwordx4 v250, v[224:227], s[24:25]
	v_lshlrev_b32_e32 v132, 16, v228
	v_and_b32_e32 v133, 0xffff0000, v228
	v_lshlrev_b32_e32 v134, 16, v229
	v_and_b32_e32 v135, 0xffff0000, v229
	v_lshlrev_b32_e32 v136, 16, v230
	v_and_b32_e32 v137, 0xffff0000, v230
	v_lshlrev_b32_e32 v138, 16, v231
	v_and_b32_e32 v139, 0xffff0000, v231
	v_pk_mul_f32 v[36:37], v[36:37], v[132:133]
	v_pk_mul_f32 v[38:39], v[38:39], v[134:135]
	v_pk_mul_f32 v[32:33], v[32:33], v[136:137]
	v_pk_mul_f32 v[34:35], v[34:35], v[138:139]
	v_cvt_pk_bf16_f32 v228, v36, v37
	v_cvt_pk_bf16_f32 v229, v38, v39
	v_cvt_pk_bf16_f32 v230, v32, v33
	v_cvt_pk_bf16_f32 v231, v34, v35
	global_store_dwordx4 v250, v[228:231], s[24:25] offset:256
	s_waitcnt vmcnt(8)
; __device__ __forceinline__ unsigned cvt_pk_bf16(float lo, float hi) { unsigned r; asm volatile("v_cvt_pk_bf16_f32 %0, %1, %2" : "=v"(r) : "v"(lo), "v"(hi)); return r; }
; __device__ __forceinline__ float bf_lo(unsigned w) { return __uint_as_float(w << 16); }
; __device__ __forceinline__ float bf_hi(unsigned w) { return __uint_as_float(w & 0xffff0000u); }
;     __device__ __forceinline__ void operator()(const f32x4 (&acc)[2][2][4][2], const Unit& u, int wr, int wc, int fr, int fq) const {
;     ...
;                 for (int bj = 0; bj < 2; ++bj) { const int col = col0 + bj * HALF;
;                     const u32x4 gw = *(const u32x4*)(proj + (size_t)6 * 512 * M_ROWS + row * 2048 + goff + col);
;                     const f32x4 g0 = (f32x4){bf_lo(gw.x), bf_hi(gw.x), bf_lo(gw.y), bf_hi(gw.y)}, g1 = (f32x4){bf_lo(gw.z), bf_hi(gw.z), bf_lo(gw.w), bf_hi(gw.w)};
;                     f32x4 v0 = acc[ai][bj][m][0] * g0, v1 = acc[ai][bj][m][1] * g1; bf16_t* mp = merged + row * 1024 + col;
;                     if (second) { const u32x4 tw = *(const u32x4*)mp;
;                         v0 = v0 + (f32x4){bf_lo(tw.x), bf_hi(tw.x), bf_lo(tw.y), bf_hi(tw.y)}; v1 = v1 + (f32x4){bf_lo(tw.z), bf_hi(tw.z), bf_lo(tw.w), bf_hi(tw.w)}; }
;                     u32x4 w; w.x = cvt_pk_bf16(v0[0], v0[1]); w.y = cvt_pk_bf16(v0[2], v0[3]); w.z = cvt_pk_bf16(v1[0], v1[1]); w.w = cvt_pk_bf16(v1[2], v1[3]);
;                     *(u32x4*)mp = w; }
	v_lshlrev_b32_e32 v132, 16, v152
	v_and_b32_e32 v133, 0xffff0000, v152
	v_lshlrev_b32_e32 v134, 16, v153
	v_and_b32_e32 v135, 0xffff0000, v153
	v_lshlrev_b32_e32 v136, 16, v154
	v_and_b32_e32 v137, 0xffff0000, v154
	v_lshlrev_b32_e32 v138, 16, v155
	v_and_b32_e32 v139, 0xffff0000, v155
	v_pk_mul_f32 v[28:29], v[28:29], v[132:133]
	v_pk_mul_f32 v[30:31], v[30:31], v[134:135]
	v_pk_mul_f32 v[24:25], v[24:25], v[136:137]
	v_pk_mul_f32 v[26:27], v[26:27], v[138:139]
	v_cvt_pk_bf16_f32 v152, v28, v29
	v_cvt_pk_bf16_f32 v153, v30, v31
	v_cvt_pk_bf16_f32 v154, v24, v25
	v_cvt_pk_bf16_f32 v155, v26, v27
	v_add_u32_e32 v250, 0x8000, v250
	global_store_dwordx4 v250, v[152:155], s[24:25]
	v_lshlrev_b32_e32 v132, 16, v156
	v_and_b32_e32 v133, 0xffff0000, v156
	v_lshlrev_b32_e32 v134, 16, v157
	v_and_b32_e32 v135, 0xffff0000, v157
	v_lshlrev_b32_e32 v136, 16, v158
	v_and_b32_e32 v137, 0xffff0000, v158
	v_lshlrev_b32_e32 v138, 16, v159
	v_and_b32_e32 v139, 0xffff0000, v159
	v_pk_mul_f32 v[20:21], v[20:21], v[132:133]
	v_pk_mul_f32 v[22:23], v[22:23], v[134:135]
	v_pk_mul_f32 v[16:17], v[16:17], v[136:137]
	v_pk_mul_f32 v[18:19], v[18:19], v[138:139]
	v_cvt_pk_bf16_f32 v156, v20, v21
	v_cvt_pk_bf16_f32 v157, v22, v23
	v_cvt_pk_bf16_f32 v158, v16, v17
	v_cvt_pk_bf16_f32 v159, v18, v19
	global_store_dwordx4 v250, v[156:159], s[24:25] offset:256
	v_lshlrev_b32_e32 v132, 16, v160
	v_and_b32_e32 v133, 0xffff0000, v160
	v_lshlrev_b32_e32 v134, 16, v161
	v_and_b32_e32 v135, 0xffff0000, v161
	v_lshlrev_b32_e32 v136, 16, v162
	v_and_b32_e32 v137, 0xffff0000, v162
	v_lshlrev_b32_e32 v138, 16, v163
	v_and_b32_e32 v139, 0xffff0000, v163
	v_pk_mul_f32 v[12:13], v[12:13], v[132:133]
	v_pk_mul_f32 v[14:15], v[14:15], v[134:135]
	v_pk_mul_f32 v[8:9], v[8:9], v[136:137]
	v_pk_mul_f32 v[10:11], v[10:11], v[138:139]
	v_cvt_pk_bf16_f32 v160, v12, v13
	v_cvt_pk_bf16_f32 v161, v14, v15
	v_cvt_pk_bf16_f32 v162, v8, v9
	v_cvt_pk_bf16_f32 v163, v10, v11
	v_add_u32_e32 v250, 0x8000, v250
	global_store_dwordx4 v250, v[160:163], s[24:25]
	v_lshlrev_b32_e32 v132, 16, v164
	v_and_b32_e32 v133, 0xffff0000, v164
	v_lshlrev_b32_e32 v134, 16, v165
	v_and_b32_e32 v135, 0xffff0000, v165
	v_lshlrev_b32_e32 v136, 16, v166
	v_and_b32_e32 v137, 0xffff0000, v166
	v_lshlrev_b32_e32 v138, 16, v167
	v_and_b32_e32 v139, 0xffff0000, v167
	v_pk_mul_f32 v[4:5], v[4:5], v[132:133]
	v_pk_mul_f32 v[6:7], v[6:7], v[134:135]
	v_pk_mul_f32 v[0:1], v[0:1], v[136:137]
	v_pk_mul_f32 v[2:3], v[2:3], v[138:139]
	v_cvt_pk_bf16_f32 v164, v4, v5
	v_cvt_pk_bf16_f32 v165, v6, v7
	v_cvt_pk_bf16_f32 v166, v0, v1
	v_cvt_pk_bf16_f32 v167, v2, v3
	global_store_dwordx4 v250, v[164:167], s[24:25] offset:256
	s_branch .Lmrg_l0_done
.Lmrg_l0_second:
	global_load_dwordx4 v[152:155], v248, s[28:29]
	global_load_dwordx4 v[168:171], v249, s[24:25]
	global_load_dwordx4 v[156:159], v248, s[28:29] offset:256
	global_load_dwordx4 v[172:175], v249, s[24:25] offset:256
	v_add_u32_e32 v248, 0x10000, v248
	v_add_u32_e32 v249, 0x8000, v249
	global_load_dwordx4 v[160:163], v248, s[28:29]
	global_load_dwordx4 v[176:179], v249, s[24:25]
	global_load_dwordx4 v[164:167], v248, s[28:29] offset:256
	global_load_dwordx4 v[180:183], v249, s[24:25] offset:256
	v_add_u32_e32 v248, 0x10000, v248
	v_add_u32_e32 v249, 0x8000, v249
	global_load_dwordx4 v[184:187], v248, s[28:29]
	global_load_dwordx4 v[200:203], v249, s[24:25]
	global_load_dwordx4 v[188:191], v248, s[28:29] offset:256
	global_load_dwordx4 v[204:207], v249, s[24:25] offset:256
	v_add_u32_e32 v248, 0x10000, v248
	v_add_u32_e32 v249, 0x8000, v249
	global_load_dwordx4 v[192:195], v248, s[28:29]
	global_load_dwordx4 v[208:211], v249, s[24:25]
	global_load_dwordx4 v[196:199], v248, s[28:29] offset:256
	global_load_dwordx4 v[212:215], v249, s[24:25] offset:256
	v_add_u32_e32 v248, 0x50000, v248
	v_add_u32_e32 v249, 0x28000, v249
	global_load_dwordx4 v[216:219], v248, s[28:29]
	global_load_dwordx4 v[232:235], v249, s[24:25]
	global_load_dwordx4 v[220:223], v248, s[28:29] offset:256
	global_load_dwordx4 v[236:239], v249, s[24:25] offset:256
	v_add_u32_e32 v248, 0x10000, v248
	v_add_u32_e32 v249, 0x8000, v249
	global_load_dwordx4 v[224:227], v248, s[28:29]
	global_load_dwordx4 v[240:243], v249, s[24:25]
	global_load_dwordx4 v[228:231], v248, s[28:29] offset:256
	global_load_dwordx4 v[244:247], v249, s[24:25] offset:256
	s_waitcnt vmcnt(16)
; __device__ __forceinline__ unsigned cvt_pk_bf16(float lo, float hi) { unsigned r; asm volatile("v_cvt_pk_bf16_f32 %0, %1, %2" : "=v"(r) : "v"(lo), "v"(hi)); return r; }
; __device__ __forceinline__ float bf_lo(unsigned w) { return __uint_as_float(w << 16); }
; __device__ __forceinline__ float bf_hi(unsigned w) { return __uint_as_float(w & 0xffff0000u); }
;     __device__ __forceinline__ void operator()(const f32x4 (&acc)[2][2][4][2], const Unit& u, int wr, int wc, int fr, int fq) const {
;     ...
;                     const u32x4 gw = *(const u32x4*)(proj + (size_t)6 * 512 * M_ROWS + row * 2048 + goff + col);
;                     const f32x4 g0 = (f32x4){bf_lo(gw.x), bf_hi(gw.x), bf_lo(gw.y), bf_hi(gw.y)}, g1 = (f32x4){bf_lo(gw.z), bf_hi(gw.z), bf_lo(gw.w), bf_hi(gw.w)};
;                     f32x4 v0 = acc[ai][bj][m][0] * g0, v1 = acc[ai][bj][m][1] * g1; bf16_t* mp = merged + row * 1024 + col;
;                     if (second) { const u32x4 tw = *(const u32x4*)mp;
;                         v0 = v0 + (f32x4){bf_lo(tw.x), bf_hi(tw.x), bf_lo(tw.y), bf_hi(tw.y)}; v1 = v1 + (f32x4){bf_lo(tw.z), bf_hi(tw.z), bf_lo(tw.w), bf_hi(tw.w)}; }
;                     u32x4 w; w.x = cvt_pk_bf16(v0[0], v0[1]); w.y = cvt_pk_bf16(v0[2], v0[3]); w.z = cvt_pk_bf16(v1[0], v1[1]); w.w = cvt_pk_bf16(v1[2], v1[3]);
;                     *(u32x4*)mp = w; }
	v_lshlrev_b32_e32 v132, 16, v152
	v_and_b32_e32 v133, 0xffff0000, v152
	v_lshlrev_b32_e32 v134, 16, v153
	v_and_b32_e32 v135, 0xffff0000, v153
	v_lshlrev_b32_e32 v136, 16, v154
	v_and_b32_e32 v137, 0xffff0000, v154
	v_lshlrev_b32_e32 v138, 16, v155
	v_and_b32_e32 v139, 0xffff0000, v155
	v_pk_mul_f32 v[124:125], v[124:125], v[132:133]
	v_pk_mul_f32 v[126:127], v[126:127], v[134:135]
	v_pk_mul_f32 v[120:121], v[120:121], v[136:137]
	v_pk_mul_f32 v[122:123], v[122:123], v[138:139]
	v_lshlrev_b32_e32 v132, 16, v168
	v_and_b32_e32 v133, 0xffff0000, v168
	v_lshlrev_b32_e32 v134, 16, v169
	v_and_b32_e32 v135, 0xffff0000, v169
	v_lshlrev_b32_e32 v136, 16, v170
	v_and_b32_e32 v137, 0xffff0000, v170
	v_lshlrev_b32_e32 v138, 16, v171
	v_and_b32_e32 v139, 0xffff0000, v171
	v_pk_add_f32 v[124:125], v[124:125], v[132:133]
	v_pk_add_f32 v[126:127], v[126:127], v[134:135]
	v_pk_add_f32 v[120:121], v[120:121], v[136:137]
	v_pk_add_f32 v[122:123], v[122:123], v[138:139]
	v_cvt_pk_bf16_f32 v152, v124, v125
	v_cvt_pk_bf16_f32 v153, v126, v127
	v_cvt_pk_bf16_f32 v154, v120, v121
	v_cvt_pk_bf16_f32 v155, v122, v123
	global_store_dwordx4 v250, v[152:155], s[24:25]
	v_lshlrev_b32_e32 v132, 16, v156
	v_and_b32_e32 v133, 0xffff0000, v156
	v_lshlrev_b32_e32 v134, 16, v157
	v_and_b32_e32 v135, 0xffff0000, v157
	v_lshlrev_b32_e32 v136, 16, v158
	v_and_b32_e32 v137, 0xffff0000, v158
	v_lshlrev_b32_e32 v138, 16, v159
	v_and_b32_e32 v139, 0xffff0000, v159
	v_pk_mul_f32 v[116:117], v[116:117], v[132:133]
	v_pk_mul_f32 v[118:119], v[118:119], v[134:135]
	v_pk_mul_f32 v[112:113], v[112:113], v[136:137]
	v_pk_mul_f32 v[114:115], v[114:115], v[138:139]
	v_lshlrev_b32_e32 v132, 16, v172
	v_and_b32_e32 v133, 0xffff0000, v172
	v_lshlrev_b32_e32 v134, 16, v173
	v_and_b32_e32 v135, 0xffff0000, v173
	v_lshlrev_b32_e32 v136, 16, v174
	v_and_b32_e32 v137, 0xffff0000, v174
	v_lshlrev_b32_e32 v138, 16, v175
	v_and_b32_e32 v139, 0xffff0000, v175
	v_pk_add_f32 v[116:117], v[116:117], v[132:133]
	v_pk_add_f32 v[118:119], v[118:119], v[134:135]
	v_pk_add_f32 v[112:113], v[112:113], v[136:137]
	v_pk_add_f32 v[114:115], v[114:115], v[138:139]
	v_cvt_pk_bf16_f32 v156, v116, v117
	v_cvt_pk_bf16_f32 v157, v118, v119
	v_cvt_pk_bf16_f32 v158, v112, v113
	v_cvt_pk_bf16_f32 v159, v114, v115
	global_store_dwordx4 v250, v[156:159], s[24:25] offset:256
	v_lshlrev_b32_e32 v132, 16, v160
	v_and_b32_e32 v133, 0xffff0000, v160
	v_lshlrev_b32_e32 v134, 16, v161
	v_and_b32_e32 v135, 0xffff0000, v161
	v_lshlrev_b32_e32 v136, 16, v162
	v_and_b32_e32 v137, 0xffff0000, v162
	v_lshlrev_b32_e32 v138, 16, v163
	v_and_b32_e32 v139, 0xffff0000, v163
	v_pk_mul_f32 v[108:109], v[108:109], v[132:133]
	v_pk_mul_f32 v[110:111], v[110:111], v[134:135]
	v_pk_mul_f32 v[104:105], v[104:105], v[136:137]
	v_pk_mul_f32 v[106:107], v[106:107], v[138:139]
	v_lshlrev_b32_e32 v132, 16, v176
	v_and_b32_e32 v133, 0xffff0000, v176
	v_lshlrev_b32_e32 v134, 16, v177
	v_and_b32_e32 v135, 0xffff0000, v177
	v_lshlrev_b32_e32 v136, 16, v178
	v_and_b32_e32 v137, 0xffff0000, v178
	v_lshlrev_b32_e32 v138, 16, v179
	v_and_b32_e32 v139, 0xffff0000, v179
	v_pk_add_f32 v[108:109], v[108:109], v[132:133]
	v_pk_add_f32 v[110:111], v[110:111], v[134:135]
	v_pk_add_f32 v[104:105], v[104:105], v[136:137]
	v_pk_add_f32 v[106:107], v[106:107], v[138:139]
	v_cvt_pk_bf16_f32 v160, v108, v109
	v_cvt_pk_bf16_f32 v161, v110, v111
	v_cvt_pk_bf16_f32 v162, v104, v105
	v_cvt_pk_bf16_f32 v163, v106, v107
	v_add_u32_e32 v250, 0x8000, v250
	global_store_dwordx4 v250, v[160:163], s[24:25]
	v_lshlrev_b32_e32 v132, 16, v164
	v_and_b32_e32 v133, 0xffff0000, v164
	v_lshlrev_b32_e32 v134, 16, v165
	v_and_b32_e32 v135, 0xffff0000, v165
	v_lshlrev_b32_e32 v136, 16, v166
	v_and_b32_e32 v137, 0xffff0000, v166
	v_lshlrev_b32_e32 v138, 16, v167
	v_and_b32_e32 v139, 0xffff0000, v167
	v_pk_mul_f32 v[100:101], v[100:101], v[132:133]
	v_pk_mul_f32 v[102:103], v[102:103], v[134:135]
	v_pk_mul_f32 v[96:97], v[96:97], v[136:137]
	v_pk_mul_f32 v[98:99], v[98:99], v[138:139]
	v_lshlrev_b32_e32 v132, 16, v180
	v_and_b32_e32 v133, 0xffff0000, v180
	v_lshlrev_b32_e32 v134, 16, v181
	v_and_b32_e32 v135, 0xffff0000, v181
	v_lshlrev_b32_e32 v136, 16, v182
	v_and_b32_e32 v137, 0xffff0000, v182
	v_lshlrev_b32_e32 v138, 16, v183
	v_and_b32_e32 v139, 0xffff0000, v183
	v_pk_add_f32 v[100:101], v[100:101], v[132:133]
	v_pk_add_f32 v[102:103], v[102:103], v[134:135]
	v_pk_add_f32 v[96:97], v[96:97], v[136:137]
	v_pk_add_f32 v[98:99], v[98:99], v[138:139]
	v_cvt_pk_bf16_f32 v164, v100, v101
	v_cvt_pk_bf16_f32 v165, v102, v103
	v_cvt_pk_bf16_f32 v166, v96, v97
	v_cvt_pk_bf16_f32 v167, v98, v99
	global_store_dwordx4 v250, v[164:167], s[24:25] offset:256
	v_add_u32_e32 v248, 0x10000, v248
	v_add_u32_e32 v249, 0x8000, v249
	global_load_dwordx4 v[152:155], v248, s[28:29]
	global_load_dwordx4 v[168:171], v249, s[24:25]
	global_load_dwordx4 v[156:159], v248, s[28:29] offset:256
	global_load_dwordx4 v[172:175], v249, s[24:25] offset:256
	v_add_u32_e32 v248, 0x10000, v248
	v_add_u32_e32 v249, 0x8000, v249
	global_load_dwordx4 v[160:163], v248, s[28:29]
	global_load_dwordx4 v[176:179], v249, s[24:25]
	global_load_dwordx4 v[164:167], v248, s[28:29] offset:256
	global_load_dwordx4 v[180:183], v249, s[24:25] offset:256
	s_waitcnt vmcnt(20)
; __device__ __forceinline__ unsigned cvt_pk_bf16(float lo, float hi) { unsigned r; asm volatile("v_cvt_pk_bf16_f32 %0, %1, %2" : "=v"(r) : "v"(lo), "v"(hi)); return r; }
; __device__ __forceinline__ float bf_lo(unsigned w) { return __uint_as_float(w << 16); }
; __device__ __forceinline__ float bf_hi(unsigned w) { return __uint_as_float(w & 0xffff0000u); }
;     __device__ __forceinline__ void operator()(const f32x4 (&acc)[2][2][4][2], const Unit& u, int wr, int wc, int fr, int fq) const {
;     ...
;                     const u32x4 gw = *(const u32x4*)(proj + (size_t)6 * 512 * M_ROWS + row * 2048 + goff + col);
;                     const f32x4 g0 = (f32x4){bf_lo(gw.x), bf_hi(gw.x), bf_lo(gw.y), bf_hi(gw.y)}, g1 = (f32x4){bf_lo(gw.z), bf_hi(gw.z), bf_lo(gw.w), bf_hi(gw.w)};
;                     f32x4 v0 = acc[ai][bj][m][0] * g0, v1 = acc[ai][bj][m][1] * g1; bf16_t* mp = merged + row * 1024 + col;
;                     if (second) { const u32x4 tw = *(const u32x4*)mp;
;                         v0 = v0 + (f32x4){bf_lo(tw.x), bf_hi(tw.x), bf_lo(tw.y), bf_hi(tw.y)}; v1 = v1 + (f32x4){bf_lo(tw.z), bf_hi(tw.z), bf_lo(tw.w), bf_hi(tw.w)}; }
;                     u32x4 w; w.x = cvt_pk_bf16(v0[0], v0[1]); w.y = cvt_pk_bf16(v0[2], v0[3]); w.z = cvt_pk_bf16(v1[0], v1[1]); w.w = cvt_pk_bf16(v1[2], v1[3]);
;                     *(u32x4*)mp = w; }
	v_lshlrev_b32_e32 v132, 16, v184
	v_and_b32_e32 v133, 0xffff0000, v184
	v_lshlrev_b32_e32 v134, 16, v185
	v_and_b32_e32 v135, 0xffff0000, v185
	v_lshlrev_b32_e32 v136, 16, v186
	v_and_b32_e32 v137, 0xffff0000, v186
	v_lshlrev_b32_e32 v138, 16, v187
	v_and_b32_e32 v139, 0xffff0000, v187
	v_pk_mul_f32 v[92:93], v[92:93], v[132:133]
	v_pk_mul_f32 v[94:95], v[94:95], v[134:135]
	v_pk_mul_f32 v[88:89], v[88:89], v[136:137]
	v_pk_mul_f32 v[90:91], v[90:91], v[138:139]
	v_lshlrev_b32_e32 v132, 16, v200
	v_and_b32_e32 v133, 0xffff0000, v200
	v_lshlrev_b32_e32 v134, 16, v201
	v_and_b32_e32 v135, 0xffff0000, v201
	v_lshlrev_b32_e32 v136, 16, v202
	v_and_b32_e32 v137, 0xffff0000, v202
	v_lshlrev_b32_e32 v138, 16, v203
	v_and_b32_e32 v139, 0xffff0000, v203
	v_pk_add_f32 v[92:93], v[92:93], v[132:133]
	v_pk_add_f32 v[94:95], v[94:95], v[134:135]
	v_pk_add_f32 v[88:89], v[88:89], v[136:137]
	v_pk_add_f32 v[90:91], v[90:91], v[138:139]
	v_cvt_pk_bf16_f32 v184, v92, v93
	v_cvt_pk_bf16_f32 v185, v94, v95
	v_cvt_pk_bf16_f32 v186, v88, v89
	v_cvt_pk_bf16_f32 v187, v90, v91
	v_add_u32_e32 v250, 0x8000, v250
	global_store_dwordx4 v250, v[184:187], s[24:25]
	v_lshlrev_b32_e32 v132, 16, v188
	v_and_b32_e32 v133, 0xffff0000, v188
	v_lshlrev_b32_e32 v134, 16, v189
	v_and_b32_e32 v135, 0xffff0000, v189
	v_lshlrev_b32_e32 v136, 16, v190
	v_and_b32_e32 v137, 0xffff0000, v190
	v_lshlrev_b32_e32 v138, 16, v191
	v_and_b32_e32 v139, 0xffff0000, v191
	v_pk_mul_f32 v[84:85], v[84:85], v[132:133]
	v_pk_mul_f32 v[86:87], v[86:87], v[134:135]
	v_pk_mul_f32 v[80:81], v[80:81], v[136:137]
	v_pk_mul_f32 v[82:83], v[82:83], v[138:139]
	v_lshlrev_b32_e32 v132, 16, v204
	v_and_b32_e32 v133, 0xffff0000, v204
	v_lshlrev_b32_e32 v134, 16, v205
	v_and_b32_e32 v135, 0xffff0000, v205
	v_lshlrev_b32_e32 v136, 16, v206
	v_and_b32_e32 v137, 0xffff0000, v206
	v_lshlrev_b32_e32 v138, 16, v207
	v_and_b32_e32 v139, 0xffff0000, v207
	v_pk_add_f32 v[84:85], v[84:85], v[132:133]
	v_pk_add_f32 v[86:87], v[86:87], v[134:135]
	v_pk_add_f32 v[80:81], v[80:81], v[136:137]
	v_pk_add_f32 v[82:83], v[82:83], v[138:139]
	v_cvt_pk_bf16_f32 v188, v84, v85
	v_cvt_pk_bf16_f32 v189, v86, v87
	v_cvt_pk_bf16_f32 v190, v80, v81
	v_cvt_pk_bf16_f32 v191, v82, v83
	global_store_dwordx4 v250, v[188:191], s[24:25] offset:256
	v_lshlrev_b32_e32 v132, 16, v192
	v_and_b32_e32 v133, 0xffff0000, v192
	v_lshlrev_b32_e32 v134, 16, v193
	v_and_b32_e32 v135, 0xffff0000, v193
	v_lshlrev_b32_e32 v136, 16, v194
	v_and_b32_e32 v137, 0xffff0000, v194
	v_lshlrev_b32_e32 v138, 16, v195
	v_and_b32_e32 v139, 0xffff0000, v195
	v_pk_mul_f32 v[76:77], v[76:77], v[132:133]
	v_pk_mul_f32 v[78:79], v[78:79], v[134:135]
	v_pk_mul_f32 v[72:73], v[72:73], v[136:137]
	v_pk_mul_f32 v[74:75], v[74:75], v[138:139]
	v_lshlrev_b32_e32 v132, 16, v208
	v_and_b32_e32 v133, 0xffff0000, v208
	v_lshlrev_b32_e32 v134, 16, v209
	v_and_b32_e32 v135, 0xffff0000, v209
	v_lshlrev_b32_e32 v136, 16, v210
	v_and_b32_e32 v137, 0xffff0000, v210
	v_lshlrev_b32_e32 v138, 16, v211
	v_and_b32_e32 v139, 0xffff0000, v211
	v_pk_add_f32 v[76:77], v[76:77], v[132:133]
	v_pk_add_f32 v[78:79], v[78:79], v[134:135]
	v_pk_add_f32 v[72:73], v[72:73], v[136:137]
	v_pk_add_f32 v[74:75], v[74:75], v[138:139]
	v_cvt_pk_bf16_f32 v192, v76, v77
	v_cvt_pk_bf16_f32 v193, v78, v79
	v_cvt_pk_bf16_f32 v194, v72, v73
	v_cvt_pk_bf16_f32 v195, v74, v75
	v_add_u32_e32 v250, 0x8000, v250
	global_store_dwordx4 v250, v[192:195], s[24:25]
	v_lshlrev_b32_e32 v132, 16, v196
	v_and_b32_e32 v133, 0xffff0000, v196
	v_lshlrev_b32_e32 v134, 16, v197
	v_and_b32_e32 v135, 0xffff0000, v197
	v_lshlrev_b32_e32 v136, 16, v198
	v_and_b32_e32 v137, 0xffff0000, v198
	v_lshlrev_b32_e32 v138, 16, v199
	v_and_b32_e32 v139, 0xffff0000, v199
	v_pk_mul_f32 v[68:69], v[68:69], v[132:133]
	v_pk_mul_f32 v[70:71], v[70:71], v[134:135]
	v_pk_mul_f32 v[64:65], v[64:65], v[136:137]
	v_pk_mul_f32 v[66:67], v[66:67], v[138:139]
	v_lshlrev_b32_e32 v132, 16, v212
	v_and_b32_e32 v133, 0xffff0000, v212
	v_lshlrev_b32_e32 v134, 16, v213
	v_and_b32_e32 v135, 0xffff0000, v213
	v_lshlrev_b32_e32 v136, 16, v214
	v_and_b32_e32 v137, 0xffff0000, v214
	v_lshlrev_b32_e32 v138, 16, v215
	v_and_b32_e32 v139, 0xffff0000, v215
	v_pk_add_f32 v[68:69], v[68:69], v[132:133]
	v_pk_add_f32 v[70:71], v[70:71], v[134:135]
	v_pk_add_f32 v[64:65], v[64:65], v[136:137]
	v_pk_add_f32 v[66:67], v[66:67], v[138:139]
	v_cvt_pk_bf16_f32 v196, v68, v69
	v_cvt_pk_bf16_f32 v197, v70, v71
	v_cvt_pk_bf16_f32 v198, v64, v65
	v_cvt_pk_bf16_f32 v199, v66, v67
	global_store_dwordx4 v250, v[196:199], s[24:25] offset:256
	s_waitcnt vmcnt(16)
; __device__ __forceinline__ unsigned cvt_pk_bf16(float lo, float hi) { unsigned r; asm volatile("v_cvt_pk_bf16_f32 %0, %1, %2" : "=v"(r) : "v"(lo), "v"(hi)); return r; }
; __device__ __forceinline__ float bf_lo(unsigned w) { return __uint_as_float(w << 16); }
; __device__ __forceinline__ float bf_hi(unsigned w) { return __uint_as_float(w & 0xffff0000u); }
;     __device__ __forceinline__ void operator()(const f32x4 (&acc)[2][2][4][2], const Unit& u, int wr, int wc, int fr, int fq) const {
;     ...
;                     const u32x4 gw = *(const u32x4*)(proj + (size_t)6 * 512 * M_ROWS + row * 2048 + goff + col);
;                     const f32x4 g0 = (f32x4){bf_lo(gw.x), bf_hi(gw.x), bf_lo(gw.y), bf_hi(gw.y)}, g1 = (f32x4){bf_lo(gw.z), bf_hi(gw.z), bf_lo(gw.w), bf_hi(gw.w)};
;                     f32x4 v0 = acc[ai][bj][m][0] * g0, v1 = acc[ai][bj][m][1] * g1; bf16_t* mp = merged + row * 1024 + col;
;                     if (second) { const u32x4 tw = *(const u32x4*)mp;
;                         v0 = v0 + (f32x4){bf_lo(tw.x), bf_hi(tw.x), bf_lo(tw.y), bf_hi(tw.y)}; v1 = v1 + (f32x4){bf_lo(tw.z), bf_hi(tw.z), bf_lo(tw.w), bf_hi(tw.w)}; }
;                     u32x4 w; w.x = cvt_pk_bf16(v0[0], v0[1]); w.y = cvt_pk_bf16(v0[2], v0[3]); w.z = cvt_pk_bf16(v1[0], v1[1]); w.w = cvt_pk_bf16(v1[2], v1[3]);
;                     *(u32x4*)mp = w; }
	v_lshlrev_b32_e32 v132, 16, v216
	v_and_b32_e32 v133, 0xffff0000, v216
	v_lshlrev_b32_e32 v134, 16, v217
	v_and_b32_e32 v135, 0xffff0000, v217
	v_lshlrev_b32_e32 v136, 16, v218
	v_and_b32_e32 v137, 0xffff0000, v218
	v_lshlrev_b32_e32 v138, 16, v219
	v_and_b32_e32 v139, 0xffff0000, v219
	v_pk_mul_f32 v[60:61], v[60:61], v[132:133]
	v_pk_mul_f32 v[62:63], v[62:63], v[134:135]
	v_pk_mul_f32 v[56:57], v[56:57], v[136:137]
	v_pk_mul_f32 v[58:59], v[58:59], v[138:139]
	v_lshlrev_b32_e32 v132, 16, v232
	v_and_b32_e32 v133, 0xffff0000, v232
	v_lshlrev_b32_e32 v134, 16, v233
	v_and_b32_e32 v135, 0xffff0000, v233
	v_lshlrev_b32_e32 v136, 16, v234
	v_and_b32_e32 v137, 0xffff0000, v234
	v_lshlrev_b32_e32 v138, 16, v235
	v_and_b32_e32 v139, 0xffff0000, v235
	v_pk_add_f32 v[60:61], v[60:61], v[132:133]
	v_pk_add_f32 v[62:63], v[62:63], v[134:135]
	v_pk_add_f32 v[56:57], v[56:57], v[136:137]
	v_pk_add_f32 v[58:59], v[58:59], v[138:139]
	v_cvt_pk_bf16_f32 v216, v60, v61
	v_cvt_pk_bf16_f32 v217, v62, v63
	v_cvt_pk_bf16_f32 v218, v56, v57
	v_cvt_pk_bf16_f32 v219, v58, v59
	v_add_u32_e32 v250, 0x28000, v250
	global_store_dwordx4 v250, v[216:219], s[24:25]
	v_lshlrev_b32_e32 v132, 16, v220
	v_and_b32_e32 v133, 0xffff0000, v220
	v_lshlrev_b32_e32 v134, 16, v221
	v_and_b32_e32 v135, 0xffff0000, v221
	v_lshlrev_b32_e32 v136, 16, v222
	v_and_b32_e32 v137, 0xffff0000, v222
	v_lshlrev_b32_e32 v138, 16, v223
	v_and_b32_e32 v139, 0xffff0000, v223
	v_pk_mul_f32 v[52:53], v[52:53], v[132:133]
	v_pk_mul_f32 v[54:55], v[54:55], v[134:135]
	v_pk_mul_f32 v[48:49], v[48:49], v[136:137]
	v_pk_mul_f32 v[50:51], v[50:51], v[138:139]
	v_lshlrev_b32_e32 v132, 16, v236
	v_and_b32_e32 v133, 0xffff0000, v236
	v_lshlrev_b32_e32 v134, 16, v237
	v_and_b32_e32 v135, 0xffff0000, v237
	v_lshlrev_b32_e32 v136, 16, v238
	v_and_b32_e32 v137, 0xffff0000, v238
	v_lshlrev_b32_e32 v138, 16, v239
	v_and_b32_e32 v139, 0xffff0000, v239
	v_pk_add_f32 v[52:53], v[52:53], v[132:133]
	v_pk_add_f32 v[54:55], v[54:55], v[134:135]
	v_pk_add_f32 v[48:49], v[48:49], v[136:137]
	v_pk_add_f32 v[50:51], v[50:51], v[138:139]
	v_cvt_pk_bf16_f32 v220, v52, v53
	v_cvt_pk_bf16_f32 v221, v54, v55
	v_cvt_pk_bf16_f32 v222, v48, v49
	v_cvt_pk_bf16_f32 v223, v50, v51
	global_store_dwordx4 v250, v[220:223], s[24:25] offset:256
	v_lshlrev_b32_e32 v132, 16, v224
	v_and_b32_e32 v133, 0xffff0000, v224
	v_lshlrev_b32_e32 v134, 16, v225
	v_and_b32_e32 v135, 0xffff0000, v225
	v_lshlrev_b32_e32 v136, 16, v226
	v_and_b32_e32 v137, 0xffff0000, v226
	v_lshlrev_b32_e32 v138, 16, v227
	v_and_b32_e32 v139, 0xffff0000, v227
	v_pk_mul_f32 v[44:45], v[44:45], v[132:133]
	v_pk_mul_f32 v[46:47], v[46:47], v[134:135]
	v_pk_mul_f32 v[40:41], v[40:41], v[136:137]
	v_pk_mul_f32 v[42:43], v[42:43], v[138:139]
	v_lshlrev_b32_e32 v132, 16, v240
	v_and_b32_e32 v133, 0xffff0000, v240
	v_lshlrev_b32_e32 v134, 16, v241
	v_and_b32_e32 v135, 0xffff0000, v241
	v_lshlrev_b32_e32 v136, 16, v242
	v_and_b32_e32 v137, 0xffff0000, v242
	v_lshlrev_b32_e32 v138, 16, v243
	v_and_b32_e32 v139, 0xffff0000, v243
	v_pk_add_f32 v[44:45], v[44:45], v[132:133]
	v_pk_add_f32 v[46:47], v[46:47], v[134:135]
	v_pk_add_f32 v[40:41], v[40:41], v[136:137]
	v_pk_add_f32 v[42:43], v[42:43], v[138:139]
	v_cvt_pk_bf16_f32 v224, v44, v45
	v_cvt_pk_bf16_f32 v225, v46, v47
	v_cvt_pk_bf16_f32 v226, v40, v41
	v_cvt_pk_bf16_f32 v227, v42, v43
	v_add_u32_e32 v250, 0x8000, v250
	global_store_dwordx4 v250, v[224:227], s[24:25]
	v_lshlrev_b32_e32 v132, 16, v228
	v_and_b32_e32 v133, 0xffff0000, v228
	v_lshlrev_b32_e32 v134, 16, v229
	v_and_b32_e32 v135, 0xffff0000, v229
	v_lshlrev_b32_e32 v136, 16, v230
	v_and_b32_e32 v137, 0xffff0000, v230
	v_lshlrev_b32_e32 v138, 16, v231
	v_and_b32_e32 v139, 0xffff0000, v231
	v_pk_mul_f32 v[36:37], v[36:37], v[132:133]
	v_pk_mul_f32 v[38:39], v[38:39], v[134:135]
	v_pk_mul_f32 v[32:33], v[32:33], v[136:137]
	v_pk_mul_f32 v[34:35], v[34:35], v[138:139]
	v_lshlrev_b32_e32 v132, 16, v244
	v_and_b32_e32 v133, 0xffff0000, v244
	v_lshlrev_b32_e32 v134, 16, v245
	v_and_b32_e32 v135, 0xffff0000, v245
	v_lshlrev_b32_e32 v136, 16, v246
	v_and_b32_e32 v137, 0xffff0000, v246
	v_lshlrev_b32_e32 v138, 16, v247
	v_and_b32_e32 v139, 0xffff0000, v247
	v_pk_add_f32 v[36:37], v[36:37], v[132:133]
	v_pk_add_f32 v[38:39], v[38:39], v[134:135]
	v_pk_add_f32 v[32:33], v[32:33], v[136:137]
	v_pk_add_f32 v[34:35], v[34:35], v[138:139]
	v_cvt_pk_bf16_f32 v228, v36, v37
	v_cvt_pk_bf16_f32 v229, v38, v39
	v_cvt_pk_bf16_f32 v230, v32, v33
	v_cvt_pk_bf16_f32 v231, v34, v35
	global_store_dwordx4 v250, v[228:231], s[24:25] offset:256
	s_waitcnt vmcnt(8)
; __device__ __forceinline__ unsigned cvt_pk_bf16(float lo, float hi) { unsigned r; asm volatile("v_cvt_pk_bf16_f32 %0, %1, %2" : "=v"(r) : "v"(lo), "v"(hi)); return r; }
; __device__ __forceinline__ float bf_lo(unsigned w) { return __uint_as_float(w << 16); }
; __device__ __forceinline__ float bf_hi(unsigned w) { return __uint_as_float(w & 0xffff0000u); }
; #define PG8_BAR __builtin_amdgcn_s_barrier()
;     __device__ __forceinline__ void operator()(const f32x4 (&acc)[2][2][4][2], const Unit& u, int wr, int wc, int fr, int fq) const {
;     ...
;                     const u32x4 gw = *(const u32x4*)(proj + (size_t)6 * 512 * M_ROWS + row * 2048 + goff + col);
;                     const f32x4 g0 = (f32x4){bf_lo(gw.x), bf_hi(gw.x), bf_lo(gw.y), bf_hi(gw.y)}, g1 = (f32x4){bf_lo(gw.z), bf_hi(gw.z), bf_lo(gw.w), bf_hi(gw.w)};
;                     f32x4 v0 = acc[ai][bj][m][0] * g0, v1 = acc[ai][bj][m][1] * g1; bf16_t* mp = merged + row * 1024 + col;
;                     if (second) { const u32x4 tw = *(const u32x4*)mp;
;                         v0 = v0 + (f32x4){bf_lo(tw.x), bf_hi(tw.x), bf_lo(tw.y), bf_hi(tw.y)}; v1 = v1 + (f32x4){bf_lo(tw.z), bf_hi(tw.z), bf_lo(tw.w), bf_hi(tw.w)}; }
;                     u32x4 w; w.x = cvt_pk_bf16(v0[0], v0[1]); w.y = cvt_pk_bf16(v0[2], v0[3]); w.z = cvt_pk_bf16(v1[0], v1[1]); w.w = cvt_pk_bf16(v1[2], v1[3]);
;                     *(u32x4*)mp = w; }
; template <class Epi, class Sched, bool ALIGN_EPI = false, bool SP2 = false, bool F8 = false>
; __device__ __forceinline__ void gemm_phase(PG8_LAS unsigned char* lds, const Gemm g, const Sched& S, const Epi& E, const int wv) {
;     ...
;         if (!has_next) break;
; #pragma unroll
;         for (int a = 0; a < 2; ++a)
; #pragma unroll
;             for (int b = 0; b < 2; ++b)
; #pragma unroll
;                 for (int m = 0; m < 4; ++m)
; #pragma unroll
;                     for (int n = 0; n < 2; ++n) acc[a][b][m][n] = (f32x4){0.f, 0.f, 0.f, 0.f};
;         cur = nxt; cA = nA; cB = nB; ++ui;
;         if constexpr (ALIGN_EPI) { if (wr == 1) PG8_BAR; }
	v_lshlrev_b32_e32 v132, 16, v152
	v_and_b32_e32 v133, 0xffff0000, v152
	v_lshlrev_b32_e32 v134, 16, v153
	v_and_b32_e32 v135, 0xffff0000, v153
	v_lshlrev_b32_e32 v136, 16, v154
	v_and_b32_e32 v137, 0xffff0000, v154
	v_lshlrev_b32_e32 v138, 16, v155
	v_and_b32_e32 v139, 0xffff0000, v155
	v_pk_mul_f32 v[28:29], v[28:29], v[132:133]
	v_pk_mul_f32 v[30:31], v[30:31], v[134:135]
	v_pk_mul_f32 v[24:25], v[24:25], v[136:137]
	v_pk_mul_f32 v[26:27], v[26:27], v[138:139]
	v_lshlrev_b32_e32 v132, 16, v168
	v_and_b32_e32 v133, 0xffff0000, v168
	v_lshlrev_b32_e32 v134, 16, v169
	v_and_b32_e32 v135, 0xffff0000, v169
	v_lshlrev_b32_e32 v136, 16, v170
	v_and_b32_e32 v137, 0xffff0000, v170
	v_lshlrev_b32_e32 v138, 16, v171
	v_and_b32_e32 v139, 0xffff0000, v171
	v_pk_add_f32 v[28:29], v[28:29], v[132:133]
	v_pk_add_f32 v[30:31], v[30:31], v[134:135]
	v_pk_add_f32 v[24:25], v[24:25], v[136:137]
	v_pk_add_f32 v[26:27], v[26:27], v[138:139]
	v_cvt_pk_bf16_f32 v152, v28, v29
	v_cvt_pk_bf16_f32 v153, v30, v31
	v_cvt_pk_bf16_f32 v154, v24, v25
	v_cvt_pk_bf16_f32 v155, v26, v27
	v_add_u32_e32 v250, 0x8000, v250
	global_store_dwordx4 v250, v[152:155], s[24:25]
	v_lshlrev_b32_e32 v132, 16, v156
	v_and_b32_e32 v133, 0xffff0000, v156
	v_lshlrev_b32_e32 v134, 16, v157
	v_and_b32_e32 v135, 0xffff0000, v157
	v_lshlrev_b32_e32 v136, 16, v158
	v_and_b32_e32 v137, 0xffff0000, v158
	v_lshlrev_b32_e32 v138, 16, v159
	v_and_b32_e32 v139, 0xffff0000, v159
	v_pk_mul_f32 v[20:21], v[20:21], v[132:133]
	v_pk_mul_f32 v[22:23], v[22:23], v[134:135]
	v_pk_mul_f32 v[16:17], v[16:17], v[136:137]
	v_pk_mul_f32 v[18:19], v[18:19], v[138:139]
	v_lshlrev_b32_e32 v132, 16, v172
	v_and_b32_e32 v133, 0xffff0000, v172
	v_lshlrev_b32_e32 v134, 16, v173
	v_and_b32_e32 v135, 0xffff0000, v173
	v_lshlrev_b32_e32 v136, 16, v174
	v_and_b32_e32 v137, 0xffff0000, v174
	v_lshlrev_b32_e32 v138, 16, v175
	v_and_b32_e32 v139, 0xffff0000, v175
	v_pk_add_f32 v[20:21], v[20:21], v[132:133]
	v_pk_add_f32 v[22:23], v[22:23], v[134:135]
	v_pk_add_f32 v[16:17], v[16:17], v[136:137]
	v_pk_add_f32 v[18:19], v[18:19], v[138:139]
	v_cvt_pk_bf16_f32 v156, v20, v21
	v_cvt_pk_bf16_f32 v157, v22, v23
	v_cvt_pk_bf16_f32 v158, v16, v17
	v_cvt_pk_bf16_f32 v159, v18, v19
	global_store_dwordx4 v250, v[156:159], s[24:25] offset:256
	v_lshlrev_b32_e32 v132, 16, v160
	v_and_b32_e32 v133, 0xffff0000, v160
	v_lshlrev_b32_e32 v134, 16, v161
	v_and_b32_e32 v135, 0xffff0000, v161
	v_lshlrev_b32_e32 v136, 16, v162
	v_and_b32_e32 v137, 0xffff0000, v162
	v_lshlrev_b32_e32 v138, 16, v163
	v_and_b32_e32 v139, 0xffff0000, v163
	v_pk_mul_f32 v[12:13], v[12:13], v[132:133]
	v_pk_mul_f32 v[14:15], v[14:15], v[134:135]
	v_pk_mul_f32 v[8:9], v[8:9], v[136:137]
	v_pk_mul_f32 v[10:11], v[10:11], v[138:139]
	v_lshlrev_b32_e32 v132, 16, v176
	v_and_b32_e32 v133, 0xffff0000, v176
	v_lshlrev_b32_e32 v134, 16, v177
	v_and_b32_e32 v135, 0xffff0000, v177
	v_lshlrev_b32_e32 v136, 16, v178
	v_and_b32_e32 v137, 0xffff0000, v178
	v_lshlrev_b32_e32 v138, 16, v179
	v_and_b32_e32 v139, 0xffff0000, v179
	v_pk_add_f32 v[12:13], v[12:13], v[132:133]
	v_pk_add_f32 v[14:15], v[14:15], v[134:135]
	v_pk_add_f32 v[8:9], v[8:9], v[136:137]
	v_pk_add_f32 v[10:11], v[10:11], v[138:139]
	v_cvt_pk_bf16_f32 v160, v12, v13
	v_cvt_pk_bf16_f32 v161, v14, v15
	v_cvt_pk_bf16_f32 v162, v8, v9
	v_cvt_pk_bf16_f32 v163, v10, v11
	v_add_u32_e32 v250, 0x8000, v250
	global_store_dwordx4 v250, v[160:163], s[24:25]
	v_lshlrev_b32_e32 v132, 16, v164
	v_and_b32_e32 v133, 0xffff0000, v164
	v_lshlrev_b32_e32 v134, 16, v165
	v_and_b32_e32 v135, 0xffff0000, v165
	v_lshlrev_b32_e32 v136, 16, v166
	v_and_b32_e32 v137, 0xffff0000, v166
	v_lshlrev_b32_e32 v138, 16, v167
	v_and_b32_e32 v139, 0xffff0000, v167
	v_pk_mul_f32 v[4:5], v[4:5], v[132:133]
	v_pk_mul_f32 v[6:7], v[6:7], v[134:135]
	v_pk_mul_f32 v[0:1], v[0:1], v[136:137]
	v_pk_mul_f32 v[2:3], v[2:3], v[138:139]
	v_lshlrev_b32_e32 v132, 16, v180
	v_and_b32_e32 v133, 0xffff0000, v180
	v_lshlrev_b32_e32 v134, 16, v181
	v_and_b32_e32 v135, 0xffff0000, v181
	v_lshlrev_b32_e32 v136, 16, v182
	v_and_b32_e32 v137, 0xffff0000, v182
	v_lshlrev_b32_e32 v138, 16, v183
	v_and_b32_e32 v139, 0xffff0000, v183
	v_pk_add_f32 v[4:5], v[4:5], v[132:133]
	v_pk_add_f32 v[6:7], v[6:7], v[134:135]
	v_pk_add_f32 v[0:1], v[0:1], v[136:137]
	v_pk_add_f32 v[2:3], v[2:3], v[138:139]
	v_cvt_pk_bf16_f32 v164, v4, v5
	v_cvt_pk_bf16_f32 v165, v6, v7
	v_cvt_pk_bf16_f32 v166, v0, v1
	v_cvt_pk_bf16_f32 v167, v2, v3
	global_store_dwordx4 v250, v[164:167], s[24:25] offset:256
.Lmrg_l0_done:
	s_andn2_b64 vcc, exec, s[4:5]
	s_mov_b64 s[4:5], -1
	s_cbranch_vccnz .LBB0_662
	s_andn2_b64 vcc, exec, s[20:21]
	s_cbranch_vccnz .LBB0_661
	s_barrier
	s_branch .LBB0_661

; __device__ __forceinline__ unsigned cvt_pk_bf16(float lo, float hi) { unsigned r; asm volatile("v_cvt_pk_bf16_f32 %0, %1, %2" : "=v"(r) : "v"(lo), "v"(hi)); return r; }
; __device__ __forceinline__ float sigm(float x) { return __builtin_amdgcn_rcpf(1.f + __builtin_amdgcn_exp2f(-1.4426950408889634f * x)); }
;     __device__ __forceinline__ void operator()(const f32x4 (&acc)[2][2][4][2], const Unit& u, int wr, int wc, int fr, int fq) const {
;         const int pn = u.pn; const float sc = (pn < 2 || (pn >= 6 && pn < 8)) ? qscale : 1.f; const bool gate = pn >= 12;
;         const int row0 = u.pm * BM + wr * 64 + fr;
;         const int seg = pn >> 1;
; #pragma unroll
;         for (int ai = 0; ai < 2; ++ai)
; #pragma unroll
;             for (int m = 0; m < 4; ++m) { const size_t row = (size_t)(row0 + ai * HALF + m * 16);
; #pragma unroll
;                 for (int bj = 0; bj < 2; ++bj) { f32x4 v0 = acc[ai][bj][m][0], v1 = acc[ai][bj][m][1];
;                     if (gate) { v0 = (f32x4){sigm(v0[0]), sigm(v0[1]), sigm(v0[2]), sigm(v0[3])}; v1 = (f32x4){sigm(v1[0]), sigm(v1[1]), sigm(v1[2]), sigm(v1[3])}; }
;                     else { v0 = v0 * sc; v1 = v1 * sc; }
;                     u32x4 w; w.x = cvt_pk_bf16(v0[0], v0[1]); w.y = cvt_pk_bf16(v0[2], v0[3]); w.z = cvt_pk_bf16(v1[0], v1[1]); w.w = cvt_pk_bf16(v1[2], v1[3]);
;                     const int g64 = 4 * (pn & 1) + 2 * bj + (wc >> 1), cin = 32 * (wc & 1) + 8 * fq;
;                     bf16_t* dst;
;                     if (gate) dst = O + (size_t)6 * 512 * M_ROWS + row * 2048 + (pn - 12) * BM + bj * HALF + wc * 32 + 8 * fq;
;                     else if (seg == 5) dst = O + (size_t)5 * 512 * M_ROWS + ((size_t)(g64 >> 1) * M_ROWS + row) * 128 + 64 * (g64 & 1) + cin;
;                     else dst = O + (size_t)seg * 512 * M_ROWS + ((size_t)g64 * M_ROWS + row) * 64 + cin;
;                     *(u32x4*)dst = w; } }
.LBB0_1142:
	s_cmp_lt_i32 s63, 4
	s_cbranch_scc1 .Lproj_l1_old
	s_lshl_b32 s10, s26, 8
	v_mbcnt_lo_u32_b32 v128, -1, 0
	v_mbcnt_hi_u32_b32 v128, -1, v128
	s_add_i32 s10, s10, s71
	v_and_b32_e32 v129, 15, v128
	v_bfe_u32 v130, v128, 4, 2
	v_or_b32_e32 v129, s10, v129
	v_lshlrev_b32_e32 v130, 4, v130
	s_cmp_gt_i32 s63, 11
	s_cbranch_scc1 .Lproj_l1_G
	s_lshr_b32 s11, s63, 1
	s_lshl_b32 s12, s82, 1
	v_or_b32_e32 v130, s12, v130
	s_cmp_eq_u32 s11, 5
	s_cbranch_scc1 .Lproj_l1_V
	s_lshl_b32 s12, s11, 24
	s_and_b32 s13, s63, 1
	s_lshl_b32 s13, s13, 2
	s_or_b32 s13, s13, s79
	s_lshl_b32 s13, s13, 21
	s_add_i32 s12, s12, s13
	v_lshl_add_u32 v138, v129, 7, v130
	s_cmp_eq_u32 s11, 3
	s_cselect_b32 s13, 0x3e38aa3b, 1.0
	v_add_u32_e32 v138, s12, v138
	v_mov_b32_e32 v140, s13
	v_mov_b32_e32 v141, s13
	v_add_u32_e32 v139, 0x400000, v138
	v_pk_mul_f32 v[124:125], v[140:141], v[124:125]
	v_pk_mul_f32 v[126:127], v[140:141], v[126:127]
	v_pk_mul_f32 v[120:121], v[140:141], v[120:121]
	v_pk_mul_f32 v[122:123], v[140:141], v[122:123]
	v_cvt_pk_bf16_f32 v178, v124, v125
	v_cvt_pk_bf16_f32 v179, v126, v127
	v_cvt_pk_bf16_f32 v180, v120, v121
	v_cvt_pk_bf16_f32 v181, v122, v123
	global_store_dwordx4 v138, v[178:181], s[28:29]
	v_pk_mul_f32 v[116:117], v[140:141], v[116:117]
	v_pk_mul_f32 v[118:119], v[140:141], v[118:119]
	v_pk_mul_f32 v[108:109], v[140:141], v[108:109]
	v_pk_mul_f32 v[110:111], v[140:141], v[110:111]
	v_cvt_pk_bf16_f32 v182, v116, v117
	v_cvt_pk_bf16_f32 v183, v118, v119
	v_cvt_pk_bf16_f32 v184, v108, v109
	v_cvt_pk_bf16_f32 v185, v110, v111
	global_store_dwordx4 v139, v[182:185], s[28:29]
	v_add_u32_e32 v138, 0x800, v138
	v_add_u32_e32 v139, 0x800, v139
	v_pk_mul_f32 v[112:113], v[140:141], v[112:113]
	v_pk_mul_f32 v[114:115], v[140:141], v[114:115]
	v_pk_mul_f32 v[104:105], v[140:141], v[104:105]
	v_pk_mul_f32 v[106:107], v[140:141], v[106:107]
	v_cvt_pk_bf16_f32 v178, v112, v113
	v_cvt_pk_bf16_f32 v179, v114, v115
	v_cvt_pk_bf16_f32 v180, v104, v105
	v_cvt_pk_bf16_f32 v181, v106, v107
	global_store_dwordx4 v138, v[178:181], s[28:29]
	v_pk_mul_f32 v[100:101], v[140:141], v[100:101]
	v_pk_mul_f32 v[102:103], v[140:141], v[102:103]
	v_pk_mul_f32 v[92:93], v[140:141], v[92:93]
	v_pk_mul_f32 v[94:95], v[140:141], v[94:95]
	v_cvt_pk_bf16_f32 v182, v100, v101
	v_cvt_pk_bf16_f32 v183, v102, v103
	v_cvt_pk_bf16_f32 v184, v92, v93
	v_cvt_pk_bf16_f32 v185, v94, v95
	global_store_dwordx4 v139, v[182:185], s[28:29]
	v_add_u32_e32 v138, 0x800, v138
	v_add_u32_e32 v139, 0x800, v139
	v_pk_mul_f32 v[96:97], v[140:141], v[96:97]
	v_pk_mul_f32 v[98:99], v[140:141], v[98:99]
	v_pk_mul_f32 v[88:89], v[140:141], v[88:89]
	v_pk_mul_f32 v[90:91], v[140:141], v[90:91]
	v_cvt_pk_bf16_f32 v178, v96, v97
	v_cvt_pk_bf16_f32 v179, v98, v99
	v_cvt_pk_bf16_f32 v180, v88, v89
	v_cvt_pk_bf16_f32 v181, v90, v91
	global_store_dwordx4 v138, v[178:181], s[28:29]
	v_pk_mul_f32 v[84:85], v[140:141], v[84:85]
	v_pk_mul_f32 v[86:87], v[140:141], v[86:87]
	v_pk_mul_f32 v[76:77], v[140:141], v[76:77]
	v_pk_mul_f32 v[78:79], v[140:141], v[78:79]
	v_cvt_pk_bf16_f32 v182, v84, v85
	v_cvt_pk_bf16_f32 v183, v86, v87
	v_cvt_pk_bf16_f32 v184, v76, v77
	v_cvt_pk_bf16_f32 v185, v78, v79
	global_store_dwordx4 v139, v[182:185], s[28:29]
	v_add_u32_e32 v138, 0x800, v138
	v_add_u32_e32 v139, 0x800, v139
	v_pk_mul_f32 v[80:81], v[140:141], v[80:81]
	v_pk_mul_f32 v[82:83], v[140:141], v[82:83]
	v_pk_mul_f32 v[72:73], v[140:141], v[72:73]
	v_pk_mul_f32 v[74:75], v[140:141], v[74:75]
	v_cvt_pk_bf16_f32 v178, v80, v81
	v_cvt_pk_bf16_f32 v179, v82, v83
	v_cvt_pk_bf16_f32 v180, v72, v73
	v_cvt_pk_bf16_f32 v181, v74, v75
	global_store_dwordx4 v138, v[178:181], s[28:29]
	v_pk_mul_f32 v[68:69], v[140:141], v[68:69]
	v_pk_mul_f32 v[70:71], v[140:141], v[70:71]
	v_pk_mul_f32 v[64:65], v[140:141], v[64:65]
	v_pk_mul_f32 v[66:67], v[140:141], v[66:67]
	v_cvt_pk_bf16_f32 v182, v68, v69
	v_cvt_pk_bf16_f32 v183, v70, v71
	v_cvt_pk_bf16_f32 v184, v64, v65
	v_cvt_pk_bf16_f32 v185, v66, v67
	global_store_dwordx4 v139, v[182:185], s[28:29]
	v_add_u32_e32 v138, 0x2800, v138
	v_add_u32_e32 v139, 0x2800, v139
	v_pk_mul_f32 v[60:61], v[140:141], v[60:61]
	v_pk_mul_f32 v[62:63], v[140:141], v[62:63]
	v_pk_mul_f32 v[56:57], v[140:141], v[56:57]
	v_pk_mul_f32 v[58:59], v[140:141], v[58:59]
	v_cvt_pk_bf16_f32 v178, v60, v61
	v_cvt_pk_bf16_f32 v179, v62, v63
	v_cvt_pk_bf16_f32 v180, v56, v57
	v_cvt_pk_bf16_f32 v181, v58, v59
	global_store_dwordx4 v138, v[178:181], s[28:29]
	v_pk_mul_f32 v[52:53], v[140:141], v[52:53]
	v_pk_mul_f32 v[54:55], v[140:141], v[54:55]
	v_pk_mul_f32 v[44:45], v[140:141], v[44:45]
	v_pk_mul_f32 v[46:47], v[140:141], v[46:47]
	v_cvt_pk_bf16_f32 v182, v52, v53
	v_cvt_pk_bf16_f32 v183, v54, v55
	v_cvt_pk_bf16_f32 v184, v44, v45
	v_cvt_pk_bf16_f32 v185, v46, v47
	global_store_dwordx4 v139, v[182:185], s[28:29]
	v_add_u32_e32 v138, 0x800, v138
	v_add_u32_e32 v139, 0x800, v139
	v_pk_mul_f32 v[48:49], v[140:141], v[48:49]
	v_pk_mul_f32 v[50:51], v[140:141], v[50:51]
	v_pk_mul_f32 v[40:41], v[140:141], v[40:41]
	v_pk_mul_f32 v[42:43], v[140:141], v[42:43]
	v_cvt_pk_bf16_f32 v178, v48, v49
	v_cvt_pk_bf16_f32 v179, v50, v51
	v_cvt_pk_bf16_f32 v180, v40, v41
	v_cvt_pk_bf16_f32 v181, v42, v43
	global_store_dwordx4 v138, v[178:181], s[28:29]
	v_pk_mul_f32 v[36:37], v[140:141], v[36:37]
	v_pk_mul_f32 v[38:39], v[140:141], v[38:39]
	v_pk_mul_f32 v[28:29], v[140:141], v[28:29]
	v_pk_mul_f32 v[30:31], v[140:141], v[30:31]
	v_cvt_pk_bf16_f32 v182, v36, v37
	v_cvt_pk_bf16_f32 v183, v38, v39
	v_cvt_pk_bf16_f32 v184, v28, v29
	v_cvt_pk_bf16_f32 v185, v30, v31
	global_store_dwordx4 v139, v[182:185], s[28:29]
; __device__ __forceinline__ unsigned cvt_pk_bf16(float lo, float hi) { unsigned r; asm volatile("v_cvt_pk_bf16_f32 %0, %1, %2" : "=v"(r) : "v"(lo), "v"(hi)); return r; }
; __device__ __forceinline__ float sigm(float x) { return __builtin_amdgcn_rcpf(1.f + __builtin_amdgcn_exp2f(-1.4426950408889634f * x)); }
;     __device__ __forceinline__ void operator()(const f32x4 (&acc)[2][2][4][2], const Unit& u, int wr, int wc, int fr, int fq) const {
;         const int pn = u.pn; const float sc = (pn < 2 || (pn >= 6 && pn < 8)) ? qscale : 1.f; const bool gate = pn >= 12;
;         const int row0 = u.pm * BM + wr * 64 + fr;
;         const int seg = pn >> 1;
; #pragma unroll
;         for (int ai = 0; ai < 2; ++ai)
; #pragma unroll
;             for (int m = 0; m < 4; ++m) { const size_t row = (size_t)(row0 + ai * HALF + m * 16);
; #pragma unroll
;                 for (int bj = 0; bj < 2; ++bj) { f32x4 v0 = acc[ai][bj][m][0], v1 = acc[ai][bj][m][1];
;                     if (gate) { v0 = (f32x4){sigm(v0[0]), sigm(v0[1]), sigm(v0[2]), sigm(v0[3])}; v1 = (f32x4){sigm(v1[0]), sigm(v1[1]), sigm(v1[2]), sigm(v1[3])}; }
;                     else { v0 = v0 * sc; v1 = v1 * sc; }
;                     u32x4 w; w.x = cvt_pk_bf16(v0[0], v0[1]); w.y = cvt_pk_bf16(v0[2], v0[3]); w.z = cvt_pk_bf16(v1[0], v1[1]); w.w = cvt_pk_bf16(v1[2], v1[3]);
;                     const int g64 = 4 * (pn & 1) + 2 * bj + (wc >> 1), cin = 32 * (wc & 1) + 8 * fq;
;                     bf16_t* dst;
;                     if (gate) dst = O + (size_t)6 * 512 * M_ROWS + row * 2048 + (pn - 12) * BM + bj * HALF + wc * 32 + 8 * fq;
;                     else if (seg == 5) dst = O + (size_t)5 * 512 * M_ROWS + ((size_t)(g64 >> 1) * M_ROWS + row) * 128 + 64 * (g64 & 1) + cin;
;                     else dst = O + (size_t)seg * 512 * M_ROWS + ((size_t)g64 * M_ROWS + row) * 64 + cin;
;                     *(u32x4*)dst = w; } }
	v_add_u32_e32 v138, 0x800, v138
	v_add_u32_e32 v139, 0x800, v139
	v_pk_mul_f32 v[32:33], v[140:141], v[32:33]
	v_pk_mul_f32 v[34:35], v[140:141], v[34:35]
	v_pk_mul_f32 v[24:25], v[140:141], v[24:25]
	v_pk_mul_f32 v[26:27], v[140:141], v[26:27]
	v_cvt_pk_bf16_f32 v178, v32, v33
	v_cvt_pk_bf16_f32 v179, v34, v35
	v_cvt_pk_bf16_f32 v180, v24, v25
	v_cvt_pk_bf16_f32 v181, v26, v27
	global_store_dwordx4 v138, v[178:181], s[28:29]
	v_pk_mul_f32 v[20:21], v[140:141], v[20:21]
	v_pk_mul_f32 v[22:23], v[140:141], v[22:23]
	v_pk_mul_f32 v[12:13], v[140:141], v[12:13]
	v_pk_mul_f32 v[14:15], v[140:141], v[14:15]
	v_cvt_pk_bf16_f32 v182, v20, v21
	v_cvt_pk_bf16_f32 v183, v22, v23
	v_cvt_pk_bf16_f32 v184, v12, v13
	v_cvt_pk_bf16_f32 v185, v14, v15
	global_store_dwordx4 v139, v[182:185], s[28:29]
	v_add_u32_e32 v138, 0x800, v138
	v_add_u32_e32 v139, 0x800, v139
	v_pk_mul_f32 v[16:17], v[140:141], v[16:17]
	v_pk_mul_f32 v[18:19], v[140:141], v[18:19]
	v_pk_mul_f32 v[8:9], v[140:141], v[8:9]
	v_pk_mul_f32 v[10:11], v[140:141], v[10:11]
	v_cvt_pk_bf16_f32 v178, v16, v17
	v_cvt_pk_bf16_f32 v179, v18, v19
	v_cvt_pk_bf16_f32 v180, v8, v9
	v_cvt_pk_bf16_f32 v181, v10, v11
	global_store_dwordx4 v138, v[178:181], s[28:29]
	v_pk_mul_f32 v[4:5], v[140:141], v[4:5]
	v_pk_mul_f32 v[6:7], v[140:141], v[6:7]
	v_pk_mul_f32 v[0:1], v[140:141], v[0:1]
	v_pk_mul_f32 v[2:3], v[140:141], v[2:3]
	v_cvt_pk_bf16_f32 v182, v4, v5
	v_cvt_pk_bf16_f32 v183, v6, v7
	v_cvt_pk_bf16_f32 v184, v0, v1
	v_cvt_pk_bf16_f32 v185, v2, v3
	global_store_dwordx4 v139, v[182:185], s[28:29]
	s_branch .LBB0_1346
.Lproj_l1_V:
	s_and_b32 s13, s63, 1
	s_lshl_b32 s13, s13, 23
	v_lshl_add_u32 v138, v129, 8, v130
	v_mov_b32_e32 v140, 1.0
	v_mov_b32_e32 v141, 1.0
	v_add_u32_e32 v138, s13, v138
	v_add_u32_e32 v139, 0x400000, v138
	v_pk_mul_f32 v[124:125], v[140:141], v[124:125]
	v_pk_mul_f32 v[126:127], v[140:141], v[126:127]
	v_pk_mul_f32 v[120:121], v[140:141], v[120:121]
	v_pk_mul_f32 v[122:123], v[140:141], v[122:123]
	v_cvt_pk_bf16_f32 v178, v124, v125
	v_cvt_pk_bf16_f32 v179, v126, v127
	v_cvt_pk_bf16_f32 v180, v120, v121
	v_cvt_pk_bf16_f32 v181, v122, v123
	global_store_dwordx4 v138, v[178:181], s[44:45]
	v_pk_mul_f32 v[116:117], v[140:141], v[116:117]
	v_pk_mul_f32 v[118:119], v[140:141], v[118:119]
	v_pk_mul_f32 v[108:109], v[140:141], v[108:109]
	v_pk_mul_f32 v[110:111], v[140:141], v[110:111]
	v_cvt_pk_bf16_f32 v182, v116, v117
	v_cvt_pk_bf16_f32 v183, v118, v119
	v_cvt_pk_bf16_f32 v184, v108, v109
	v_cvt_pk_bf16_f32 v185, v110, v111
	global_store_dwordx4 v139, v[182:185], s[44:45]
	v_add_u32_e32 v138, 0x1000, v138
	v_add_u32_e32 v139, 0x1000, v139
	v_pk_mul_f32 v[112:113], v[140:141], v[112:113]
	v_pk_mul_f32 v[114:115], v[140:141], v[114:115]
	v_pk_mul_f32 v[104:105], v[140:141], v[104:105]
	v_pk_mul_f32 v[106:107], v[140:141], v[106:107]
	v_cvt_pk_bf16_f32 v178, v112, v113
	v_cvt_pk_bf16_f32 v179, v114, v115
	v_cvt_pk_bf16_f32 v180, v104, v105
	v_cvt_pk_bf16_f32 v181, v106, v107
	global_store_dwordx4 v138, v[178:181], s[44:45]
	v_pk_mul_f32 v[100:101], v[140:141], v[100:101]
	v_pk_mul_f32 v[102:103], v[140:141], v[102:103]
	v_pk_mul_f32 v[92:93], v[140:141], v[92:93]
	v_pk_mul_f32 v[94:95], v[140:141], v[94:95]
	v_cvt_pk_bf16_f32 v182, v100, v101
	v_cvt_pk_bf16_f32 v183, v102, v103
	v_cvt_pk_bf16_f32 v184, v92, v93
	v_cvt_pk_bf16_f32 v185, v94, v95
	global_store_dwordx4 v139, v[182:185], s[44:45]
	v_add_u32_e32 v138, 0x1000, v138
	v_add_u32_e32 v139, 0x1000, v139
	v_pk_mul_f32 v[96:97], v[140:141], v[96:97]
	v_pk_mul_f32 v[98:99], v[140:141], v[98:99]
	v_pk_mul_f32 v[88:89], v[140:141], v[88:89]
	v_pk_mul_f32 v[90:91], v[140:141], v[90:91]
	v_cvt_pk_bf16_f32 v178, v96, v97
	v_cvt_pk_bf16_f32 v179, v98, v99
	v_cvt_pk_bf16_f32 v180, v88, v89
	v_cvt_pk_bf16_f32 v181, v90, v91
	global_store_dwordx4 v138, v[178:181], s[44:45]
	v_pk_mul_f32 v[84:85], v[140:141], v[84:85]
	v_pk_mul_f32 v[86:87], v[140:141], v[86:87]
	v_pk_mul_f32 v[76:77], v[140:141], v[76:77]
	v_pk_mul_f32 v[78:79], v[140:141], v[78:79]
	v_cvt_pk_bf16_f32 v182, v84, v85
	v_cvt_pk_bf16_f32 v183, v86, v87
	v_cvt_pk_bf16_f32 v184, v76, v77
	v_cvt_pk_bf16_f32 v185, v78, v79
	global_store_dwordx4 v139, v[182:185], s[44:45]
	v_add_u32_e32 v138, 0x1000, v138
	v_add_u32_e32 v139, 0x1000, v139
	v_pk_mul_f32 v[80:81], v[140:141], v[80:81]
	v_pk_mul_f32 v[82:83], v[140:141], v[82:83]
	v_pk_mul_f32 v[72:73], v[140:141], v[72:73]
	v_pk_mul_f32 v[74:75], v[140:141], v[74:75]
	v_cvt_pk_bf16_f32 v178, v80, v81
	v_cvt_pk_bf16_f32 v179, v82, v83
	v_cvt_pk_bf16_f32 v180, v72, v73
	v_cvt_pk_bf16_f32 v181, v74, v75
	global_store_dwordx4 v138, v[178:181], s[44:45]
	v_pk_mul_f32 v[68:69], v[140:141], v[68:69]
	v_pk_mul_f32 v[70:71], v[140:141], v[70:71]
	v_pk_mul_f32 v[64:65], v[140:141], v[64:65]
	v_pk_mul_f32 v[66:67], v[140:141], v[66:67]
	v_cvt_pk_bf16_f32 v182, v68, v69
	v_cvt_pk_bf16_f32 v183, v70, v71
	v_cvt_pk_bf16_f32 v184, v64, v65
	v_cvt_pk_bf16_f32 v185, v66, v67
	global_store_dwordx4 v139, v[182:185], s[44:45]
	v_add_u32_e32 v138, 0x5000, v138
	v_add_u32_e32 v139, 0x5000, v139
	v_pk_mul_f32 v[60:61], v[140:141], v[60:61]
	v_pk_mul_f32 v[62:63], v[140:141], v[62:63]
	v_pk_mul_f32 v[56:57], v[140:141], v[56:57]
	v_pk_mul_f32 v[58:59], v[140:141], v[58:59]
	v_cvt_pk_bf16_f32 v178, v60, v61
	v_cvt_pk_bf16_f32 v179, v62, v63
	v_cvt_pk_bf16_f32 v180, v56, v57
	v_cvt_pk_bf16_f32 v181, v58, v59
	global_store_dwordx4 v138, v[178:181], s[44:45]
	v_pk_mul_f32 v[52:53], v[140:141], v[52:53]
	v_pk_mul_f32 v[54:55], v[140:141], v[54:55]
	v_pk_mul_f32 v[44:45], v[140:141], v[44:45]
	v_pk_mul_f32 v[46:47], v[140:141], v[46:47]
	v_cvt_pk_bf16_f32 v182, v52, v53
; __device__ __forceinline__ unsigned cvt_pk_bf16(float lo, float hi) { unsigned r; asm volatile("v_cvt_pk_bf16_f32 %0, %1, %2" : "=v"(r) : "v"(lo), "v"(hi)); return r; }
; __device__ __forceinline__ float sigm(float x) { return __builtin_amdgcn_rcpf(1.f + __builtin_amdgcn_exp2f(-1.4426950408889634f * x)); }
;     __device__ __forceinline__ void operator()(const f32x4 (&acc)[2][2][4][2], const Unit& u, int wr, int wc, int fr, int fq) const {
;         const int pn = u.pn; const float sc = (pn < 2 || (pn >= 6 && pn < 8)) ? qscale : 1.f; const bool gate = pn >= 12;
;         const int row0 = u.pm * BM + wr * 64 + fr;
;         const int seg = pn >> 1;
; #pragma unroll
;         for (int ai = 0; ai < 2; ++ai)
; #pragma unroll
;             for (int m = 0; m < 4; ++m) { const size_t row = (size_t)(row0 + ai * HALF + m * 16);
; #pragma unroll
;                 for (int bj = 0; bj < 2; ++bj) { f32x4 v0 = acc[ai][bj][m][0], v1 = acc[ai][bj][m][1];
;                     if (gate) { v0 = (f32x4){sigm(v0[0]), sigm(v0[1]), sigm(v0[2]), sigm(v0[3])}; v1 = (f32x4){sigm(v1[0]), sigm(v1[1]), sigm(v1[2]), sigm(v1[3])}; }
;                     else { v0 = v0 * sc; v1 = v1 * sc; }
;                     u32x4 w; w.x = cvt_pk_bf16(v0[0], v0[1]); w.y = cvt_pk_bf16(v0[2], v0[3]); w.z = cvt_pk_bf16(v1[0], v1[1]); w.w = cvt_pk_bf16(v1[2], v1[3]);
;                     const int g64 = 4 * (pn & 1) + 2 * bj + (wc >> 1), cin = 32 * (wc & 1) + 8 * fq;
;                     bf16_t* dst;
;                     if (gate) dst = O + (size_t)6 * 512 * M_ROWS + row * 2048 + (pn - 12) * BM + bj * HALF + wc * 32 + 8 * fq;
;                     else if (seg == 5) dst = O + (size_t)5 * 512 * M_ROWS + ((size_t)(g64 >> 1) * M_ROWS + row) * 128 + 64 * (g64 & 1) + cin;
;                     else dst = O + (size_t)seg * 512 * M_ROWS + ((size_t)g64 * M_ROWS + row) * 64 + cin;
;                     *(u32x4*)dst = w; } }
	v_cvt_pk_bf16_f32 v183, v54, v55
	v_cvt_pk_bf16_f32 v184, v44, v45
	v_cvt_pk_bf16_f32 v185, v46, v47
	global_store_dwordx4 v139, v[182:185], s[44:45]
	v_add_u32_e32 v138, 0x1000, v138
	v_add_u32_e32 v139, 0x1000, v139
	v_pk_mul_f32 v[48:49], v[140:141], v[48:49]
	v_pk_mul_f32 v[50:51], v[140:141], v[50:51]
	v_pk_mul_f32 v[40:41], v[140:141], v[40:41]
	v_pk_mul_f32 v[42:43], v[140:141], v[42:43]
	v_cvt_pk_bf16_f32 v178, v48, v49
	v_cvt_pk_bf16_f32 v179, v50, v51
	v_cvt_pk_bf16_f32 v180, v40, v41
	v_cvt_pk_bf16_f32 v181, v42, v43
	global_store_dwordx4 v138, v[178:181], s[44:45]
	v_pk_mul_f32 v[36:37], v[140:141], v[36:37]
	v_pk_mul_f32 v[38:39], v[140:141], v[38:39]
	v_pk_mul_f32 v[28:29], v[140:141], v[28:29]
	v_pk_mul_f32 v[30:31], v[140:141], v[30:31]
	v_cvt_pk_bf16_f32 v182, v36, v37
	v_cvt_pk_bf16_f32 v183, v38, v39
	v_cvt_pk_bf16_f32 v184, v28, v29
	v_cvt_pk_bf16_f32 v185, v30, v31
	global_store_dwordx4 v139, v[182:185], s[44:45]
	v_add_u32_e32 v138, 0x1000, v138
	v_add_u32_e32 v139, 0x1000, v139
	v_pk_mul_f32 v[32:33], v[140:141], v[32:33]
	v_pk_mul_f32 v[34:35], v[140:141], v[34:35]
	v_pk_mul_f32 v[24:25], v[140:141], v[24:25]
	v_pk_mul_f32 v[26:27], v[140:141], v[26:27]
	v_cvt_pk_bf16_f32 v178, v32, v33
	v_cvt_pk_bf16_f32 v179, v34, v35
	v_cvt_pk_bf16_f32 v180, v24, v25
	v_cvt_pk_bf16_f32 v181, v26, v27
	global_store_dwordx4 v138, v[178:181], s[44:45]
	v_pk_mul_f32 v[20:21], v[140:141], v[20:21]
	v_pk_mul_f32 v[22:23], v[140:141], v[22:23]
	v_pk_mul_f32 v[12:13], v[140:141], v[12:13]
	v_pk_mul_f32 v[14:15], v[140:141], v[14:15]
	v_cvt_pk_bf16_f32 v182, v20, v21
	v_cvt_pk_bf16_f32 v183, v22, v23
	v_cvt_pk_bf16_f32 v184, v12, v13
	v_cvt_pk_bf16_f32 v185, v14, v15
	global_store_dwordx4 v139, v[182:185], s[44:45]
	v_add_u32_e32 v138, 0x1000, v138
	v_add_u32_e32 v139, 0x1000, v139
	v_pk_mul_f32 v[16:17], v[140:141], v[16:17]
	v_pk_mul_f32 v[18:19], v[140:141], v[18:19]
	v_pk_mul_f32 v[8:9], v[140:141], v[8:9]
	v_pk_mul_f32 v[10:11], v[140:141], v[10:11]
	v_cvt_pk_bf16_f32 v178, v16, v17
	v_cvt_pk_bf16_f32 v179, v18, v19
	v_cvt_pk_bf16_f32 v180, v8, v9
	v_cvt_pk_bf16_f32 v181, v10, v11
	global_store_dwordx4 v138, v[178:181], s[44:45]
	v_pk_mul_f32 v[4:5], v[140:141], v[4:5]
	v_pk_mul_f32 v[6:7], v[140:141], v[6:7]
	v_pk_mul_f32 v[0:1], v[140:141], v[0:1]
	v_pk_mul_f32 v[2:3], v[140:141], v[2:3]
	v_cvt_pk_bf16_f32 v182, v4, v5
	v_cvt_pk_bf16_f32 v183, v6, v7
	v_cvt_pk_bf16_f32 v184, v0, v1
	v_cvt_pk_bf16_f32 v185, v2, v3
	global_store_dwordx4 v139, v[182:185], s[44:45]
	s_branch .LBB0_1346
.Lproj_l1_G:
	s_add_i32 s11, s63, -12
	s_lshl_b32 s11, s11, 9
	s_lshl_b32 s12, s78, 1
	s_add_i32 s11, s11, s12
	v_lshl_add_u32 v138, v129, 12, v130
	v_mov_b32_e32 v142, 0xbfb8aa3b
	v_mov_b32_e32 v143, 0xbfb8aa3b
	v_add_u32_e32 v138, s11, v138
	v_mov_b32_e32 v144, 1.0
	v_mov_b32_e32 v145, 1.0
	v_pk_mul_f32 v[162:163], v[142:143], v[124:125]
	v_pk_mul_f32 v[164:165], v[142:143], v[126:127]
	v_pk_mul_f32 v[166:167], v[142:143], v[120:121]
	v_pk_mul_f32 v[168:169], v[142:143], v[122:123]
	v_exp_f32_e32 v162, v162
	v_exp_f32_e32 v163, v163
	v_exp_f32_e32 v164, v164
	v_exp_f32_e32 v165, v165
	v_exp_f32_e32 v166, v166
	v_exp_f32_e32 v167, v167
	v_exp_f32_e32 v168, v168
	v_exp_f32_e32 v169, v169
	v_pk_add_f32 v[162:163], v[144:145], v[162:163]
	v_pk_add_f32 v[164:165], v[144:145], v[164:165]
	v_pk_add_f32 v[166:167], v[144:145], v[166:167]
	v_pk_add_f32 v[168:169], v[144:145], v[168:169]
	v_rcp_f32_e32 v162, v162
	v_rcp_f32_e32 v163, v163
	v_rcp_f32_e32 v164, v164
	v_rcp_f32_e32 v165, v165
	v_rcp_f32_e32 v166, v166
	v_rcp_f32_e32 v167, v167
	v_rcp_f32_e32 v168, v168
	v_rcp_f32_e32 v169, v169
	v_cvt_pk_bf16_f32 v178, v162, v163
	v_cvt_pk_bf16_f32 v179, v164, v165
	v_cvt_pk_bf16_f32 v180, v166, v167
	v_cvt_pk_bf16_f32 v181, v168, v169
	global_store_dwordx4 v138, v[178:181], s[46:47]
	v_pk_mul_f32 v[170:171], v[142:143], v[116:117]
	v_pk_mul_f32 v[172:173], v[142:143], v[118:119]
	v_pk_mul_f32 v[174:175], v[142:143], v[108:109]
	v_pk_mul_f32 v[176:177], v[142:143], v[110:111]
	v_exp_f32_e32 v170, v170
	v_exp_f32_e32 v171, v171
	v_exp_f32_e32 v172, v172
	v_exp_f32_e32 v173, v173
	v_exp_f32_e32 v174, v174
	v_exp_f32_e32 v175, v175
	v_exp_f32_e32 v176, v176
	v_exp_f32_e32 v177, v177
	v_pk_add_f32 v[170:171], v[144:145], v[170:171]
	v_pk_add_f32 v[172:173], v[144:145], v[172:173]
	v_pk_add_f32 v[174:175], v[144:145], v[174:175]
	v_pk_add_f32 v[176:177], v[144:145], v[176:177]
	v_rcp_f32_e32 v170, v170
	v_rcp_f32_e32 v171, v171
	v_rcp_f32_e32 v172, v172
	v_rcp_f32_e32 v173, v173
	v_rcp_f32_e32 v174, v174
	v_rcp_f32_e32 v175, v175
	v_rcp_f32_e32 v176, v176
	v_rcp_f32_e32 v177, v177
	v_cvt_pk_bf16_f32 v182, v170, v171
	v_cvt_pk_bf16_f32 v183, v172, v173
	v_cvt_pk_bf16_f32 v184, v174, v175
	v_cvt_pk_bf16_f32 v185, v176, v177
	global_store_dwordx4 v138, v[182:185], s[46:47] offset:256
	v_add_u32_e32 v138, 0x10000, v138
	v_pk_mul_f32 v[162:163], v[142:143], v[112:113]
	v_pk_mul_f32 v[164:165], v[142:143], v[114:115]
	v_pk_mul_f32 v[166:167], v[142:143], v[104:105]
	v_pk_mul_f32 v[168:169], v[142:143], v[106:107]
	v_exp_f32_e32 v162, v162
	v_exp_f32_e32 v163, v163
	v_exp_f32_e32 v164, v164
	v_exp_f32_e32 v165, v165
	v_exp_f32_e32 v166, v166
	v_exp_f32_e32 v167, v167
	v_exp_f32_e32 v168, v168
	v_exp_f32_e32 v169, v169
	v_pk_add_f32 v[162:163], v[144:145], v[162:163]
	v_pk_add_f32 v[164:165], v[144:145], v[164:165]
	v_pk_add_f32 v[166:167], v[144:145], v[166:167]
	v_pk_add_f32 v[168:169], v[144:145], v[168:169]
	v_rcp_f32_e32 v162, v162
	v_rcp_f32_e32 v163, v163
	v_rcp_f32_e32 v164, v164
	v_rcp_f32_e32 v165, v165
	v_rcp_f32_e32 v166, v166
	v_rcp_f32_e32 v167, v167
; __device__ __forceinline__ unsigned cvt_pk_bf16(float lo, float hi) { unsigned r; asm volatile("v_cvt_pk_bf16_f32 %0, %1, %2" : "=v"(r) : "v"(lo), "v"(hi)); return r; }
; __device__ __forceinline__ float sigm(float x) { return __builtin_amdgcn_rcpf(1.f + __builtin_amdgcn_exp2f(-1.4426950408889634f * x)); }
;     __device__ __forceinline__ void operator()(const f32x4 (&acc)[2][2][4][2], const Unit& u, int wr, int wc, int fr, int fq) const {
;     ...
;                     if (gate) { v0 = (f32x4){sigm(v0[0]), sigm(v0[1]), sigm(v0[2]), sigm(v0[3])}; v1 = (f32x4){sigm(v1[0]), sigm(v1[1]), sigm(v1[2]), sigm(v1[3])}; }
;                     else { v0 = v0 * sc; v1 = v1 * sc; }
;                     u32x4 w; w.x = cvt_pk_bf16(v0[0], v0[1]); w.y = cvt_pk_bf16(v0[2], v0[3]); w.z = cvt_pk_bf16(v1[0], v1[1]); w.w = cvt_pk_bf16(v1[2], v1[3]);
;                     const int g64 = 4 * (pn & 1) + 2 * bj + (wc >> 1), cin = 32 * (wc & 1) + 8 * fq;
;                     bf16_t* dst;
;                     if (gate) dst = O + (size_t)6 * 512 * M_ROWS + row * 2048 + (pn - 12) * BM + bj * HALF + wc * 32 + 8 * fq;
	v_rcp_f32_e32 v168, v168
	v_rcp_f32_e32 v169, v169
	v_cvt_pk_bf16_f32 v178, v162, v163
	v_cvt_pk_bf16_f32 v179, v164, v165
	v_cvt_pk_bf16_f32 v180, v166, v167
	v_cvt_pk_bf16_f32 v181, v168, v169
	global_store_dwordx4 v138, v[178:181], s[46:47]
	v_pk_mul_f32 v[170:171], v[142:143], v[100:101]
	v_pk_mul_f32 v[172:173], v[142:143], v[102:103]
	v_pk_mul_f32 v[174:175], v[142:143], v[92:93]
	v_pk_mul_f32 v[176:177], v[142:143], v[94:95]
	v_exp_f32_e32 v170, v170
	v_exp_f32_e32 v171, v171
	v_exp_f32_e32 v172, v172
	v_exp_f32_e32 v173, v173
	v_exp_f32_e32 v174, v174
	v_exp_f32_e32 v175, v175
	v_exp_f32_e32 v176, v176
	v_exp_f32_e32 v177, v177
	v_pk_add_f32 v[170:171], v[144:145], v[170:171]
	v_pk_add_f32 v[172:173], v[144:145], v[172:173]
	v_pk_add_f32 v[174:175], v[144:145], v[174:175]
	v_pk_add_f32 v[176:177], v[144:145], v[176:177]
	v_rcp_f32_e32 v170, v170
	v_rcp_f32_e32 v171, v171
	v_rcp_f32_e32 v172, v172
	v_rcp_f32_e32 v173, v173
	v_rcp_f32_e32 v174, v174
	v_rcp_f32_e32 v175, v175
	v_rcp_f32_e32 v176, v176
	v_rcp_f32_e32 v177, v177
	v_cvt_pk_bf16_f32 v182, v170, v171
	v_cvt_pk_bf16_f32 v183, v172, v173
	v_cvt_pk_bf16_f32 v184, v174, v175
	v_cvt_pk_bf16_f32 v185, v176, v177
	global_store_dwordx4 v138, v[182:185], s[46:47] offset:256
	v_add_u32_e32 v138, 0x10000, v138
	v_pk_mul_f32 v[162:163], v[142:143], v[96:97]
	v_pk_mul_f32 v[164:165], v[142:143], v[98:99]
	v_pk_mul_f32 v[166:167], v[142:143], v[88:89]
	v_pk_mul_f32 v[168:169], v[142:143], v[90:91]
	v_exp_f32_e32 v162, v162
	v_exp_f32_e32 v163, v163
	v_exp_f32_e32 v164, v164
	v_exp_f32_e32 v165, v165
	v_exp_f32_e32 v166, v166
	v_exp_f32_e32 v167, v167
	v_exp_f32_e32 v168, v168
	v_exp_f32_e32 v169, v169
	v_pk_add_f32 v[162:163], v[144:145], v[162:163]
	v_pk_add_f32 v[164:165], v[144:145], v[164:165]
	v_pk_add_f32 v[166:167], v[144:145], v[166:167]
	v_pk_add_f32 v[168:169], v[144:145], v[168:169]
	v_rcp_f32_e32 v162, v162
	v_rcp_f32_e32 v163, v163
	v_rcp_f32_e32 v164, v164
	v_rcp_f32_e32 v165, v165
	v_rcp_f32_e32 v166, v166
	v_rcp_f32_e32 v167, v167
	v_rcp_f32_e32 v168, v168
	v_rcp_f32_e32 v169, v169
	v_cvt_pk_bf16_f32 v178, v162, v163
	v_cvt_pk_bf16_f32 v179, v164, v165
	v_cvt_pk_bf16_f32 v180, v166, v167
	v_cvt_pk_bf16_f32 v181, v168, v169
	global_store_dwordx4 v138, v[178:181], s[46:47]
	v_pk_mul_f32 v[170:171], v[142:143], v[84:85]
	v_pk_mul_f32 v[172:173], v[142:143], v[86:87]
	v_pk_mul_f32 v[174:175], v[142:143], v[76:77]
	v_pk_mul_f32 v[176:177], v[142:143], v[78:79]
	v_exp_f32_e32 v170, v170
	v_exp_f32_e32 v171, v171
	v_exp_f32_e32 v172, v172
	v_exp_f32_e32 v173, v173
	v_exp_f32_e32 v174, v174
	v_exp_f32_e32 v175, v175
	v_exp_f32_e32 v176, v176
	v_exp_f32_e32 v177, v177
	v_pk_add_f32 v[170:171], v[144:145], v[170:171]
	v_pk_add_f32 v[172:173], v[144:145], v[172:173]
	v_pk_add_f32 v[174:175], v[144:145], v[174:175]
	v_pk_add_f32 v[176:177], v[144:145], v[176:177]
	v_rcp_f32_e32 v170, v170
	v_rcp_f32_e32 v171, v171
	v_rcp_f32_e32 v172, v172
	v_rcp_f32_e32 v173, v173
	v_rcp_f32_e32 v174, v174
	v_rcp_f32_e32 v175, v175
	v_rcp_f32_e32 v176, v176
	v_rcp_f32_e32 v177, v177
	v_cvt_pk_bf16_f32 v182, v170, v171
	v_cvt_pk_bf16_f32 v183, v172, v173
	v_cvt_pk_bf16_f32 v184, v174, v175
	v_cvt_pk_bf16_f32 v185, v176, v177
	global_store_dwordx4 v138, v[182:185], s[46:47] offset:256
	v_add_u32_e32 v138, 0x10000, v138
	v_pk_mul_f32 v[162:163], v[142:143], v[80:81]
	v_pk_mul_f32 v[164:165], v[142:143], v[82:83]
	v_pk_mul_f32 v[166:167], v[142:143], v[72:73]
	v_pk_mul_f32 v[168:169], v[142:143], v[74:75]
	v_exp_f32_e32 v162, v162
	v_exp_f32_e32 v163, v163
	v_exp_f32_e32 v164, v164
	v_exp_f32_e32 v165, v165
	v_exp_f32_e32 v166, v166
	v_exp_f32_e32 v167, v167
	v_exp_f32_e32 v168, v168
	v_exp_f32_e32 v169, v169
	v_pk_add_f32 v[162:163], v[144:145], v[162:163]
	v_pk_add_f32 v[164:165], v[144:145], v[164:165]
	v_pk_add_f32 v[166:167], v[144:145], v[166:167]
	v_pk_add_f32 v[168:169], v[144:145], v[168:169]
	v_rcp_f32_e32 v162, v162
	v_rcp_f32_e32 v163, v163
	v_rcp_f32_e32 v164, v164
	v_rcp_f32_e32 v165, v165
	v_rcp_f32_e32 v166, v166
	v_rcp_f32_e32 v167, v167
	v_rcp_f32_e32 v168, v168
	v_rcp_f32_e32 v169, v169
	v_cvt_pk_bf16_f32 v178, v162, v163
	v_cvt_pk_bf16_f32 v179, v164, v165
	v_cvt_pk_bf16_f32 v180, v166, v167
	v_cvt_pk_bf16_f32 v181, v168, v169
	global_store_dwordx4 v138, v[178:181], s[46:47]
	v_pk_mul_f32 v[170:171], v[142:143], v[68:69]
	v_pk_mul_f32 v[172:173], v[142:143], v[70:71]
	v_pk_mul_f32 v[174:175], v[142:143], v[64:65]
	v_pk_mul_f32 v[176:177], v[142:143], v[66:67]
	v_exp_f32_e32 v170, v170
	v_exp_f32_e32 v171, v171
	v_exp_f32_e32 v172, v172
	v_exp_f32_e32 v173, v173
	v_exp_f32_e32 v174, v174
	v_exp_f32_e32 v175, v175
	v_exp_f32_e32 v176, v176
	v_exp_f32_e32 v177, v177
	v_pk_add_f32 v[170:171], v[144:145], v[170:171]
	v_pk_add_f32 v[172:173], v[144:145], v[172:173]
	v_pk_add_f32 v[174:175], v[144:145], v[174:175]
	v_pk_add_f32 v[176:177], v[144:145], v[176:177]
	v_rcp_f32_e32 v170, v170
	v_rcp_f32_e32 v171, v171
	v_rcp_f32_e32 v172, v172
	v_rcp_f32_e32 v173, v173
	v_rcp_f32_e32 v174, v174
	v_rcp_f32_e32 v175, v175
	v_rcp_f32_e32 v176, v176
	v_rcp_f32_e32 v177, v177
	v_cvt_pk_bf16_f32 v182, v170, v171
	v_cvt_pk_bf16_f32 v183, v172, v173
	v_cvt_pk_bf16_f32 v184, v174, v175
	v_cvt_pk_bf16_f32 v185, v176, v177
	global_store_dwordx4 v138, v[182:185], s[46:47] offset:256
	v_add_u32_e32 v138, 0x50000, v138
	v_pk_mul_f32 v[162:163], v[142:143], v[60:61]
	v_pk_mul_f32 v[164:165], v[142:143], v[62:63]
	v_pk_mul_f32 v[166:167], v[142:143], v[56:57]
	v_pk_mul_f32 v[168:169], v[142:143], v[58:59]
	v_exp_f32_e32 v162, v162
	v_exp_f32_e32 v163, v163
	v_exp_f32_e32 v164, v164
	v_exp_f32_e32 v165, v165
; __device__ __forceinline__ unsigned cvt_pk_bf16(float lo, float hi) { unsigned r; asm volatile("v_cvt_pk_bf16_f32 %0, %1, %2" : "=v"(r) : "v"(lo), "v"(hi)); return r; }
; __device__ __forceinline__ float sigm(float x) { return __builtin_amdgcn_rcpf(1.f + __builtin_amdgcn_exp2f(-1.4426950408889634f * x)); }
;     __device__ __forceinline__ void operator()(const f32x4 (&acc)[2][2][4][2], const Unit& u, int wr, int wc, int fr, int fq) const {
;     ...
;                     if (gate) { v0 = (f32x4){sigm(v0[0]), sigm(v0[1]), sigm(v0[2]), sigm(v0[3])}; v1 = (f32x4){sigm(v1[0]), sigm(v1[1]), sigm(v1[2]), sigm(v1[3])}; }
;                     else { v0 = v0 * sc; v1 = v1 * sc; }
;                     u32x4 w; w.x = cvt_pk_bf16(v0[0], v0[1]); w.y = cvt_pk_bf16(v0[2], v0[3]); w.z = cvt_pk_bf16(v1[0], v1[1]); w.w = cvt_pk_bf16(v1[2], v1[3]);
;                     const int g64 = 4 * (pn & 1) + 2 * bj + (wc >> 1), cin = 32 * (wc & 1) + 8 * fq;
;                     bf16_t* dst;
;                     if (gate) dst = O + (size_t)6 * 512 * M_ROWS + row * 2048 + (pn - 12) * BM + bj * HALF + wc * 32 + 8 * fq;
	v_exp_f32_e32 v166, v166
	v_exp_f32_e32 v167, v167
	v_exp_f32_e32 v168, v168
	v_exp_f32_e32 v169, v169
	v_pk_add_f32 v[162:163], v[144:145], v[162:163]
	v_pk_add_f32 v[164:165], v[144:145], v[164:165]
	v_pk_add_f32 v[166:167], v[144:145], v[166:167]
	v_pk_add_f32 v[168:169], v[144:145], v[168:169]
	v_rcp_f32_e32 v162, v162
	v_rcp_f32_e32 v163, v163
	v_rcp_f32_e32 v164, v164
	v_rcp_f32_e32 v165, v165
	v_rcp_f32_e32 v166, v166
	v_rcp_f32_e32 v167, v167
	v_rcp_f32_e32 v168, v168
	v_rcp_f32_e32 v169, v169
	v_cvt_pk_bf16_f32 v178, v162, v163
	v_cvt_pk_bf16_f32 v179, v164, v165
	v_cvt_pk_bf16_f32 v180, v166, v167
	v_cvt_pk_bf16_f32 v181, v168, v169
	global_store_dwordx4 v138, v[178:181], s[46:47]
	v_pk_mul_f32 v[170:171], v[142:143], v[52:53]
	v_pk_mul_f32 v[172:173], v[142:143], v[54:55]
	v_pk_mul_f32 v[174:175], v[142:143], v[44:45]
	v_pk_mul_f32 v[176:177], v[142:143], v[46:47]
	v_exp_f32_e32 v170, v170
	v_exp_f32_e32 v171, v171
	v_exp_f32_e32 v172, v172
	v_exp_f32_e32 v173, v173
	v_exp_f32_e32 v174, v174
	v_exp_f32_e32 v175, v175
	v_exp_f32_e32 v176, v176
	v_exp_f32_e32 v177, v177
	v_pk_add_f32 v[170:171], v[144:145], v[170:171]
	v_pk_add_f32 v[172:173], v[144:145], v[172:173]
	v_pk_add_f32 v[174:175], v[144:145], v[174:175]
	v_pk_add_f32 v[176:177], v[144:145], v[176:177]
	v_rcp_f32_e32 v170, v170
	v_rcp_f32_e32 v171, v171
	v_rcp_f32_e32 v172, v172
	v_rcp_f32_e32 v173, v173
	v_rcp_f32_e32 v174, v174
	v_rcp_f32_e32 v175, v175
	v_rcp_f32_e32 v176, v176
	v_rcp_f32_e32 v177, v177
	v_cvt_pk_bf16_f32 v182, v170, v171
	v_cvt_pk_bf16_f32 v183, v172, v173
	v_cvt_pk_bf16_f32 v184, v174, v175
	v_cvt_pk_bf16_f32 v185, v176, v177
	global_store_dwordx4 v138, v[182:185], s[46:47] offset:256
	v_add_u32_e32 v138, 0x10000, v138
	v_pk_mul_f32 v[162:163], v[142:143], v[48:49]
	v_pk_mul_f32 v[164:165], v[142:143], v[50:51]
	v_pk_mul_f32 v[166:167], v[142:143], v[40:41]
	v_pk_mul_f32 v[168:169], v[142:143], v[42:43]
	v_exp_f32_e32 v162, v162
	v_exp_f32_e32 v163, v163
	v_exp_f32_e32 v164, v164
	v_exp_f32_e32 v165, v165
	v_exp_f32_e32 v166, v166
	v_exp_f32_e32 v167, v167
	v_exp_f32_e32 v168, v168
	v_exp_f32_e32 v169, v169
	v_pk_add_f32 v[162:163], v[144:145], v[162:163]
	v_pk_add_f32 v[164:165], v[144:145], v[164:165]
	v_pk_add_f32 v[166:167], v[144:145], v[166:167]
	v_pk_add_f32 v[168:169], v[144:145], v[168:169]
	v_rcp_f32_e32 v162, v162
	v_rcp_f32_e32 v163, v163
	v_rcp_f32_e32 v164, v164
	v_rcp_f32_e32 v165, v165
	v_rcp_f32_e32 v166, v166
	v_rcp_f32_e32 v167, v167
	v_rcp_f32_e32 v168, v168
	v_rcp_f32_e32 v169, v169
	v_cvt_pk_bf16_f32 v178, v162, v163
	v_cvt_pk_bf16_f32 v179, v164, v165
	v_cvt_pk_bf16_f32 v180, v166, v167
	v_cvt_pk_bf16_f32 v181, v168, v169
	global_store_dwordx4 v138, v[178:181], s[46:47]
	v_pk_mul_f32 v[170:171], v[142:143], v[36:37]
	v_pk_mul_f32 v[172:173], v[142:143], v[38:39]
	v_pk_mul_f32 v[174:175], v[142:143], v[28:29]
	v_pk_mul_f32 v[176:177], v[142:143], v[30:31]
	v_exp_f32_e32 v170, v170
	v_exp_f32_e32 v171, v171
	v_exp_f32_e32 v172, v172
	v_exp_f32_e32 v173, v173
	v_exp_f32_e32 v174, v174
	v_exp_f32_e32 v175, v175
	v_exp_f32_e32 v176, v176
	v_exp_f32_e32 v177, v177
	v_pk_add_f32 v[170:171], v[144:145], v[170:171]
	v_pk_add_f32 v[172:173], v[144:145], v[172:173]
	v_pk_add_f32 v[174:175], v[144:145], v[174:175]
	v_pk_add_f32 v[176:177], v[144:145], v[176:177]
	v_rcp_f32_e32 v170, v170
	v_rcp_f32_e32 v171, v171
	v_rcp_f32_e32 v172, v172
	v_rcp_f32_e32 v173, v173
	v_rcp_f32_e32 v174, v174
	v_rcp_f32_e32 v175, v175
	v_rcp_f32_e32 v176, v176
	v_rcp_f32_e32 v177, v177
	v_cvt_pk_bf16_f32 v182, v170, v171
	v_cvt_pk_bf16_f32 v183, v172, v173
	v_cvt_pk_bf16_f32 v184, v174, v175
	v_cvt_pk_bf16_f32 v185, v176, v177
	global_store_dwordx4 v138, v[182:185], s[46:47] offset:256
	v_add_u32_e32 v138, 0x10000, v138
	v_pk_mul_f32 v[162:163], v[142:143], v[32:33]
	v_pk_mul_f32 v[164:165], v[142:143], v[34:35]
	v_pk_mul_f32 v[166:167], v[142:143], v[24:25]
; __device__ __forceinline__ unsigned cvt_pk_bf16(float lo, float hi) { unsigned r; asm volatile("v_cvt_pk_bf16_f32 %0, %1, %2" : "=v"(r) : "v"(lo), "v"(hi)); return r; }
; __device__ __forceinline__ float sigm(float x) { return __builtin_amdgcn_rcpf(1.f + __builtin_amdgcn_exp2f(-1.4426950408889634f * x)); }
;     __device__ __forceinline__ void operator()(const f32x4 (&acc)[2][2][4][2], const Unit& u, int wr, int wc, int fr, int fq) const {
;     ...
;                     if (gate) { v0 = (f32x4){sigm(v0[0]), sigm(v0[1]), sigm(v0[2]), sigm(v0[3])}; v1 = (f32x4){sigm(v1[0]), sigm(v1[1]), sigm(v1[2]), sigm(v1[3])}; }
;                     else { v0 = v0 * sc; v1 = v1 * sc; }
;                     u32x4 w; w.x = cvt_pk_bf16(v0[0], v0[1]); w.y = cvt_pk_bf16(v0[2], v0[3]); w.z = cvt_pk_bf16(v1[0], v1[1]); w.w = cvt_pk_bf16(v1[2], v1[3]);
;                     const int g64 = 4 * (pn & 1) + 2 * bj + (wc >> 1), cin = 32 * (wc & 1) + 8 * fq;
;                     bf16_t* dst;
;                     if (gate) dst = O + (size_t)6 * 512 * M_ROWS + row * 2048 + (pn - 12) * BM + bj * HALF + wc * 32 + 8 * fq;
	v_pk_mul_f32 v[168:169], v[142:143], v[26:27]
	v_exp_f32_e32 v162, v162
	v_exp_f32_e32 v163, v163
	v_exp_f32_e32 v164, v164
	v_exp_f32_e32 v165, v165
	v_exp_f32_e32 v166, v166
	v_exp_f32_e32 v167, v167
	v_exp_f32_e32 v168, v168
	v_exp_f32_e32 v169, v169
	v_pk_add_f32 v[162:163], v[144:145], v[162:163]
	v_pk_add_f32 v[164:165], v[144:145], v[164:165]
	v_pk_add_f32 v[166:167], v[144:145], v[166:167]
	v_pk_add_f32 v[168:169], v[144:145], v[168:169]
	v_rcp_f32_e32 v162, v162
	v_rcp_f32_e32 v163, v163
	v_rcp_f32_e32 v164, v164
	v_rcp_f32_e32 v165, v165
	v_rcp_f32_e32 v166, v166
	v_rcp_f32_e32 v167, v167
	v_rcp_f32_e32 v168, v168
	v_rcp_f32_e32 v169, v169
	v_cvt_pk_bf16_f32 v178, v162, v163
	v_cvt_pk_bf16_f32 v179, v164, v165
	v_cvt_pk_bf16_f32 v180, v166, v167
	v_cvt_pk_bf16_f32 v181, v168, v169
	global_store_dwordx4 v138, v[178:181], s[46:47]
	v_pk_mul_f32 v[170:171], v[142:143], v[20:21]
	v_pk_mul_f32 v[172:173], v[142:143], v[22:23]
	v_pk_mul_f32 v[174:175], v[142:143], v[12:13]
	v_pk_mul_f32 v[176:177], v[142:143], v[14:15]
	v_exp_f32_e32 v170, v170
	v_exp_f32_e32 v171, v171
	v_exp_f32_e32 v172, v172
	v_exp_f32_e32 v173, v173
	v_exp_f32_e32 v174, v174
	v_exp_f32_e32 v175, v175
	v_exp_f32_e32 v176, v176
	v_exp_f32_e32 v177, v177
	v_pk_add_f32 v[170:171], v[144:145], v[170:171]
	v_pk_add_f32 v[172:173], v[144:145], v[172:173]
	v_pk_add_f32 v[174:175], v[144:145], v[174:175]
	v_pk_add_f32 v[176:177], v[144:145], v[176:177]
	v_rcp_f32_e32 v170, v170
	v_rcp_f32_e32 v171, v171
	v_rcp_f32_e32 v172, v172
	v_rcp_f32_e32 v173, v173
	v_rcp_f32_e32 v174, v174
	v_rcp_f32_e32 v175, v175
	v_rcp_f32_e32 v176, v176
	v_rcp_f32_e32 v177, v177
	v_cvt_pk_bf16_f32 v182, v170, v171
	v_cvt_pk_bf16_f32 v183, v172, v173
	v_cvt_pk_bf16_f32 v184, v174, v175
	v_cvt_pk_bf16_f32 v185, v176, v177
	global_store_dwordx4 v138, v[182:185], s[46:47] offset:256
	v_add_u32_e32 v138, 0x10000, v138
	v_pk_mul_f32 v[162:163], v[142:143], v[16:17]
	v_pk_mul_f32 v[164:165], v[142:143], v[18:19]
	v_pk_mul_f32 v[166:167], v[142:143], v[8:9]
	v_pk_mul_f32 v[168:169], v[142:143], v[10:11]
	v_exp_f32_e32 v162, v162
	v_exp_f32_e32 v163, v163
	v_exp_f32_e32 v164, v164
	v_exp_f32_e32 v165, v165
	v_exp_f32_e32 v166, v166
	v_exp_f32_e32 v167, v167
	v_exp_f32_e32 v168, v168
	v_exp_f32_e32 v169, v169
	v_pk_add_f32 v[162:163], v[144:145], v[162:163]
	v_pk_add_f32 v[164:165], v[144:145], v[164:165]
	v_pk_add_f32 v[166:167], v[144:145], v[166:167]
	v_pk_add_f32 v[168:169], v[144:145], v[168:169]
	v_rcp_f32_e32 v162, v162
	v_rcp_f32_e32 v163, v163
	v_rcp_f32_e32 v164, v164
	v_rcp_f32_e32 v165, v165
	v_rcp_f32_e32 v166, v166
	v_rcp_f32_e32 v167, v167
	v_rcp_f32_e32 v168, v168
	v_rcp_f32_e32 v169, v169
	v_cvt_pk_bf16_f32 v178, v162, v163
	v_cvt_pk_bf16_f32 v179, v164, v165
	v_cvt_pk_bf16_f32 v180, v166, v167
	v_cvt_pk_bf16_f32 v181, v168, v169
	global_store_dwordx4 v138, v[178:181], s[46:47]
	v_pk_mul_f32 v[170:171], v[142:143], v[4:5]
	v_pk_mul_f32 v[172:173], v[142:143], v[6:7]
	v_pk_mul_f32 v[174:175], v[142:143], v[0:1]
	v_pk_mul_f32 v[176:177], v[142:143], v[2:3]
	v_exp_f32_e32 v170, v170
	v_exp_f32_e32 v171, v171
	v_exp_f32_e32 v172, v172
	v_exp_f32_e32 v173, v173
	v_exp_f32_e32 v174, v174
	v_exp_f32_e32 v175, v175
	v_exp_f32_e32 v176, v176
	v_exp_f32_e32 v177, v177
	v_pk_add_f32 v[170:171], v[144:145], v[170:171]
	v_pk_add_f32 v[172:173], v[144:145], v[172:173]
	v_pk_add_f32 v[174:175], v[144:145], v[174:175]
	v_pk_add_f32 v[176:177], v[144:145], v[176:177]
	v_rcp_f32_e32 v170, v170
	v_rcp_f32_e32 v171, v171
	v_rcp_f32_e32 v172, v172
	v_rcp_f32_e32 v173, v173
	v_rcp_f32_e32 v174, v174
	v_rcp_f32_e32 v175, v175
	v_rcp_f32_e32 v176, v176
	v_rcp_f32_e32 v177, v177
	v_cvt_pk_bf16_f32 v182, v170, v171
	v_cvt_pk_bf16_f32 v183, v172, v173
	v_cvt_pk_bf16_f32 v184, v174, v175
	v_cvt_pk_bf16_f32 v185, v176, v177
	global_store_dwordx4 v138, v[182:185], s[46:47] offset:256
	s_branch .LBB0_1346

; __device__ __forceinline__ unsigned cvt_pk_bf16(float lo, float hi) { unsigned r; asm volatile("v_cvt_pk_bf16_f32 %0, %1, %2" : "=v"(r) : "v"(lo), "v"(hi)); return r; }
; __device__ __forceinline__ float bf_lo(unsigned w) { return __uint_as_float(w << 16); }
; __device__ __forceinline__ float bf_hi(unsigned w) { return __uint_as_float(w & 0xffff0000u); }
;     __device__ __forceinline__ void operator()(const f32x4 (&acc)[2][2][4][2], const Unit& u, int wr, int wc, int fr, int fq) const {
;         const bool second = u.pn >= 4; const int pn = second ? u.pn - 4 : u.pn, pm = second ? u.pm - 64 : u.pm;
;         const int row0 = pm * BM + wr * 64 + fr, col0 = pn * BM + wc * 32 + 8 * fq; const int goff = second ? 1024 : 0;
; #pragma unroll
;         for (int ai = 0; ai < 2; ++ai)
; #pragma unroll
;             for (int m = 0; m < 4; ++m) { const size_t row = (size_t)(row0 + ai * HALF + m * 16);
; #pragma unroll
;                 for (int bj = 0; bj < 2; ++bj) { const int col = col0 + bj * HALF;
;                     const u32x4 gw = *(const u32x4*)(proj + (size_t)6 * 512 * M_ROWS + row * 2048 + goff + col);
;                     const f32x4 g0 = (f32x4){bf_lo(gw.x), bf_hi(gw.x), bf_lo(gw.y), bf_hi(gw.y)}, g1 = (f32x4){bf_lo(gw.z), bf_hi(gw.z), bf_lo(gw.w), bf_hi(gw.w)};
;                     f32x4 v0 = acc[ai][bj][m][0] * g0, v1 = acc[ai][bj][m][1] * g1; bf16_t* mp = merged + row * 1024 + col;
;                     if (second) { const u32x4 tw = *(const u32x4*)mp;
;                         v0 = v0 + (f32x4){bf_lo(tw.x), bf_hi(tw.x), bf_lo(tw.y), bf_hi(tw.y)}; v1 = v1 + (f32x4){bf_lo(tw.z), bf_hi(tw.z), bf_lo(tw.w), bf_hi(tw.w)}; }
;                     u32x4 w; w.x = cvt_pk_bf16(v0[0], v0[1]); w.y = cvt_pk_bf16(v0[2], v0[3]); w.z = cvt_pk_bf16(v1[0], v1[1]); w.w = cvt_pk_bf16(v1[2], v1[3]);
;                     *(u32x4*)mp = w; }
.LBB0_1713:
	s_lshl_b32 s22, s22, 8
	s_lshl_b32 s59, s57, 8
	s_add_i32 s58, s22, 0xffffc000
	s_add_i32 s60, s59, 0xfffffc00
	s_cmp_gt_i32 s57, 3
	s_cselect_b64 s[18:19], -1, 0
	s_and_b64 s[10:11], s[18:19], exec
	s_cselect_b32 s11, s58, s22
	v_mbcnt_lo_u32_b32 v132, -1, 0
	v_mbcnt_hi_u32_b32 v132, -1, v132
	s_cselect_b32 s10, 0x400, 0
	s_cselect_b32 s58, s60, s59
	s_add_i32 s11, s11, s71
	v_and_or_b32 v134, v132, 15, s11
	v_lshrrev_b32_e32 v132, 1, v132
	v_and_or_b32 v132, v132, 24, s58
	v_ashrrev_i32_e32 v135, 31, v134
	v_or_b32_e32 v132, s75, v132
	s_lshl_b32 s22, s10, 1
	v_lshlrev_b32_e32 v248, 12, v134
	v_lshlrev_b32_e32 v249, 11, v134
	v_lshl_add_u32 v248, v132, 1, v248
	v_lshl_add_u32 v249, v132, 1, v249
	v_add_u32_e32 v248, s22, v248
	v_mov_b32_e32 v250, v249
	s_and_b64 vcc, exec, s[18:19]
	s_cbranch_vccnz .Lmrg_l1_second
	global_load_dwordx4 v[152:155], v248, s[28:29]
	global_load_dwordx4 v[156:159], v248, s[28:29] offset:256
	v_add_u32_e32 v248, 0x10000, v248
	global_load_dwordx4 v[160:163], v248, s[28:29]
	global_load_dwordx4 v[164:167], v248, s[28:29] offset:256
	v_add_u32_e32 v248, 0x10000, v248
	global_load_dwordx4 v[184:187], v248, s[28:29]
	global_load_dwordx4 v[188:191], v248, s[28:29] offset:256
	v_add_u32_e32 v248, 0x10000, v248
	global_load_dwordx4 v[192:195], v248, s[28:29]
	global_load_dwordx4 v[196:199], v248, s[28:29] offset:256
	v_add_u32_e32 v248, 0x50000, v248
	global_load_dwordx4 v[216:219], v248, s[28:29]
	global_load_dwordx4 v[220:223], v248, s[28:29] offset:256
	v_add_u32_e32 v248, 0x10000, v248
	global_load_dwordx4 v[224:227], v248, s[28:29]
	global_load_dwordx4 v[228:231], v248, s[28:29] offset:256
	s_waitcnt vmcnt(8)
	v_lshlrev_b32_e32 v132, 16, v152
	v_and_b32_e32 v133, 0xffff0000, v152
	v_lshlrev_b32_e32 v134, 16, v153
	v_and_b32_e32 v135, 0xffff0000, v153
	v_lshlrev_b32_e32 v136, 16, v154
	v_and_b32_e32 v137, 0xffff0000, v154
	v_lshlrev_b32_e32 v138, 16, v155
	v_and_b32_e32 v139, 0xffff0000, v155
	v_pk_mul_f32 v[124:125], v[124:125], v[132:133]
	v_pk_mul_f32 v[126:127], v[126:127], v[134:135]
	v_pk_mul_f32 v[120:121], v[120:121], v[136:137]
	v_pk_mul_f32 v[122:123], v[122:123], v[138:139]
	v_cvt_pk_bf16_f32 v152, v124, v125
	v_cvt_pk_bf16_f32 v153, v126, v127
	v_cvt_pk_bf16_f32 v154, v120, v121
	v_cvt_pk_bf16_f32 v155, v122, v123
	global_store_dwordx4 v250, v[152:155], s[24:25]
	v_lshlrev_b32_e32 v132, 16, v156
	v_and_b32_e32 v133, 0xffff0000, v156
	v_lshlrev_b32_e32 v134, 16, v157
	v_and_b32_e32 v135, 0xffff0000, v157
	v_lshlrev_b32_e32 v136, 16, v158
	v_and_b32_e32 v137, 0xffff0000, v158
	v_lshlrev_b32_e32 v138, 16, v159
	v_and_b32_e32 v139, 0xffff0000, v159
	v_pk_mul_f32 v[116:117], v[116:117], v[132:133]
	v_pk_mul_f32 v[118:119], v[118:119], v[134:135]
	v_pk_mul_f32 v[112:113], v[112:113], v[136:137]
	v_pk_mul_f32 v[114:115], v[114:115], v[138:139]
	v_cvt_pk_bf16_f32 v156, v116, v117
	v_cvt_pk_bf16_f32 v157, v118, v119
	v_cvt_pk_bf16_f32 v158, v112, v113
	v_cvt_pk_bf16_f32 v159, v114, v115
	global_store_dwordx4 v250, v[156:159], s[24:25] offset:256
	v_lshlrev_b32_e32 v132, 16, v160
	v_and_b32_e32 v133, 0xffff0000, v160
	v_lshlrev_b32_e32 v134, 16, v161
	v_and_b32_e32 v135, 0xffff0000, v161
	v_lshlrev_b32_e32 v136, 16, v162
	v_and_b32_e32 v137, 0xffff0000, v162
	v_lshlrev_b32_e32 v138, 16, v163
	v_and_b32_e32 v139, 0xffff0000, v163
	v_pk_mul_f32 v[108:109], v[108:109], v[132:133]
	v_pk_mul_f32 v[110:111], v[110:111], v[134:135]
	v_pk_mul_f32 v[104:105], v[104:105], v[136:137]
	v_pk_mul_f32 v[106:107], v[106:107], v[138:139]
	v_cvt_pk_bf16_f32 v160, v108, v109
	v_cvt_pk_bf16_f32 v161, v110, v111
	v_cvt_pk_bf16_f32 v162, v104, v105
	v_cvt_pk_bf16_f32 v163, v106, v107
	v_add_u32_e32 v250, 0x8000, v250
	global_store_dwordx4 v250, v[160:163], s[24:25]
	v_lshlrev_b32_e32 v132, 16, v164
	v_and_b32_e32 v133, 0xffff0000, v164
	v_lshlrev_b32_e32 v134, 16, v165
	v_and_b32_e32 v135, 0xffff0000, v165
	v_lshlrev_b32_e32 v136, 16, v166
	v_and_b32_e32 v137, 0xffff0000, v166
	v_lshlrev_b32_e32 v138, 16, v167
	v_and_b32_e32 v139, 0xffff0000, v167
	v_pk_mul_f32 v[100:101], v[100:101], v[132:133]
	v_pk_mul_f32 v[102:103], v[102:103], v[134:135]
	v_pk_mul_f32 v[96:97], v[96:97], v[136:137]
	v_pk_mul_f32 v[98:99], v[98:99], v[138:139]
	v_cvt_pk_bf16_f32 v164, v100, v101
	v_cvt_pk_bf16_f32 v165, v102, v103
	v_cvt_pk_bf16_f32 v166, v96, v97
	v_cvt_pk_bf16_f32 v167, v98, v99
	global_store_dwordx4 v250, v[164:167], s[24:25] offset:256
	v_add_u32_e32 v248, 0x10000, v248
	global_load_dwordx4 v[152:155], v248, s[28:29]
	global_load_dwordx4 v[156:159], v248, s[28:29] offset:256
	v_add_u32_e32 v248, 0x10000, v248
	global_load_dwordx4 v[160:163], v248, s[28:29]
	global_load_dwordx4 v[164:167], v248, s[28:29] offset:256
	s_waitcnt vmcnt(12)
; __device__ __forceinline__ unsigned cvt_pk_bf16(float lo, float hi) { unsigned r; asm volatile("v_cvt_pk_bf16_f32 %0, %1, %2" : "=v"(r) : "v"(lo), "v"(hi)); return r; }
; __device__ __forceinline__ float bf_lo(unsigned w) { return __uint_as_float(w << 16); }
; __device__ __forceinline__ float bf_hi(unsigned w) { return __uint_as_float(w & 0xffff0000u); }
;     __device__ __forceinline__ void operator()(const f32x4 (&acc)[2][2][4][2], const Unit& u, int wr, int wc, int fr, int fq) const {
;     ...
;                     const u32x4 gw = *(const u32x4*)(proj + (size_t)6 * 512 * M_ROWS + row * 2048 + goff + col);
;                     const f32x4 g0 = (f32x4){bf_lo(gw.x), bf_hi(gw.x), bf_lo(gw.y), bf_hi(gw.y)}, g1 = (f32x4){bf_lo(gw.z), bf_hi(gw.z), bf_lo(gw.w), bf_hi(gw.w)};
;                     f32x4 v0 = acc[ai][bj][m][0] * g0, v1 = acc[ai][bj][m][1] * g1; bf16_t* mp = merged + row * 1024 + col;
;                     if (second) { const u32x4 tw = *(const u32x4*)mp;
;                         v0 = v0 + (f32x4){bf_lo(tw.x), bf_hi(tw.x), bf_lo(tw.y), bf_hi(tw.y)}; v1 = v1 + (f32x4){bf_lo(tw.z), bf_hi(tw.z), bf_lo(tw.w), bf_hi(tw.w)}; }
;                     u32x4 w; w.x = cvt_pk_bf16(v0[0], v0[1]); w.y = cvt_pk_bf16(v0[2], v0[3]); w.z = cvt_pk_bf16(v1[0], v1[1]); w.w = cvt_pk_bf16(v1[2], v1[3]);
;                     *(u32x4*)mp = w; }
	v_lshlrev_b32_e32 v132, 16, v184
	v_and_b32_e32 v133, 0xffff0000, v184
	v_lshlrev_b32_e32 v134, 16, v185
	v_and_b32_e32 v135, 0xffff0000, v185
	v_lshlrev_b32_e32 v136, 16, v186
	v_and_b32_e32 v137, 0xffff0000, v186
	v_lshlrev_b32_e32 v138, 16, v187
	v_and_b32_e32 v139, 0xffff0000, v187
	v_pk_mul_f32 v[92:93], v[92:93], v[132:133]
	v_pk_mul_f32 v[94:95], v[94:95], v[134:135]
	v_pk_mul_f32 v[88:89], v[88:89], v[136:137]
	v_pk_mul_f32 v[90:91], v[90:91], v[138:139]
	v_cvt_pk_bf16_f32 v184, v92, v93
	v_cvt_pk_bf16_f32 v185, v94, v95
	v_cvt_pk_bf16_f32 v186, v88, v89
	v_cvt_pk_bf16_f32 v187, v90, v91
	v_add_u32_e32 v250, 0x8000, v250
	global_store_dwordx4 v250, v[184:187], s[24:25]
	v_lshlrev_b32_e32 v132, 16, v188
	v_and_b32_e32 v133, 0xffff0000, v188
	v_lshlrev_b32_e32 v134, 16, v189
	v_and_b32_e32 v135, 0xffff0000, v189
	v_lshlrev_b32_e32 v136, 16, v190
	v_and_b32_e32 v137, 0xffff0000, v190
	v_lshlrev_b32_e32 v138, 16, v191
	v_and_b32_e32 v139, 0xffff0000, v191
	v_pk_mul_f32 v[84:85], v[84:85], v[132:133]
	v_pk_mul_f32 v[86:87], v[86:87], v[134:135]
	v_pk_mul_f32 v[80:81], v[80:81], v[136:137]
	v_pk_mul_f32 v[82:83], v[82:83], v[138:139]
	v_cvt_pk_bf16_f32 v188, v84, v85
	v_cvt_pk_bf16_f32 v189, v86, v87
	v_cvt_pk_bf16_f32 v190, v80, v81
	v_cvt_pk_bf16_f32 v191, v82, v83
	global_store_dwordx4 v250, v[188:191], s[24:25] offset:256
	v_lshlrev_b32_e32 v132, 16, v192
	v_and_b32_e32 v133, 0xffff0000, v192
	v_lshlrev_b32_e32 v134, 16, v193
	v_and_b32_e32 v135, 0xffff0000, v193
	v_lshlrev_b32_e32 v136, 16, v194
	v_and_b32_e32 v137, 0xffff0000, v194
	v_lshlrev_b32_e32 v138, 16, v195
	v_and_b32_e32 v139, 0xffff0000, v195
	v_pk_mul_f32 v[76:77], v[76:77], v[132:133]
	v_pk_mul_f32 v[78:79], v[78:79], v[134:135]
	v_pk_mul_f32 v[72:73], v[72:73], v[136:137]
	v_pk_mul_f32 v[74:75], v[74:75], v[138:139]
	v_cvt_pk_bf16_f32 v192, v76, v77
	v_cvt_pk_bf16_f32 v193, v78, v79
	v_cvt_pk_bf16_f32 v194, v72, v73
	v_cvt_pk_bf16_f32 v195, v74, v75
	v_add_u32_e32 v250, 0x8000, v250
	global_store_dwordx4 v250, v[192:195], s[24:25]
	v_lshlrev_b32_e32 v132, 16, v196
	v_and_b32_e32 v133, 0xffff0000, v196
	v_lshlrev_b32_e32 v134, 16, v197
	v_and_b32_e32 v135, 0xffff0000, v197
	v_lshlrev_b32_e32 v136, 16, v198
	v_and_b32_e32 v137, 0xffff0000, v198
	v_lshlrev_b32_e32 v138, 16, v199
	v_and_b32_e32 v139, 0xffff0000, v199
	v_pk_mul_f32 v[68:69], v[68:69], v[132:133]
	v_pk_mul_f32 v[70:71], v[70:71], v[134:135]
	v_pk_mul_f32 v[64:65], v[64:65], v[136:137]
	v_pk_mul_f32 v[66:67], v[66:67], v[138:139]
	v_cvt_pk_bf16_f32 v196, v68, v69
	v_cvt_pk_bf16_f32 v197, v70, v71
	v_cvt_pk_bf16_f32 v198, v64, v65
	v_cvt_pk_bf16_f32 v199, v66, v67
	global_store_dwordx4 v250, v[196:199], s[24:25] offset:256
	s_waitcnt vmcnt(12)
; __device__ __forceinline__ unsigned cvt_pk_bf16(float lo, float hi) { unsigned r; asm volatile("v_cvt_pk_bf16_f32 %0, %1, %2" : "=v"(r) : "v"(lo), "v"(hi)); return r; }
; __device__ __forceinline__ float bf_lo(unsigned w) { return __uint_as_float(w << 16); }
; __device__ __forceinline__ float bf_hi(unsigned w) { return __uint_as_float(w & 0xffff0000u); }
;     __device__ __forceinline__ void operator()(const f32x4 (&acc)[2][2][4][2], const Unit& u, int wr, int wc, int fr, int fq) const {
;     ...
;                     const u32x4 gw = *(const u32x4*)(proj + (size_t)6 * 512 * M_ROWS + row * 2048 + goff + col);
;                     const f32x4 g0 = (f32x4){bf_lo(gw.x), bf_hi(gw.x), bf_lo(gw.y), bf_hi(gw.y)}, g1 = (f32x4){bf_lo(gw.z), bf_hi(gw.z), bf_lo(gw.w), bf_hi(gw.w)};
;                     f32x4 v0 = acc[ai][bj][m][0] * g0, v1 = acc[ai][bj][m][1] * g1; bf16_t* mp = merged + row * 1024 + col;
;                     if (second) { const u32x4 tw = *(const u32x4*)mp;
;                         v0 = v0 + (f32x4){bf_lo(tw.x), bf_hi(tw.x), bf_lo(tw.y), bf_hi(tw.y)}; v1 = v1 + (f32x4){bf_lo(tw.z), bf_hi(tw.z), bf_lo(tw.w), bf_hi(tw.w)}; }
;                     u32x4 w; w.x = cvt_pk_bf16(v0[0], v0[1]); w.y = cvt_pk_bf16(v0[2], v0[3]); w.z = cvt_pk_bf16(v1[0], v1[1]); w.w = cvt_pk_bf16(v1[2], v1[3]);
;                     *(u32x4*)mp = w; }
	v_lshlrev_b32_e32 v132, 16, v216
	v_and_b32_e32 v133, 0xffff0000, v216
	v_lshlrev_b32_e32 v134, 16, v217
	v_and_b32_e32 v135, 0xffff0000, v217
	v_lshlrev_b32_e32 v136, 16, v218
	v_and_b32_e32 v137, 0xffff0000, v218
	v_lshlrev_b32_e32 v138, 16, v219
	v_and_b32_e32 v139, 0xffff0000, v219
	v_pk_mul_f32 v[60:61], v[60:61], v[132:133]
	v_pk_mul_f32 v[62:63], v[62:63], v[134:135]
	v_pk_mul_f32 v[56:57], v[56:57], v[136:137]
	v_pk_mul_f32 v[58:59], v[58:59], v[138:139]
	v_cvt_pk_bf16_f32 v216, v60, v61
	v_cvt_pk_bf16_f32 v217, v62, v63
	v_cvt_pk_bf16_f32 v218, v56, v57
	v_cvt_pk_bf16_f32 v219, v58, v59
	v_add_u32_e32 v250, 0x28000, v250
	global_store_dwordx4 v250, v[216:219], s[24:25]
	v_lshlrev_b32_e32 v132, 16, v220
	v_and_b32_e32 v133, 0xffff0000, v220
	v_lshlrev_b32_e32 v134, 16, v221
	v_and_b32_e32 v135, 0xffff0000, v221
	v_lshlrev_b32_e32 v136, 16, v222
	v_and_b32_e32 v137, 0xffff0000, v222
	v_lshlrev_b32_e32 v138, 16, v223
	v_and_b32_e32 v139, 0xffff0000, v223
	v_pk_mul_f32 v[52:53], v[52:53], v[132:133]
	v_pk_mul_f32 v[54:55], v[54:55], v[134:135]
	v_pk_mul_f32 v[48:49], v[48:49], v[136:137]
	v_pk_mul_f32 v[50:51], v[50:51], v[138:139]
	v_cvt_pk_bf16_f32 v220, v52, v53
	v_cvt_pk_bf16_f32 v221, v54, v55
	v_cvt_pk_bf16_f32 v222, v48, v49
	v_cvt_pk_bf16_f32 v223, v50, v51
	global_store_dwordx4 v250, v[220:223], s[24:25] offset:256
	v_lshlrev_b32_e32 v132, 16, v224
	v_and_b32_e32 v133, 0xffff0000, v224
	v_lshlrev_b32_e32 v134, 16, v225
	v_and_b32_e32 v135, 0xffff0000, v225
	v_lshlrev_b32_e32 v136, 16, v226
	v_and_b32_e32 v137, 0xffff0000, v226
	v_lshlrev_b32_e32 v138, 16, v227
	v_and_b32_e32 v139, 0xffff0000, v227
	v_pk_mul_f32 v[44:45], v[44:45], v[132:133]
	v_pk_mul_f32 v[46:47], v[46:47], v[134:135]
	v_pk_mul_f32 v[40:41], v[40:41], v[136:137]
	v_pk_mul_f32 v[42:43], v[42:43], v[138:139]
	v_cvt_pk_bf16_f32 v224, v44, v45
	v_cvt_pk_bf16_f32 v225, v46, v47
	v_cvt_pk_bf16_f32 v226, v40, v41
	v_cvt_pk_bf16_f32 v227, v42, v43
	v_add_u32_e32 v250, 0x8000, v250
	global_store_dwordx4 v250, v[224:227], s[24:25]
	v_lshlrev_b32_e32 v132, 16, v228
	v_and_b32_e32 v133, 0xffff0000, v228
	v_lshlrev_b32_e32 v134, 16, v229
	v_and_b32_e32 v135, 0xffff0000, v229
	v_lshlrev_b32_e32 v136, 16, v230
	v_and_b32_e32 v137, 0xffff0000, v230
	v_lshlrev_b32_e32 v138, 16, v231
	v_and_b32_e32 v139, 0xffff0000, v231
	v_pk_mul_f32 v[36:37], v[36:37], v[132:133]
	v_pk_mul_f32 v[38:39], v[38:39], v[134:135]
	v_pk_mul_f32 v[32:33], v[32:33], v[136:137]
	v_pk_mul_f32 v[34:35], v[34:35], v[138:139]
	v_cvt_pk_bf16_f32 v228, v36, v37
	v_cvt_pk_bf16_f32 v229, v38, v39
	v_cvt_pk_bf16_f32 v230, v32, v33
	v_cvt_pk_bf16_f32 v231, v34, v35
	global_store_dwordx4 v250, v[228:231], s[24:25] offset:256
	s_waitcnt vmcnt(8)
	v_lshlrev_b32_e32 v132, 16, v152
	v_and_b32_e32 v133, 0xffff0000, v152
	v_lshlrev_b32_e32 v134, 16, v153
	v_and_b32_e32 v135, 0xffff0000, v153
	v_lshlrev_b32_e32 v136, 16, v154
	v_and_b32_e32 v137, 0xffff0000, v154
	v_lshlrev_b32_e32 v138, 16, v155
	v_and_b32_e32 v139, 0xffff0000, v155
	v_pk_mul_f32 v[28:29], v[28:29], v[132:133]
	v_pk_mul_f32 v[30:31], v[30:31], v[134:135]
	v_pk_mul_f32 v[24:25], v[24:25], v[136:137]
	v_pk_mul_f32 v[26:27], v[26:27], v[138:139]
	v_cvt_pk_bf16_f32 v152, v28, v29
	v_cvt_pk_bf16_f32 v153, v30, v31
	v_cvt_pk_bf16_f32 v154, v24, v25
	v_cvt_pk_bf16_f32 v155, v26, v27
	v_add_u32_e32 v250, 0x8000, v250
	global_store_dwordx4 v250, v[152:155], s[24:25]
	v_lshlrev_b32_e32 v132, 16, v156
	v_and_b32_e32 v133, 0xffff0000, v156
	v_lshlrev_b32_e32 v134, 16, v157
	v_and_b32_e32 v135, 0xffff0000, v157
	v_lshlrev_b32_e32 v136, 16, v158
	v_and_b32_e32 v137, 0xffff0000, v158
	v_lshlrev_b32_e32 v138, 16, v159
	v_and_b32_e32 v139, 0xffff0000, v159
	v_pk_mul_f32 v[20:21], v[20:21], v[132:133]
	v_pk_mul_f32 v[22:23], v[22:23], v[134:135]
	v_pk_mul_f32 v[16:17], v[16:17], v[136:137]
	v_pk_mul_f32 v[18:19], v[18:19], v[138:139]
	v_cvt_pk_bf16_f32 v156, v20, v21
	v_cvt_pk_bf16_f32 v157, v22, v23
	v_cvt_pk_bf16_f32 v158, v16, v17
	v_cvt_pk_bf16_f32 v159, v18, v19
	global_store_dwordx4 v250, v[156:159], s[24:25] offset:256
	v_lshlrev_b32_e32 v132, 16, v160
	v_and_b32_e32 v133, 0xffff0000, v160
	v_lshlrev_b32_e32 v134, 16, v161
	v_and_b32_e32 v135, 0xffff0000, v161
	v_lshlrev_b32_e32 v136, 16, v162
	v_and_b32_e32 v137, 0xffff0000, v162
	v_lshlrev_b32_e32 v138, 16, v163
	v_and_b32_e32 v139, 0xffff0000, v163
	v_pk_mul_f32 v[12:13], v[12:13], v[132:133]
	v_pk_mul_f32 v[14:15], v[14:15], v[134:135]
	v_pk_mul_f32 v[8:9], v[8:9], v[136:137]
	v_pk_mul_f32 v[10:11], v[10:11], v[138:139]
	v_cvt_pk_bf16_f32 v160, v12, v13
	v_cvt_pk_bf16_f32 v161, v14, v15
	v_cvt_pk_bf16_f32 v162, v8, v9
	v_cvt_pk_bf16_f32 v163, v10, v11
	v_add_u32_e32 v250, 0x8000, v250
	global_store_dwordx4 v250, v[160:163], s[24:25]
	v_lshlrev_b32_e32 v132, 16, v164
	v_and_b32_e32 v133, 0xffff0000, v164
	v_lshlrev_b32_e32 v134, 16, v165
	v_and_b32_e32 v135, 0xffff0000, v165
	v_lshlrev_b32_e32 v136, 16, v166
	v_and_b32_e32 v137, 0xffff0000, v166
	v_lshlrev_b32_e32 v138, 16, v167
	v_and_b32_e32 v139, 0xffff0000, v167
	v_pk_mul_f32 v[4:5], v[4:5], v[132:133]
	v_pk_mul_f32 v[6:7], v[6:7], v[134:135]
	v_pk_mul_f32 v[0:1], v[0:1], v[136:137]
	v_pk_mul_f32 v[2:3], v[2:3], v[138:139]
	v_cvt_pk_bf16_f32 v164, v4, v5
	v_cvt_pk_bf16_f32 v165, v6, v7
	v_cvt_pk_bf16_f32 v166, v0, v1
	v_cvt_pk_bf16_f32 v167, v2, v3
	global_store_dwordx4 v250, v[164:167], s[24:25] offset:256
	s_branch .Lmrg_l1_done

; #define PG8_BAR __builtin_amdgcn_s_barrier()
; template <class Epi, class Sched, bool ALIGN_EPI = false, bool SP2 = false, bool F8 = false>
; __device__ __forceinline__ void gemm_phase(PG8_LAS unsigned char* lds, const Gemm g, const Sched& S, const Epi& E, const int wv) {
;     ...
;         if (!has_next) break;
; #pragma unroll
;         for (int a = 0; a < 2; ++a)
; #pragma unroll
;             for (int b = 0; b < 2; ++b)
; #pragma unroll
;                 for (int m = 0; m < 4; ++m)
; #pragma unroll
;                     for (int n = 0; n < 2; ++n) acc[a][b][m][n] = (f32x4){0.f, 0.f, 0.f, 0.f};
;         cur = nxt; cA = nA; cB = nB; ++ui;
;         if constexpr (ALIGN_EPI) { if (wr == 1) PG8_BAR; }
.Lmrg_l1_done:
	s_andn2_b64 vcc, exec, s[8:9]
	s_mov_b64 s[8:9], -1
	s_cbranch_vccnz .LBB0_1702
	s_andn2_b64 vcc, exec, s[20:21]
	s_cbranch_vccnz .LBB0_1701
	s_barrier
	s_branch .LBB0_1701
